# in-projection epilogues: f32 state outputs stored with the nt (streaming) cache hint so they do not displace the bf16 q/k/v images
# speedup vs baseline: 1.0662x; 1.0114x over previous
.LBB0_239:
	s_and_saveexec_b64 s[0:1], s[16:17]
	s_cbranch_execz .LBB0_256
	global_load_dword v37, v[158:159], off
	s_lshl_b32 s4, s76, 7
	s_ashr_i32 s54, s76, 6
	s_and_b32 s55, s4, 0x1f80
	s_cmpk_eq_i32 s76, 0x100
	s_waitcnt vmcnt(8)
	v_mov_b32_e32 v34, s54
	s_cselect_b64 s[4:5], -1, 0
	v_cndmask_b32_e64 v66, v34, v183, s[4:5]
	v_or_b32_e32 v35, s55, v184
	s_waitcnt vmcnt(7)
	v_cndmask_b32_e64 v36, v35, v182, s[4:5]
	v_mov_b64_e32 v[32:33], s[42:43]
	s_and_b64 s[6:7], s[4:5], exec
	s_cselect_b32 s6, s57, 0x10080000
	s_cselect_b32 s53, 4, 13
	s_add_u32 s78, s62, s6
	s_addc_u32 s79, s63, 0
	v_lshlrev_b32_e32 v152, 2, v36
	s_cmpk_lg_i32 s76, 0x100
	s_waitcnt vmcnt(0)
	v_add_f32_e32 v16, v16, v37
	v_mul_f32_e64 v34, |v16|, s88
	v_add_f32_e32 v17, v17, v37
	v_exp_f32_e32 v67, v34
	v_mul_f32_e64 v35, |v17|, s88
	v_exp_f32_e32 v68, v35
	v_add_f32_e32 v18, v18, v37
	v_add_f32_e32 v40, 1.0, v67
	v_frexp_mant_f32_e32 v43, v40
	v_cvt_f64_f32_e32 v[34:35], v40
	v_add_f32_e32 v41, 1.0, v68
	v_frexp_exp_i32_f64_e32 v34, v[34:35]
	v_cmp_gt_f32_e32 vcc, s89, v43
	v_add_f32_e32 v42, -1.0, v40
	v_add_f32_e32 v44, -1.0, v41
	v_frexp_mant_f32_e32 v45, v41
	v_cvt_f64_f32_e32 v[38:39], v41
	v_subbrev_co_u32_e32 v34, vcc, 0, v34, vcc
	v_sub_f32_e32 v46, v42, v40
	v_sub_f32_e32 v35, v44, v41
	v_frexp_exp_i32_f64_e32 v38, v[38:39]
	v_cmp_gt_f32_e32 vcc, s89, v45
	v_sub_f32_e32 v42, v67, v42
	v_sub_f32_e32 v44, v68, v44
	v_add_f32_e32 v39, 1.0, v46
	v_add_f32_e32 v35, 1.0, v35
	v_subbrev_co_u32_e32 v38, vcc, 0, v38, vcc
	v_add_f32_e32 v39, v42, v39
	v_sub_u32_e32 v42, 0, v34
	v_add_f32_e32 v43, v44, v35
	v_sub_u32_e32 v44, 0, v38
	v_cvt_f32_i32_e32 v35, v38
	v_cvt_f32_i32_e32 v34, v34
	v_ldexp_f32 v38, v40, v42
	v_ldexp_f32 v40, v39, v42
	v_ldexp_f32 v39, v41, v44
	v_ldexp_f32 v41, v43, v44
	v_pk_add_f32 v[42:43], v[38:39], 1.0 op_sel_hi:[1,0]
	v_pk_add_f32 v[44:45], v[38:39], -1.0 op_sel_hi:[1,0]
	v_pk_add_f32 v[46:47], v[42:43], -1.0 op_sel_hi:[1,0]
	v_pk_add_f32 v[48:49], v[44:45], 1.0 op_sel_hi:[1,0]
	v_pk_add_f32 v[46:47], v[38:39], v[46:47] neg_lo:[0,1] neg_hi:[0,1]
	v_pk_add_f32 v[38:39], v[38:39], v[48:49] neg_lo:[0,1] neg_hi:[0,1]
	v_pk_mul_f32 v[48:49], v[34:35], s[48:49] op_sel_hi:[1,0]
	v_pk_add_f32 v[46:47], v[40:41], v[46:47]
	v_pk_add_f32 v[38:39], v[40:41], v[38:39]
	v_pk_fma_f32 v[40:41], v[34:35], s[48:49], v[48:49] op_sel_hi:[1,0,1] neg_lo:[0,0,1] neg_hi:[0,0,1]
	v_pk_add_f32 v[52:53], v[42:43], v[46:47]
	v_pk_fma_f32 v[34:35], v[34:35], s[50:51], v[40:41] op_sel_hi:[1,0,1]
	v_rcp_f32_e32 v40, v52
	v_rcp_f32_e32 v41, v53
	v_pk_add_f32 v[54:55], v[44:45], v[38:39]
	v_pk_add_f32 v[42:43], v[52:53], v[42:43] neg_lo:[0,1] neg_hi:[0,1]
	v_pk_add_f32 v[44:45], v[54:55], v[44:45] neg_lo:[0,1] neg_hi:[0,1]
	v_pk_add_f32 v[42:43], v[46:47], v[42:43] neg_lo:[0,1] neg_hi:[0,1]
	v_pk_add_f32 v[38:39], v[38:39], v[44:45] neg_lo:[0,1] neg_hi:[0,1]
	v_pk_mul_f32 v[44:45], v[54:55], v[40:41]
	v_mov_b32_e32 v50, v48
	v_pk_mul_f32 v[46:47], v[52:53], v[44:45]
	v_mov_b32_e32 v58, v34
	v_pk_fma_f32 v[60:61], v[44:45], v[52:53], v[46:47] neg_lo:[0,0,1] neg_hi:[0,0,1]
	v_pk_add_f32 v[56:57], v[48:49], v[34:35]
	v_pk_fma_f32 v[60:61], v[44:45], v[42:43], v[60:61]
	v_cmp_neq_f32_e32 vcc, s90, v67
	v_pk_add_f32 v[62:63], v[46:47], v[60:61]
	v_min_f32_e32 v16, 0, v16
	v_pk_add_f32 v[64:65], v[54:55], v[62:63] neg_lo:[0,1] neg_hi:[0,1]
	v_pk_add_f32 v[46:47], v[62:63], v[46:47] neg_lo:[0,1] neg_hi:[0,1]
	v_pk_add_f32 v[54:55], v[54:55], v[64:65] neg_lo:[0,1] neg_hi:[0,1]
	v_pk_add_f32 v[46:47], v[46:47], v[60:61] neg_lo:[0,1] neg_hi:[0,1]
	v_pk_add_f32 v[54:55], v[54:55], v[62:63] neg_lo:[0,1] neg_hi:[0,1]
	v_min_f32_e32 v17, 0, v17
	v_pk_add_f32 v[38:39], v[38:39], v[54:55]
	v_add_f32_e32 v19, v19, v37
	v_pk_add_f32 v[38:39], v[46:47], v[38:39]
	s_nop 0
	v_pk_add_f32 v[46:47], v[64:65], v[38:39]
	s_nop 0
	v_pk_mul_f32 v[54:55], v[40:41], v[46:47]
	v_pk_add_f32 v[60:61], v[64:65], v[46:47] neg_lo:[0,1] neg_hi:[0,1]
	v_pk_mul_f32 v[62:63], v[52:53], v[54:55]
	v_pk_add_f32 v[38:39], v[38:39], v[60:61]
	v_pk_fma_f32 v[52:53], v[54:55], v[52:53], v[62:63] neg_lo:[0,0,1] neg_hi:[0,0,1]
	v_pk_add_f32 v[60:61], v[44:45], v[54:55]
	v_pk_fma_f32 v[42:43], v[54:55], v[42:43], v[52:53]
	v_pk_add_f32 v[44:45], v[60:61], v[44:45] neg_lo:[0,1] neg_hi:[0,1]
	v_pk_add_f32 v[52:53], v[62:63], v[42:43]
	v_pk_add_f32 v[44:45], v[54:55], v[44:45] neg_lo:[0,1] neg_hi:[0,1]
	v_pk_add_f32 v[54:55], v[52:53], v[62:63] neg_lo:[0,1] neg_hi:[0,1]
	v_pk_add_f32 v[62:63], v[46:47], v[52:53] neg_lo:[0,1] neg_hi:[0,1]
	v_pk_add_f32 v[42:43], v[54:55], v[42:43] neg_lo:[0,1] neg_hi:[0,1]
	v_pk_add_f32 v[46:47], v[46:47], v[62:63] neg_lo:[0,1] neg_hi:[0,1]
	v_mov_b32_e32 v54, v56
	v_pk_add_f32 v[46:47], v[46:47], v[52:53] neg_lo:[0,1] neg_hi:[0,1]
	v_mov_b32_e32 v53, v57
	v_pk_add_f32 v[38:39], v[38:39], v[46:47]
	v_mov_b32_e32 v55, v49
	v_pk_add_f32 v[38:39], v[42:43], v[38:39]
	s_nop 0
	v_pk_add_f32 v[38:39], v[62:63], v[38:39]
	s_nop 0
	v_pk_mul_f32 v[38:39], v[40:41], v[38:39]
	s_nop 0
	v_pk_add_f32 v[38:39], v[44:45], v[38:39]
	s_nop 0
	v_pk_add_f32 v[40:41], v[60:61], v[38:39]
	s_nop 0
	v_pk_add_f32 v[42:43], v[40:41], v[60:61] neg_lo:[0,1] neg_hi:[0,1]
	v_pk_mul_f32 v[46:47], v[40:41], v[40:41]
	v_pk_add_f32 v[38:39], v[38:39], v[42:43] neg_lo:[0,1] neg_hi:[0,1]
	v_pk_fma_f32 v[42:43], v[46:47], s[44:45], v[32:33] op_sel_hi:[1,0,0]
	v_ldexp_f32 v44, v40, 1
	v_ldexp_f32 v45, v41, 1
	v_pk_mul_f32 v[40:41], v[40:41], v[46:47]
	v_pk_fma_f32 v[42:43], v[46:47], v[42:43], s[46:47] op_sel_hi:[1,1,0]
	v_ldexp_f32 v59, v39, 1
	v_pk_mul_f32 v[40:41], v[40:41], v[42:43]
	v_ldexp_f32 v38, v38, 1
	v_pk_add_f32 v[42:43], v[44:45], v[40:41]
	v_mov_b32_e32 v39, v59
	v_pk_add_f32 v[44:45], v[42:43], v[44:45] neg_lo:[0,1] neg_hi:[0,1]
	v_mov_b32_e32 v60, v42
	v_pk_add_f32 v[40:41], v[40:41], v[44:45] neg_lo:[0,1] neg_hi:[0,1]
	v_mov_b32_e32 v61, v57
	v_mov_b32_e32 v51, v41
	v_pk_add_f32 v[44:45], v[38:39], v[40:41]
	v_mov_b32_e32 v41, v43
	v_pk_add_f32 v[46:47], v[50:51], v[58:59]
	v_mov_b32_e32 v39, v45
	v_pk_add_f32 v[50:51], v[42:43], v[44:45]
	v_pk_add_f32 v[38:39], v[38:39], v[40:41]
	v_pk_add_f32 v[40:41], v[56:57], v[50:51]
	v_mov_b32_e32 v58, v50
	v_mov_b32_e32 v59, v41
	v_pk_add_f32 v[58:59], v[58:59], v[60:61] neg_lo:[0,1] neg_hi:[0,1]
	v_mov_b32_e32 v52, v40
	v_mov_b32_e32 v60, v56
	v_mov_b32_e32 v61, v41
	v_mov_b32_e32 v49, v59
	v_pk_add_f32 v[52:53], v[52:53], v[54:55] neg_lo:[0,1] neg_hi:[0,1]
	v_mov_b32_e32 v54, v50
	v_mov_b32_e32 v55, v35
	v_pk_add_f32 v[48:49], v[60:61], v[48:49] neg_lo:[0,1] neg_hi:[0,1]
	v_pk_add_f32 v[54:55], v[54:55], v[52:53] neg_lo:[0,1] neg_hi:[0,1]
	v_mov_b32_e32 v60, v48
	v_mov_b32_e32 v61, v53
	v_mov_b32_e32 v62, v40
	v_mov_b32_e32 v63, v51
	v_mov_b32_e32 v53, v43
	v_pk_add_f32 v[60:61], v[34:35], v[60:61] neg_lo:[0,1] neg_hi:[0,1]
	v_pk_add_f32 v[52:53], v[62:63], v[52:53] neg_lo:[0,1] neg_hi:[0,1]
	v_mov_b32_e32 v35, v57
	v_pk_add_f32 v[42:43], v[50:51], v[42:43] neg_lo:[0,1] neg_hi:[0,1]
	v_pk_add_f32 v[46:47], v[46:47], v[52:53] neg_lo:[0,1] neg_hi:[0,1]
	v_pk_add_f32 v[34:35], v[34:35], v[48:49] neg_lo:[0,1] neg_hi:[0,1]
	v_pk_add_f32 v[38:39], v[38:39], v[58:59] neg_lo:[0,1] neg_hi:[0,1]
	v_pk_add_f32 v[42:43], v[44:45], v[42:43] neg_lo:[0,1] neg_hi:[0,1]
	v_pk_add_f32 v[44:45], v[38:39], v[34:35]
	v_mov_b32_e32 v35, v55
	v_mov_b32_e32 v39, v47
	v_pk_add_f32 v[48:49], v[54:55], v[46:47]
	v_pk_add_f32 v[38:39], v[34:35], v[38:39]
	v_mov_b32_e32 v46, v44
	v_pk_add_f32 v[38:39], v[38:39], v[60:61] neg_lo:[0,1] neg_hi:[0,1]
	v_mov_b32_e32 v47, v49
	v_pk_add_f32 v[46:47], v[46:47], v[38:39] neg_lo:[0,1] neg_hi:[0,1]
	v_pk_add_f32 v[38:39], v[42:43], v[38:39] neg_lo:[0,1] neg_hi:[0,1]
	v_pk_add_f32 v[34:35], v[34:35], v[46:47] neg_lo:[0,1] neg_hi:[0,1]
	s_nop 0
	v_pk_add_f32 v[34:35], v[38:39], v[34:35]
	v_pk_add_f32 v[38:39], v[48:49], v[44:45]
	s_nop 0
	v_pk_add_f32 v[42:43], v[40:41], v[38:39]
	s_nop 0
	v_pk_add_f32 v[40:41], v[42:43], v[40:41] neg_lo:[0,1] neg_hi:[0,1]
	s_nop 0
	v_pk_add_f32 v[38:39], v[38:39], v[40:41] neg_lo:[0,1] neg_hi:[0,1]
	s_nop 0
	v_pk_add_f32 v[34:35], v[34:35], v[38:39]
	v_mul_f32_e64 v38, |v18|, s88
	v_pk_add_f32 v[34:35], v[42:43], v[34:35]
	v_exp_f32_e32 v62, v38
	v_cndmask_b32_e32 v34, v205, v34, vcc
	v_cmp_neq_f32_e32 vcc, s90, v68
	v_min_f32_e32 v18, 0, v18
	v_add_f32_e32 v38, 1.0, v62
	v_cndmask_b32_e32 v35, v205, v35, vcc
	v_cmp_ngt_f32_e32 vcc, -1.0, v68
	v_frexp_mant_f32_e32 v40, v38
	s_nop 0
	v_cndmask_b32_e32 v35, v206, v35, vcc
	v_cmp_ngt_f32_e32 vcc, -1.0, v67
	s_nop 1
	v_cndmask_b32_e32 v34, v206, v34, vcc
	v_cmp_neq_f32_e32 vcc, -1.0, v67
	s_nop 1
	v_cndmask_b32_e32 v34, v207, v34, vcc
	v_cmp_neq_f32_e32 vcc, -1.0, v68
	s_nop 1
	v_cndmask_b32_e32 v35, v207, v35, vcc
	v_cmp_lt_f32_e64 vcc, |v68|, s91
	s_nop 1
	v_cndmask_b32_e32 v35, v35, v68, vcc
	v_cmp_lt_f32_e64 vcc, |v67|, s91
	s_nop 1
	v_cndmask_b32_e32 v34, v34, v67, vcc
	v_pk_add_f32 v[16:17], v[16:17], v[34:35] neg_lo:[0,1] neg_hi:[0,1]
	v_add_f32_e32 v34, -1.0, v38
	v_sub_f32_e32 v35, v34, v38
	v_add_f32_e32 v35, 1.0, v35
	v_sub_f32_e32 v34, v62, v34
	v_add_f32_e32 v39, v34, v35
	v_cvt_f64_f32_e32 v[34:35], v38
	v_frexp_exp_i32_f64_e32 v34, v[34:35]
	v_cmp_gt_f32_e32 vcc, s89, v40
	s_nop 1
	v_subbrev_co_u32_e32 v56, vcc, 0, v34, vcc
	v_mul_f32_e64 v34, |v19|, s88
	v_exp_f32_e32 v37, v34
	v_sub_u32_e32 v35, 0, v56
	v_ldexp_f32 v34, v38, v35
	v_ldexp_f32 v38, v39, v35
	v_add_f32_e32 v35, 1.0, v37
	v_add_f32_e32 v39, -1.0, v35
	v_sub_f32_e32 v40, v39, v35
	v_add_f32_e32 v40, 1.0, v40
	v_sub_f32_e32 v39, v37, v39
	v_add_f32_e32 v39, v39, v40
	v_frexp_mant_f32_e32 v42, v35
	v_cvt_f64_f32_e32 v[40:41], v35
	v_frexp_exp_i32_f64_e32 v40, v[40:41]
	v_cmp_gt_f32_e32 vcc, s89, v42
	v_min_f32_e32 v19, 0, v19
	s_nop 0
	v_subbrev_co_u32_e32 v57, vcc, 0, v40, vcc
	v_sub_u32_e32 v40, 0, v57
	v_ldexp_f32 v35, v35, v40
	v_ldexp_f32 v39, v39, v40
	v_pk_add_f32 v[40:41], v[34:35], 1.0 op_sel_hi:[1,0]
	v_pk_add_f32 v[48:49], v[34:35], -1.0 op_sel_hi:[1,0]
	v_pk_add_f32 v[42:43], v[40:41], -1.0 op_sel_hi:[1,0]
	v_pk_add_f32 v[50:51], v[48:49], 1.0 op_sel_hi:[1,0]
	v_pk_add_f32 v[42:43], v[34:35], v[42:43] neg_lo:[0,1] neg_hi:[0,1]
	v_pk_add_f32 v[34:35], v[34:35], v[50:51] neg_lo:[0,1] neg_hi:[0,1]
	v_pk_add_f32 v[42:43], v[38:39], v[42:43]
	v_pk_add_f32 v[34:35], v[38:39], v[34:35]
	v_pk_add_f32 v[44:45], v[40:41], v[42:43]
	v_pk_add_f32 v[38:39], v[48:49], v[34:35]
	v_rcp_f32_e32 v46, v44
	v_rcp_f32_e32 v47, v45
	v_pk_add_f32 v[40:41], v[44:45], v[40:41] neg_lo:[0,1] neg_hi:[0,1]
	v_pk_add_f32 v[48:49], v[38:39], v[48:49] neg_lo:[0,1] neg_hi:[0,1]
	v_pk_add_f32 v[40:41], v[42:43], v[40:41] neg_lo:[0,1] neg_hi:[0,1]
	v_pk_mul_f32 v[42:43], v[38:39], v[46:47]
	v_pk_add_f32 v[34:35], v[34:35], v[48:49] neg_lo:[0,1] neg_hi:[0,1]
	v_pk_mul_f32 v[48:49], v[44:45], v[42:43]
	v_cmp_neq_f32_e32 vcc, s90, v62
	v_pk_fma_f32 v[50:51], v[42:43], v[44:45], v[48:49] neg_lo:[0,0,1] neg_hi:[0,0,1]
	s_nop 0
	v_pk_fma_f32 v[50:51], v[42:43], v[40:41], v[50:51]
	s_nop 0
	v_pk_add_f32 v[52:53], v[48:49], v[50:51]
	s_nop 0
	v_pk_add_f32 v[54:55], v[38:39], v[52:53] neg_lo:[0,1] neg_hi:[0,1]
	v_pk_add_f32 v[48:49], v[52:53], v[48:49] neg_lo:[0,1] neg_hi:[0,1]
	v_pk_add_f32 v[38:39], v[38:39], v[54:55] neg_lo:[0,1] neg_hi:[0,1]
	s_nop 0
	v_pk_add_f32 v[38:39], v[38:39], v[52:53] neg_lo:[0,1] neg_hi:[0,1]
	s_nop 0
	v_pk_add_f32 v[34:35], v[34:35], v[38:39]
	v_pk_add_f32 v[38:39], v[48:49], v[50:51] neg_lo:[0,1] neg_hi:[0,1]
	s_nop 0
	v_pk_add_f32 v[34:35], v[38:39], v[34:35]
	s_nop 0
	v_pk_add_f32 v[38:39], v[54:55], v[34:35]
	s_nop 0
	v_pk_mul_f32 v[48:49], v[46:47], v[38:39]
	s_nop 0
	v_pk_mul_f32 v[50:51], v[44:45], v[48:49]
	s_nop 0
	v_pk_fma_f32 v[44:45], v[48:49], v[44:45], v[50:51] neg_lo:[0,0,1] neg_hi:[0,0,1]
	s_nop 0
	v_pk_fma_f32 v[40:41], v[48:49], v[40:41], v[44:45]
	v_pk_add_f32 v[44:45], v[54:55], v[38:39] neg_lo:[0,1] neg_hi:[0,1]
	s_nop 0
	v_pk_add_f32 v[34:35], v[34:35], v[44:45]
	v_pk_add_f32 v[44:45], v[50:51], v[40:41]
	s_nop 0
	v_pk_add_f32 v[52:53], v[38:39], v[44:45] neg_lo:[0,1] neg_hi:[0,1]
	v_pk_add_f32 v[50:51], v[44:45], v[50:51] neg_lo:[0,1] neg_hi:[0,1]
	v_pk_add_f32 v[38:39], v[38:39], v[52:53] neg_lo:[0,1] neg_hi:[0,1]
	s_nop 0
	v_pk_add_f32 v[38:39], v[38:39], v[44:45] neg_lo:[0,1] neg_hi:[0,1]
	v_cvt_f32_i32_e32 v45, v57
	v_pk_add_f32 v[34:35], v[34:35], v[38:39]
	v_pk_add_f32 v[38:39], v[50:51], v[40:41] neg_lo:[0,1] neg_hi:[0,1]
	v_cvt_f32_i32_e32 v44, v56
	v_pk_add_f32 v[34:35], v[38:39], v[34:35]
	v_pk_add_f32 v[38:39], v[42:43], v[48:49]
	v_pk_add_f32 v[34:35], v[52:53], v[34:35]
	v_pk_add_f32 v[40:41], v[38:39], v[42:43] neg_lo:[0,1] neg_hi:[0,1]
	v_pk_mul_f32 v[34:35], v[46:47], v[34:35]
	v_pk_add_f32 v[40:41], v[48:49], v[40:41] neg_lo:[0,1] neg_hi:[0,1]
	s_nop 0
	v_pk_add_f32 v[34:35], v[40:41], v[34:35]
	s_nop 0
	v_pk_add_f32 v[40:41], v[38:39], v[34:35]
	s_nop 0
	v_pk_mul_f32 v[42:43], v[40:41], v[40:41]
	v_pk_add_f32 v[38:39], v[40:41], v[38:39] neg_lo:[0,1] neg_hi:[0,1]
	v_pk_fma_f32 v[32:33], v[42:43], s[44:45], v[32:33] op_sel_hi:[1,0,0]
	v_pk_add_f32 v[34:35], v[34:35], v[38:39] neg_lo:[0,1] neg_hi:[0,1]
	v_ldexp_f32 v38, v40, 1
	v_pk_fma_f32 v[32:33], v[42:43], v[32:33], s[46:47] op_sel_hi:[1,1,0]
	v_ldexp_f32 v39, v41, 1
	v_pk_mul_f32 v[40:41], v[40:41], v[42:43]
	v_pk_mul_f32 v[42:43], v[44:45], s[48:49] op_sel_hi:[1,0]
	v_pk_mul_f32 v[32:33], v[40:41], v[32:33]
	v_pk_fma_f32 v[48:49], v[44:45], s[48:49], v[42:43] op_sel_hi:[1,0,1] neg_lo:[0,0,1] neg_hi:[0,0,1]
	v_pk_add_f32 v[40:41], v[38:39], v[32:33]
	v_ldexp_f32 v47, v35, 1
	v_pk_add_f32 v[38:39], v[40:41], v[38:39] neg_lo:[0,1] neg_hi:[0,1]
	v_pk_fma_f32 v[44:45], v[44:45], s[50:51], v[48:49] op_sel_hi:[1,0,1]
	v_pk_add_f32 v[32:33], v[32:33], v[38:39] neg_lo:[0,1] neg_hi:[0,1]
	v_ldexp_f32 v34, v34, 1
	v_mov_b32_e32 v38, v42
	v_mov_b32_e32 v39, v33
	v_mov_b32_e32 v46, v44
	v_mov_b32_e32 v35, v47
	v_pk_add_f32 v[38:39], v[38:39], v[46:47]
	v_pk_add_f32 v[46:47], v[34:35], v[32:33]
	v_mov_b32_e32 v33, v41
	v_mov_b32_e32 v35, v47
	v_pk_add_f32 v[48:49], v[42:43], v[44:45]
	v_pk_add_f32 v[32:33], v[34:35], v[32:33]
	v_pk_add_f32 v[34:35], v[40:41], v[46:47]
	v_mov_b32_e32 v58, v40
	v_pk_add_f32 v[50:51], v[48:49], v[34:35]
	v_mov_b32_e32 v56, v34
	v_mov_b32_e32 v57, v51
	v_mov_b32_e32 v59, v49
	v_pk_add_f32 v[56:57], v[56:57], v[58:59] neg_lo:[0,1] neg_hi:[0,1]
	v_mov_b32_e32 v52, v50
	v_mov_b32_e32 v53, v49
	v_mov_b32_e32 v54, v48
	v_mov_b32_e32 v55, v43
	v_mov_b32_e32 v58, v48
	v_mov_b32_e32 v59, v51
	v_mov_b32_e32 v43, v57
	v_pk_add_f32 v[52:53], v[52:53], v[54:55] neg_lo:[0,1] neg_hi:[0,1]
	v_mov_b32_e32 v54, v34
	v_mov_b32_e32 v55, v45
	v_pk_add_f32 v[42:43], v[58:59], v[42:43] neg_lo:[0,1] neg_hi:[0,1]
	v_pk_add_f32 v[54:55], v[54:55], v[52:53] neg_lo:[0,1] neg_hi:[0,1]
	v_mov_b32_e32 v58, v42
	v_mov_b32_e32 v59, v53
	v_mov_b32_e32 v60, v50
	v_mov_b32_e32 v61, v35
	v_mov_b32_e32 v53, v41
	v_pk_add_f32 v[58:59], v[44:45], v[58:59] neg_lo:[0,1] neg_hi:[0,1]
	v_pk_add_f32 v[52:53], v[60:61], v[52:53] neg_lo:[0,1] neg_hi:[0,1]
	v_mov_b32_e32 v45, v49
	v_pk_add_f32 v[34:35], v[34:35], v[40:41] neg_lo:[0,1] neg_hi:[0,1]
	v_pk_add_f32 v[38:39], v[38:39], v[52:53] neg_lo:[0,1] neg_hi:[0,1]
	v_pk_add_f32 v[40:41], v[44:45], v[42:43] neg_lo:[0,1] neg_hi:[0,1]
	v_pk_add_f32 v[32:33], v[32:33], v[56:57] neg_lo:[0,1] neg_hi:[0,1]
	v_pk_add_f32 v[44:45], v[54:55], v[38:39]
	v_pk_add_f32 v[42:43], v[32:33], v[40:41]
	v_mov_b32_e32 v41, v55
	v_mov_b32_e32 v33, v39
	v_pk_add_f32 v[32:33], v[40:41], v[32:33]
	v_mov_b32_e32 v38, v42
	v_pk_add_f32 v[32:33], v[32:33], v[58:59] neg_lo:[0,1] neg_hi:[0,1]
	v_mov_b32_e32 v39, v45
	v_pk_add_f32 v[34:35], v[46:47], v[34:35] neg_lo:[0,1] neg_hi:[0,1]
	v_pk_add_f32 v[38:39], v[38:39], v[32:33] neg_lo:[0,1] neg_hi:[0,1]
	v_pk_add_f32 v[32:33], v[34:35], v[32:33] neg_lo:[0,1] neg_hi:[0,1]
	v_pk_add_f32 v[38:39], v[40:41], v[38:39] neg_lo:[0,1] neg_hi:[0,1]
	v_pk_add_f32 v[34:35], v[44:45], v[42:43]
	v_pk_add_f32 v[32:33], v[32:33], v[38:39]
	v_pk_add_f32 v[38:39], v[50:51], v[34:35]
	s_nop 0
	v_pk_add_f32 v[40:41], v[38:39], v[50:51] neg_lo:[0,1] neg_hi:[0,1]
	s_nop 0
	v_pk_add_f32 v[34:35], v[34:35], v[40:41] neg_lo:[0,1] neg_hi:[0,1]
	s_nop 0
	v_pk_add_f32 v[32:33], v[32:33], v[34:35]
	s_nop 0
	v_pk_add_f32 v[32:33], v[38:39], v[32:33]
	s_nop 0
	v_cndmask_b32_e32 v32, v205, v32, vcc
	v_cmp_neq_f32_e32 vcc, s90, v37
	s_nop 1
	v_cndmask_b32_e32 v33, v205, v33, vcc
	v_cmp_ngt_f32_e32 vcc, -1.0, v37
	s_nop 1
	v_cndmask_b32_e32 v33, v206, v33, vcc
	v_cmp_ngt_f32_e32 vcc, -1.0, v62
	s_nop 1
	v_cndmask_b32_e32 v32, v206, v32, vcc
	v_cmp_neq_f32_e32 vcc, -1.0, v62
	s_nop 1
	v_cndmask_b32_e32 v32, v207, v32, vcc
	v_cmp_neq_f32_e32 vcc, -1.0, v37
	s_nop 1
	v_cndmask_b32_e32 v33, v207, v33, vcc
	v_cmp_lt_f32_e64 vcc, |v37|, s91
	s_nop 1
	v_cndmask_b32_e32 v33, v33, v37, vcc
	v_cmp_lt_f32_e64 vcc, |v62|, s91
	s_nop 1
	v_cndmask_b32_e32 v32, v32, v62, vcc
	v_pk_add_f32 v[18:19], v[18:19], v[32:33] neg_lo:[0,1] neg_hi:[0,1]
	v_lshl_or_b32 v32, v66, 3, v161
	v_ashrrev_i32_e32 v33, 31, v32
	v_lshlrev_b64 v[34:35], s53, v[32:33]
	v_lshl_add_u64 v[34:35], v[34:35], 2, s[78:79]
	v_lshl_add_u64 v[34:35], v[34:35], 0, v[152:153]
	global_store_dwordx4 v[34:35], v[16:19], off nt
	s_cbranch_scc1 .LBB0_242
	v_readlane_b32 s6, v250, 0
	v_readlane_b32 s7, v250, 1
	s_nop 1
	v_mov_b64_e32 v[38:39], s[6:7]
	v_mad_i64_i32 v[38:39], s[6:7], v32, s92, v[38:39]
	v_lshl_add_u64 v[38:39], v[38:39], 0, v[152:153]
	v_add_co_u32_e32 v38, vcc, 0x10c06000, v38
	s_nop 1
	v_addc_co_u32_e32 v39, vcc, 0, v39, vcc
	global_store_dwordx4 v[38:39], v[16:19], off offset:256 nt
.LBB0_242:
	global_load_dword v33, v[158:159], off
	s_nop 0
	v_mov_b64_e32 v[18:19], s[42:43]
	s_waitcnt vmcnt(0)
	v_add_f32_e32 v16, v20, v33
	v_mul_f32_e64 v20, |v16|, s88
	v_add_f32_e32 v17, v21, v33
	v_exp_f32_e32 v37, v20
	v_mul_f32_e64 v21, |v17|, s88
	v_exp_f32_e32 v76, v21
	v_add_f32_e32 v22, v22, v33
	v_add_f32_e32 v40, 1.0, v37
	v_frexp_mant_f32_e32 v43, v40
	v_cvt_f64_f32_e32 v[20:21], v40
	v_add_f32_e32 v41, 1.0, v76
	v_frexp_exp_i32_f64_e32 v20, v[20:21]
	v_cmp_gt_f32_e32 vcc, s89, v43
	v_add_f32_e32 v42, -1.0, v40
	v_add_f32_e32 v44, -1.0, v41
	v_frexp_mant_f32_e32 v45, v41
	v_cvt_f64_f32_e32 v[38:39], v41
	v_subbrev_co_u32_e32 v20, vcc, 0, v20, vcc
	v_sub_f32_e32 v46, v42, v40
	v_sub_f32_e32 v21, v44, v41
	v_frexp_exp_i32_f64_e32 v38, v[38:39]
	v_cmp_gt_f32_e32 vcc, s89, v45
	v_sub_f32_e32 v42, v37, v42
	v_sub_f32_e32 v44, v76, v44
	v_add_f32_e32 v39, 1.0, v46
	v_add_f32_e32 v21, 1.0, v21
	v_subbrev_co_u32_e32 v38, vcc, 0, v38, vcc
	v_add_f32_e32 v39, v42, v39
	v_sub_u32_e32 v42, 0, v20
	v_add_f32_e32 v43, v44, v21
	v_sub_u32_e32 v44, 0, v38
	v_cvt_f32_i32_e32 v21, v38
	v_cvt_f32_i32_e32 v20, v20
	v_ldexp_f32 v38, v40, v42
	v_ldexp_f32 v40, v39, v42
	v_ldexp_f32 v39, v41, v44
	v_ldexp_f32 v41, v43, v44
	v_pk_add_f32 v[42:43], v[38:39], 1.0 op_sel_hi:[1,0]
	v_pk_add_f32 v[44:45], v[38:39], -1.0 op_sel_hi:[1,0]
	v_pk_add_f32 v[46:47], v[42:43], -1.0 op_sel_hi:[1,0]
	v_pk_add_f32 v[48:49], v[44:45], 1.0 op_sel_hi:[1,0]
	v_pk_add_f32 v[46:47], v[38:39], v[46:47] neg_lo:[0,1] neg_hi:[0,1]
	v_pk_add_f32 v[38:39], v[38:39], v[48:49] neg_lo:[0,1] neg_hi:[0,1]
	v_pk_mul_f32 v[48:49], v[20:21], s[48:49] op_sel_hi:[1,0]
	v_pk_add_f32 v[46:47], v[40:41], v[46:47]
	v_pk_add_f32 v[38:39], v[40:41], v[38:39]
	v_pk_fma_f32 v[40:41], v[20:21], s[48:49], v[48:49] op_sel_hi:[1,0,1] neg_lo:[0,0,1] neg_hi:[0,0,1]
	v_pk_add_f32 v[54:55], v[42:43], v[46:47]
	v_pk_fma_f32 v[20:21], v[20:21], s[50:51], v[40:41] op_sel_hi:[1,0,1]
	v_rcp_f32_e32 v40, v54
	v_rcp_f32_e32 v41, v55
	v_pk_add_f32 v[56:57], v[44:45], v[38:39]
	v_pk_add_f32 v[42:43], v[54:55], v[42:43] neg_lo:[0,1] neg_hi:[0,1]
	v_pk_add_f32 v[44:45], v[56:57], v[44:45] neg_lo:[0,1] neg_hi:[0,1]
	v_pk_mul_f32 v[66:67], v[56:57], v[40:41]
	v_pk_add_f32 v[42:43], v[46:47], v[42:43] neg_lo:[0,1] neg_hi:[0,1]
	v_pk_mul_f32 v[68:69], v[54:55], v[66:67]
	v_pk_add_f32 v[38:39], v[38:39], v[44:45] neg_lo:[0,1] neg_hi:[0,1]
	v_pk_fma_f32 v[70:71], v[66:67], v[54:55], v[68:69] neg_lo:[0,0,1] neg_hi:[0,0,1]
	v_pk_add_f32 v[58:59], v[48:49], v[20:21]
	v_pk_fma_f32 v[70:71], v[66:67], v[42:43], v[70:71]
	v_mov_b32_e32 v50, v48
	v_pk_add_f32 v[72:73], v[68:69], v[70:71]
	v_mov_b32_e32 v60, v20
	v_pk_add_f32 v[74:75], v[56:57], v[72:73] neg_lo:[0,1] neg_hi:[0,1]
	v_pk_add_f32 v[68:69], v[72:73], v[68:69] neg_lo:[0,1] neg_hi:[0,1]
	v_pk_add_f32 v[56:57], v[56:57], v[74:75] neg_lo:[0,1] neg_hi:[0,1]
	v_pk_add_f32 v[68:69], v[68:69], v[70:71] neg_lo:[0,1] neg_hi:[0,1]
	v_pk_add_f32 v[56:57], v[56:57], v[72:73] neg_lo:[0,1] neg_hi:[0,1]
	v_mov_b32_e32 v47, v59
	v_pk_add_f32 v[38:39], v[38:39], v[56:57]
	v_mov_b32_e32 v53, v49
	v_pk_add_f32 v[38:39], v[68:69], v[38:39]
	v_mov_b32_e32 v45, v59
	v_pk_add_f32 v[56:57], v[74:75], v[38:39]
	v_mov_b32_e32 v52, v58
	v_pk_mul_f32 v[68:69], v[40:41], v[56:57]
	v_pk_add_f32 v[70:71], v[74:75], v[56:57] neg_lo:[0,1] neg_hi:[0,1]
	v_pk_mul_f32 v[72:73], v[54:55], v[68:69]
	v_pk_add_f32 v[38:39], v[38:39], v[70:71]
	v_pk_add_f32 v[70:71], v[66:67], v[68:69]
	v_pk_fma_f32 v[54:55], v[68:69], v[54:55], v[72:73] neg_lo:[0,0,1] neg_hi:[0,0,1]
	v_pk_add_f32 v[66:67], v[70:71], v[66:67] neg_lo:[0,1] neg_hi:[0,1]
	v_pk_fma_f32 v[42:43], v[68:69], v[42:43], v[54:55]
	v_pk_add_f32 v[54:55], v[68:69], v[66:67] neg_lo:[0,1] neg_hi:[0,1]
	v_pk_add_f32 v[66:67], v[72:73], v[42:43]
	v_mov_b32_e32 v64, v58
	v_pk_add_f32 v[68:69], v[66:67], v[72:73] neg_lo:[0,1] neg_hi:[0,1]
	v_pk_add_f32 v[72:73], v[56:57], v[66:67] neg_lo:[0,1] neg_hi:[0,1]
	v_pk_add_f32 v[42:43], v[68:69], v[42:43] neg_lo:[0,1] neg_hi:[0,1]
	v_pk_add_f32 v[56:57], v[56:57], v[72:73] neg_lo:[0,1] neg_hi:[0,1]
	v_mov_b32_e32 v63, v21
	v_pk_add_f32 v[56:57], v[56:57], v[66:67] neg_lo:[0,1] neg_hi:[0,1]
	v_cmp_neq_f32_e32 vcc, s90, v37
	v_pk_add_f32 v[38:39], v[38:39], v[56:57]
	v_min_f32_e32 v16, 0, v16
	v_pk_add_f32 v[38:39], v[42:43], v[38:39]
	v_min_f32_e32 v17, 0, v17
	v_pk_add_f32 v[38:39], v[72:73], v[38:39]
	v_add_f32_e32 v23, v23, v33
	v_pk_mul_f32 v[38:39], v[40:41], v[38:39]
	s_nop 0
	v_pk_add_f32 v[38:39], v[54:55], v[38:39]
	s_nop 0
	v_pk_add_f32 v[40:41], v[70:71], v[38:39]
	s_nop 0
	v_pk_add_f32 v[42:43], v[40:41], v[70:71] neg_lo:[0,1] neg_hi:[0,1]
	v_pk_mul_f32 v[56:57], v[40:41], v[40:41]
	v_pk_add_f32 v[38:39], v[38:39], v[42:43] neg_lo:[0,1] neg_hi:[0,1]
	v_pk_fma_f32 v[42:43], v[56:57], s[44:45], v[18:19] op_sel_hi:[1,0,0]
	v_ldexp_f32 v54, v40, 1
	v_ldexp_f32 v55, v41, 1
	v_pk_mul_f32 v[40:41], v[40:41], v[56:57]
	v_pk_fma_f32 v[42:43], v[56:57], v[42:43], s[46:47] op_sel_hi:[1,1,0]
	v_ldexp_f32 v61, v39, 1
	v_pk_mul_f32 v[40:41], v[40:41], v[42:43]
	v_ldexp_f32 v38, v38, 1
	v_pk_add_f32 v[42:43], v[54:55], v[40:41]
	v_mov_b32_e32 v39, v61
	v_pk_add_f32 v[54:55], v[42:43], v[54:55] neg_lo:[0,1] neg_hi:[0,1]
	v_mov_b32_e32 v46, v42
	v_pk_add_f32 v[40:41], v[40:41], v[54:55] neg_lo:[0,1] neg_hi:[0,1]
	s_nop 0
	v_pk_add_f32 v[54:55], v[38:39], v[40:41]
	v_mov_b32_e32 v51, v41
	v_mov_b32_e32 v41, v43
	v_mov_b32_e32 v39, v55
	v_pk_add_f32 v[56:57], v[42:43], v[54:55]
	v_pk_add_f32 v[38:39], v[38:39], v[40:41]
	v_pk_add_f32 v[40:41], v[58:59], v[56:57]
	v_pk_add_f32 v[50:51], v[50:51], v[60:61]
	v_mov_b32_e32 v60, v56
	v_mov_b32_e32 v61, v41
	v_pk_add_f32 v[46:47], v[60:61], v[46:47] neg_lo:[0,1] neg_hi:[0,1]
	v_mov_b32_e32 v44, v40
	v_mov_b32_e32 v65, v41
	v_mov_b32_e32 v49, v47
	v_mov_b32_e32 v62, v56
	v_pk_add_f32 v[44:45], v[44:45], v[52:53] neg_lo:[0,1] neg_hi:[0,1]
	v_pk_add_f32 v[48:49], v[64:65], v[48:49] neg_lo:[0,1] neg_hi:[0,1]
	v_mov_b32_e32 v66, v40
	v_pk_add_f32 v[52:53], v[62:63], v[44:45] neg_lo:[0,1] neg_hi:[0,1]
	v_mov_b32_e32 v61, v45
	v_mov_b32_e32 v60, v48
	v_mov_b32_e32 v67, v57
	v_mov_b32_e32 v45, v43
	v_pk_add_f32 v[60:61], v[20:21], v[60:61] neg_lo:[0,1] neg_hi:[0,1]
	v_pk_add_f32 v[44:45], v[66:67], v[44:45] neg_lo:[0,1] neg_hi:[0,1]
	v_mov_b32_e32 v21, v59
	v_pk_add_f32 v[44:45], v[50:51], v[44:45] neg_lo:[0,1] neg_hi:[0,1]
	v_pk_add_f32 v[20:21], v[20:21], v[48:49] neg_lo:[0,1] neg_hi:[0,1]
	v_pk_add_f32 v[38:39], v[38:39], v[46:47] neg_lo:[0,1] neg_hi:[0,1]
	v_pk_add_f32 v[48:49], v[52:53], v[44:45]
	v_pk_add_f32 v[46:47], v[38:39], v[20:21]
	v_mov_b32_e32 v21, v53
	v_mov_b32_e32 v39, v45
	v_pk_add_f32 v[38:39], v[20:21], v[38:39]
	v_pk_add_f32 v[42:43], v[56:57], v[42:43] neg_lo:[0,1] neg_hi:[0,1]
	v_pk_add_f32 v[38:39], v[38:39], v[60:61] neg_lo:[0,1] neg_hi:[0,1]
	v_mov_b32_e32 v44, v46
	v_mov_b32_e32 v45, v49
	v_pk_add_f32 v[42:43], v[54:55], v[42:43] neg_lo:[0,1] neg_hi:[0,1]
	v_pk_add_f32 v[44:45], v[44:45], v[38:39] neg_lo:[0,1] neg_hi:[0,1]
	v_pk_add_f32 v[38:39], v[42:43], v[38:39] neg_lo:[0,1] neg_hi:[0,1]
	v_pk_add_f32 v[20:21], v[20:21], v[44:45] neg_lo:[0,1] neg_hi:[0,1]
	s_nop 0
	v_pk_add_f32 v[20:21], v[38:39], v[20:21]
	v_pk_add_f32 v[38:39], v[48:49], v[46:47]
	s_nop 0
	v_pk_add_f32 v[42:43], v[40:41], v[38:39]
	s_nop 0
	v_pk_add_f32 v[40:41], v[42:43], v[40:41] neg_lo:[0,1] neg_hi:[0,1]
	s_nop 0
	v_pk_add_f32 v[38:39], v[38:39], v[40:41] neg_lo:[0,1] neg_hi:[0,1]
	s_nop 0
	v_pk_add_f32 v[20:21], v[20:21], v[38:39]
	v_mul_f32_e64 v38, |v22|, s88
	v_pk_add_f32 v[20:21], v[42:43], v[20:21]
	v_exp_f32_e32 v62, v38
	v_cndmask_b32_e32 v20, v205, v20, vcc
	v_cmp_neq_f32_e32 vcc, s90, v76
	s_nop 1
	v_cndmask_b32_e32 v21, v205, v21, vcc
	v_cmp_ngt_f32_e32 vcc, -1.0, v76
	s_nop 1
	v_cndmask_b32_e32 v21, v206, v21, vcc
	v_cmp_ngt_f32_e32 vcc, -1.0, v37
	s_nop 1
	v_cndmask_b32_e32 v20, v206, v20, vcc
	v_cmp_neq_f32_e32 vcc, -1.0, v37
	s_nop 1
	v_cndmask_b32_e32 v20, v207, v20, vcc
	v_cmp_neq_f32_e32 vcc, -1.0, v76
	s_nop 1
	v_cndmask_b32_e32 v21, v207, v21, vcc
	v_cmp_lt_f32_e64 vcc, |v76|, s91
	s_nop 1
	v_cndmask_b32_e32 v21, v21, v76, vcc
	v_cmp_lt_f32_e64 vcc, |v37|, s91
	s_nop 1
	v_cndmask_b32_e32 v20, v20, v37, vcc
	v_pk_add_f32 v[16:17], v[16:17], v[20:21] neg_lo:[0,1] neg_hi:[0,1]
	v_add_f32_e32 v21, 1.0, v62
	v_min_f32_e32 v20, 0, v22
	v_add_f32_e32 v22, -1.0, v21
	v_sub_f32_e32 v37, v22, v21
	v_add_f32_e32 v37, 1.0, v37
	v_sub_f32_e32 v22, v62, v22
	v_add_f32_e32 v37, v22, v37
	v_frexp_mant_f32_e32 v22, v21
	v_cmp_gt_f32_e32 vcc, s89, v22
	v_mul_f32_e64 v22, |v23|, s88
	v_cvt_f64_f32_e32 v[38:39], v21
	v_exp_f32_e32 v33, v22
	v_frexp_exp_i32_f64_e32 v38, v[38:39]
	v_subbrev_co_u32_e32 v56, vcc, 0, v38, vcc
	v_sub_u32_e32 v38, 0, v56
	v_ldexp_f32 v22, v21, v38
	v_min_f32_e32 v21, 0, v23
	v_add_f32_e32 v23, 1.0, v33
	v_ldexp_f32 v38, v37, v38
	v_add_f32_e32 v37, -1.0, v23
	v_sub_f32_e32 v39, v37, v23
	v_add_f32_e32 v39, 1.0, v39
	v_sub_f32_e32 v37, v33, v37
	v_add_f32_e32 v37, v37, v39
	v_frexp_mant_f32_e32 v39, v23
	v_cvt_f64_f32_e32 v[40:41], v23
	v_frexp_exp_i32_f64_e32 v40, v[40:41]
	v_cmp_gt_f32_e32 vcc, s89, v39
	s_nop 1
	v_subbrev_co_u32_e32 v57, vcc, 0, v40, vcc
	v_sub_u32_e32 v39, 0, v57
	v_ldexp_f32 v23, v23, v39
	v_pk_add_f32 v[40:41], v[22:23], 1.0 op_sel_hi:[1,0]
	v_ldexp_f32 v39, v37, v39
	v_pk_add_f32 v[42:43], v[40:41], -1.0 op_sel_hi:[1,0]
	v_pk_add_f32 v[48:49], v[22:23], -1.0 op_sel_hi:[1,0]
	v_pk_add_f32 v[42:43], v[22:23], v[42:43] neg_lo:[0,1] neg_hi:[0,1]
	v_pk_add_f32 v[50:51], v[48:49], 1.0 op_sel_hi:[1,0]
	v_pk_add_f32 v[42:43], v[38:39], v[42:43]
	v_pk_add_f32 v[22:23], v[22:23], v[50:51] neg_lo:[0,1] neg_hi:[0,1]
	v_pk_add_f32 v[44:45], v[40:41], v[42:43]
	v_pk_add_f32 v[22:23], v[38:39], v[22:23]
	v_rcp_f32_e32 v46, v44
	v_rcp_f32_e32 v47, v45
	v_pk_add_f32 v[38:39], v[48:49], v[22:23]
	v_pk_add_f32 v[40:41], v[44:45], v[40:41] neg_lo:[0,1] neg_hi:[0,1]
	v_pk_add_f32 v[48:49], v[38:39], v[48:49] neg_lo:[0,1] neg_hi:[0,1]
	v_pk_add_f32 v[40:41], v[42:43], v[40:41] neg_lo:[0,1] neg_hi:[0,1]
	v_pk_mul_f32 v[42:43], v[38:39], v[46:47]
	v_pk_add_f32 v[22:23], v[22:23], v[48:49] neg_lo:[0,1] neg_hi:[0,1]
	v_pk_mul_f32 v[48:49], v[44:45], v[42:43]
	v_cmp_neq_f32_e32 vcc, s90, v62
	v_pk_fma_f32 v[50:51], v[42:43], v[44:45], v[48:49] neg_lo:[0,0,1] neg_hi:[0,0,1]
	s_nop 0
	v_pk_fma_f32 v[50:51], v[42:43], v[40:41], v[50:51]
	s_nop 0
	v_pk_add_f32 v[52:53], v[48:49], v[50:51]
	s_nop 0
	v_pk_add_f32 v[54:55], v[38:39], v[52:53] neg_lo:[0,1] neg_hi:[0,1]
	v_pk_add_f32 v[48:49], v[52:53], v[48:49] neg_lo:[0,1] neg_hi:[0,1]
	v_pk_add_f32 v[38:39], v[38:39], v[54:55] neg_lo:[0,1] neg_hi:[0,1]
	s_nop 0
	v_pk_add_f32 v[38:39], v[38:39], v[52:53] neg_lo:[0,1] neg_hi:[0,1]
	s_nop 0
	v_pk_add_f32 v[22:23], v[22:23], v[38:39]
	v_pk_add_f32 v[38:39], v[48:49], v[50:51] neg_lo:[0,1] neg_hi:[0,1]
	s_nop 0
	v_pk_add_f32 v[22:23], v[38:39], v[22:23]
	s_nop 0
	v_pk_add_f32 v[38:39], v[54:55], v[22:23]
	s_nop 0
	v_pk_mul_f32 v[48:49], v[46:47], v[38:39]
	s_nop 0
	v_pk_mul_f32 v[50:51], v[44:45], v[48:49]
	s_nop 0
	v_pk_fma_f32 v[44:45], v[48:49], v[44:45], v[50:51] neg_lo:[0,0,1] neg_hi:[0,0,1]
	s_nop 0
	v_pk_fma_f32 v[40:41], v[48:49], v[40:41], v[44:45]
	v_pk_add_f32 v[44:45], v[54:55], v[38:39] neg_lo:[0,1] neg_hi:[0,1]
	s_nop 0
	v_pk_add_f32 v[22:23], v[22:23], v[44:45]
	v_pk_add_f32 v[44:45], v[50:51], v[40:41]
	s_nop 0
	v_pk_add_f32 v[52:53], v[38:39], v[44:45] neg_lo:[0,1] neg_hi:[0,1]
	v_pk_add_f32 v[50:51], v[44:45], v[50:51] neg_lo:[0,1] neg_hi:[0,1]
	v_pk_add_f32 v[38:39], v[38:39], v[52:53] neg_lo:[0,1] neg_hi:[0,1]
	s_nop 0
	v_pk_add_f32 v[38:39], v[38:39], v[44:45] neg_lo:[0,1] neg_hi:[0,1]
	v_cvt_f32_i32_e32 v45, v57
	v_pk_add_f32 v[22:23], v[22:23], v[38:39]
	v_pk_add_f32 v[38:39], v[50:51], v[40:41] neg_lo:[0,1] neg_hi:[0,1]
	v_cvt_f32_i32_e32 v44, v56
	v_pk_add_f32 v[22:23], v[38:39], v[22:23]
	v_pk_add_f32 v[38:39], v[42:43], v[48:49]
	v_pk_add_f32 v[22:23], v[52:53], v[22:23]
	v_pk_add_f32 v[40:41], v[38:39], v[42:43] neg_lo:[0,1] neg_hi:[0,1]
	v_pk_mul_f32 v[22:23], v[46:47], v[22:23]
	v_pk_add_f32 v[40:41], v[48:49], v[40:41] neg_lo:[0,1] neg_hi:[0,1]
	s_nop 0
	v_pk_add_f32 v[22:23], v[40:41], v[22:23]
	s_nop 0
	v_pk_add_f32 v[40:41], v[38:39], v[22:23]
	s_nop 0
	v_pk_mul_f32 v[42:43], v[40:41], v[40:41]
	v_pk_add_f32 v[38:39], v[40:41], v[38:39] neg_lo:[0,1] neg_hi:[0,1]
	v_pk_fma_f32 v[18:19], v[42:43], s[44:45], v[18:19] op_sel_hi:[1,0,0]
	v_pk_add_f32 v[22:23], v[22:23], v[38:39] neg_lo:[0,1] neg_hi:[0,1]
	v_ldexp_f32 v38, v40, 1
	v_pk_fma_f32 v[18:19], v[42:43], v[18:19], s[46:47] op_sel_hi:[1,1,0]
	v_ldexp_f32 v39, v41, 1
	v_pk_mul_f32 v[40:41], v[40:41], v[42:43]
	v_pk_mul_f32 v[42:43], v[44:45], s[48:49] op_sel_hi:[1,0]
	v_pk_mul_f32 v[18:19], v[40:41], v[18:19]
	v_pk_fma_f32 v[48:49], v[44:45], s[48:49], v[42:43] op_sel_hi:[1,0,1] neg_lo:[0,0,1] neg_hi:[0,0,1]
	v_pk_add_f32 v[40:41], v[38:39], v[18:19]
	v_ldexp_f32 v47, v23, 1
	v_pk_add_f32 v[38:39], v[40:41], v[38:39] neg_lo:[0,1] neg_hi:[0,1]
	v_pk_fma_f32 v[44:45], v[44:45], s[50:51], v[48:49] op_sel_hi:[1,0,1]
	v_pk_add_f32 v[18:19], v[18:19], v[38:39] neg_lo:[0,1] neg_hi:[0,1]
	v_ldexp_f32 v22, v22, 1
	v_mov_b32_e32 v38, v42
	v_mov_b32_e32 v39, v19
	v_mov_b32_e32 v46, v44
	v_mov_b32_e32 v23, v47
	v_pk_add_f32 v[38:39], v[38:39], v[46:47]
	v_pk_add_f32 v[46:47], v[22:23], v[18:19]
	v_mov_b32_e32 v19, v41
	v_mov_b32_e32 v23, v47
	v_pk_add_f32 v[48:49], v[42:43], v[44:45]
	v_pk_add_f32 v[18:19], v[22:23], v[18:19]
	v_pk_add_f32 v[22:23], v[40:41], v[46:47]
	v_mov_b32_e32 v58, v40
	v_pk_add_f32 v[50:51], v[48:49], v[22:23]
	v_mov_b32_e32 v56, v22
	v_mov_b32_e32 v57, v51
	v_mov_b32_e32 v59, v49
	v_pk_add_f32 v[56:57], v[56:57], v[58:59] neg_lo:[0,1] neg_hi:[0,1]
	v_mov_b32_e32 v52, v50
	v_mov_b32_e32 v53, v49
	v_mov_b32_e32 v54, v48
	v_mov_b32_e32 v55, v43
	v_mov_b32_e32 v58, v48
	v_mov_b32_e32 v59, v51
	v_mov_b32_e32 v43, v57
	v_pk_add_f32 v[52:53], v[52:53], v[54:55] neg_lo:[0,1] neg_hi:[0,1]
	v_mov_b32_e32 v54, v22
	v_mov_b32_e32 v55, v45
	v_pk_add_f32 v[42:43], v[58:59], v[42:43] neg_lo:[0,1] neg_hi:[0,1]
	v_pk_add_f32 v[54:55], v[54:55], v[52:53] neg_lo:[0,1] neg_hi:[0,1]
	v_mov_b32_e32 v58, v42
	v_mov_b32_e32 v59, v53
	v_mov_b32_e32 v60, v50
	v_mov_b32_e32 v61, v23
	v_mov_b32_e32 v53, v41
	v_pk_add_f32 v[58:59], v[44:45], v[58:59] neg_lo:[0,1] neg_hi:[0,1]
	v_pk_add_f32 v[52:53], v[60:61], v[52:53] neg_lo:[0,1] neg_hi:[0,1]
	v_mov_b32_e32 v45, v49
	v_pk_add_f32 v[22:23], v[22:23], v[40:41] neg_lo:[0,1] neg_hi:[0,1]
	v_pk_add_f32 v[38:39], v[38:39], v[52:53] neg_lo:[0,1] neg_hi:[0,1]
	v_pk_add_f32 v[40:41], v[44:45], v[42:43] neg_lo:[0,1] neg_hi:[0,1]
	v_pk_add_f32 v[18:19], v[18:19], v[56:57] neg_lo:[0,1] neg_hi:[0,1]
	v_pk_add_f32 v[44:45], v[54:55], v[38:39]
	v_pk_add_f32 v[42:43], v[18:19], v[40:41]
	v_mov_b32_e32 v41, v55
	v_mov_b32_e32 v19, v39
	v_pk_add_f32 v[18:19], v[40:41], v[18:19]
	v_mov_b32_e32 v38, v42
	v_pk_add_f32 v[18:19], v[18:19], v[58:59] neg_lo:[0,1] neg_hi:[0,1]
	v_mov_b32_e32 v39, v45
	v_pk_add_f32 v[22:23], v[46:47], v[22:23] neg_lo:[0,1] neg_hi:[0,1]
	v_pk_add_f32 v[38:39], v[38:39], v[18:19] neg_lo:[0,1] neg_hi:[0,1]
	v_pk_add_f32 v[18:19], v[22:23], v[18:19] neg_lo:[0,1] neg_hi:[0,1]
	v_pk_add_f32 v[38:39], v[40:41], v[38:39] neg_lo:[0,1] neg_hi:[0,1]
	v_pk_add_f32 v[22:23], v[44:45], v[42:43]
	v_pk_add_f32 v[18:19], v[18:19], v[38:39]
	v_pk_add_f32 v[38:39], v[50:51], v[22:23]
	s_nop 0
	v_pk_add_f32 v[40:41], v[38:39], v[50:51] neg_lo:[0,1] neg_hi:[0,1]
	s_nop 0
	v_pk_add_f32 v[22:23], v[22:23], v[40:41] neg_lo:[0,1] neg_hi:[0,1]
	s_nop 0
	v_pk_add_f32 v[18:19], v[18:19], v[22:23]
	s_nop 0
	v_pk_add_f32 v[18:19], v[38:39], v[18:19]
	s_nop 0
	v_cndmask_b32_e32 v18, v205, v18, vcc
	v_cmp_neq_f32_e32 vcc, s90, v33
	s_nop 1
	v_cndmask_b32_e32 v19, v205, v19, vcc
	v_cmp_ngt_f32_e32 vcc, -1.0, v33
	s_nop 1
	v_cndmask_b32_e32 v19, v206, v19, vcc
	v_cmp_ngt_f32_e32 vcc, -1.0, v62
	s_nop 1
	v_cndmask_b32_e32 v18, v206, v18, vcc
	v_cmp_neq_f32_e32 vcc, -1.0, v62
	s_nop 1
	v_cndmask_b32_e32 v18, v207, v18, vcc
	v_cmp_neq_f32_e32 vcc, -1.0, v33
	s_nop 1
	v_cndmask_b32_e32 v19, v207, v19, vcc
	v_cmp_lt_f32_e64 vcc, |v33|, s91
	s_nop 1
	v_cndmask_b32_e32 v19, v19, v33, vcc
	v_cmp_lt_f32_e64 vcc, |v62|, s91
	s_nop 1
	v_cndmask_b32_e32 v18, v18, v62, vcc
	v_pk_add_f32 v[18:19], v[20:21], v[18:19] neg_lo:[0,1] neg_hi:[0,1]
	v_cndmask_b32_e64 v20, 0, 1, s[4:5]
	v_cmp_ne_u32_e64 s[6:7], 1, v20
	s_andn2_b64 vcc, exec, s[4:5]
	v_mov_b32_e32 v20, s54
	global_store_dwordx4 v[34:35], v[16:19], off offset:32 nt
	s_cbranch_vccnz .LBB0_244
	v_readlane_b32 s62, v250, 0
	v_readlane_b32 s63, v250, 1
	v_lshl_or_b32 v152, v36, 2, 32
	s_nop 0
	v_mov_b64_e32 v[20:21], s[62:63]
	v_mad_i64_i32 v[20:21], s[62:63], v32, s92, v[20:21]
	v_lshl_add_u64 v[20:21], v[20:21], 0, v[152:153]
	v_add_co_u32_e32 v20, vcc, 0x10c06000, v20
	s_nop 1
	v_addc_co_u32_e32 v21, vcc, 0, v21, vcc
	global_store_dwordx4 v[20:21], v[16:19], off offset:256 nt
	v_mov_b32_e32 v20, v185
.LBB0_244:
	global_load_dword v21, v[158:159], off
	v_or_b32_e32 v16, s55, v186
	v_cndmask_b32_e64 v68, v16, v182, s[4:5]
	v_mov_b64_e32 v[18:19], s[42:43]
	v_lshl_or_b32 v20, v20, 3, v161
	v_lshlrev_b32_e32 v152, 2, v68
	s_waitcnt vmcnt(0)
	v_add_f32_e32 v16, v24, v21
	v_mul_f32_e64 v22, |v16|, s88
	v_add_f32_e32 v17, v25, v21
	v_exp_f32_e32 v69, v22
	v_mul_f32_e64 v23, |v17|, s88
	v_exp_f32_e32 v70, v23
	v_min_f32_e32 v16, 0, v16
	v_add_f32_e32 v32, 1.0, v69
	v_frexp_mant_f32_e32 v35, v32
	v_cvt_f64_f32_e32 v[22:23], v32
	v_add_f32_e32 v33, 1.0, v70
	v_frexp_exp_i32_f64_e32 v22, v[22:23]
	v_cmp_gt_f32_e32 vcc, s89, v35
	v_add_f32_e32 v34, -1.0, v32
	v_add_f32_e32 v36, -1.0, v33
	v_frexp_mant_f32_e32 v37, v33
	v_cvt_f64_f32_e32 v[24:25], v33
	v_subbrev_co_u32_e32 v22, vcc, 0, v22, vcc
	v_sub_f32_e32 v38, v34, v32
	v_sub_f32_e32 v23, v36, v33
	v_frexp_exp_i32_f64_e32 v24, v[24:25]
	v_cmp_gt_f32_e32 vcc, s89, v37
	v_sub_f32_e32 v34, v69, v34
	v_sub_f32_e32 v36, v70, v36
	v_add_f32_e32 v25, 1.0, v38
	v_add_f32_e32 v23, 1.0, v23
	v_subbrev_co_u32_e32 v24, vcc, 0, v24, vcc
	v_add_f32_e32 v25, v34, v25
	v_sub_u32_e32 v34, 0, v22
	v_add_f32_e32 v35, v36, v23
	v_sub_u32_e32 v36, 0, v24
	v_cvt_f32_i32_e32 v23, v24
	v_cvt_f32_i32_e32 v22, v22
	v_ldexp_f32 v24, v32, v34
	v_ldexp_f32 v32, v25, v34
	v_ldexp_f32 v25, v33, v36
	v_ldexp_f32 v33, v35, v36
	v_pk_add_f32 v[34:35], v[24:25], 1.0 op_sel_hi:[1,0]
	v_pk_add_f32 v[36:37], v[24:25], -1.0 op_sel_hi:[1,0]
	v_pk_add_f32 v[38:39], v[34:35], -1.0 op_sel_hi:[1,0]
	v_pk_add_f32 v[40:41], v[36:37], 1.0 op_sel_hi:[1,0]
	v_pk_add_f32 v[38:39], v[24:25], v[38:39] neg_lo:[0,1] neg_hi:[0,1]
	v_pk_add_f32 v[24:25], v[24:25], v[40:41] neg_lo:[0,1] neg_hi:[0,1]
	v_pk_mul_f32 v[40:41], v[22:23], s[48:49] op_sel_hi:[1,0]
	v_pk_add_f32 v[38:39], v[32:33], v[38:39]
	v_pk_add_f32 v[24:25], v[32:33], v[24:25]
	v_pk_fma_f32 v[32:33], v[22:23], s[48:49], v[40:41] op_sel_hi:[1,0,1] neg_lo:[0,0,1] neg_hi:[0,0,1]
	v_pk_add_f32 v[46:47], v[34:35], v[38:39]
	v_pk_fma_f32 v[22:23], v[22:23], s[50:51], v[32:33] op_sel_hi:[1,0,1]
	v_rcp_f32_e32 v32, v46
	v_rcp_f32_e32 v33, v47
	v_pk_add_f32 v[48:49], v[36:37], v[24:25]
	v_pk_add_f32 v[34:35], v[46:47], v[34:35] neg_lo:[0,1] neg_hi:[0,1]
	v_pk_add_f32 v[36:37], v[48:49], v[36:37] neg_lo:[0,1] neg_hi:[0,1]
	v_pk_mul_f32 v[58:59], v[48:49], v[32:33]
	v_pk_add_f32 v[34:35], v[38:39], v[34:35] neg_lo:[0,1] neg_hi:[0,1]
	v_pk_mul_f32 v[60:61], v[46:47], v[58:59]
	v_pk_add_f32 v[24:25], v[24:25], v[36:37] neg_lo:[0,1] neg_hi:[0,1]
	v_pk_fma_f32 v[62:63], v[58:59], v[46:47], v[60:61] neg_lo:[0,0,1] neg_hi:[0,0,1]
	v_pk_add_f32 v[50:51], v[40:41], v[22:23]
	v_pk_fma_f32 v[62:63], v[58:59], v[34:35], v[62:63]
	v_mov_b32_e32 v42, v40
	v_pk_add_f32 v[64:65], v[60:61], v[62:63]
	v_mov_b32_e32 v52, v22
	v_pk_add_f32 v[66:67], v[48:49], v[64:65] neg_lo:[0,1] neg_hi:[0,1]
	v_pk_add_f32 v[60:61], v[64:65], v[60:61] neg_lo:[0,1] neg_hi:[0,1]
	v_pk_add_f32 v[48:49], v[48:49], v[66:67] neg_lo:[0,1] neg_hi:[0,1]
	v_pk_add_f32 v[60:61], v[60:61], v[62:63] neg_lo:[0,1] neg_hi:[0,1]
	v_pk_add_f32 v[48:49], v[48:49], v[64:65] neg_lo:[0,1] neg_hi:[0,1]
	v_mov_b32_e32 v39, v51
	v_pk_add_f32 v[24:25], v[24:25], v[48:49]
	v_mov_b32_e32 v45, v41
	v_pk_add_f32 v[24:25], v[60:61], v[24:25]
	v_mov_b32_e32 v37, v51
	v_pk_add_f32 v[48:49], v[66:67], v[24:25]
	v_mov_b32_e32 v44, v50
	v_pk_mul_f32 v[60:61], v[32:33], v[48:49]
	v_pk_add_f32 v[62:63], v[66:67], v[48:49] neg_lo:[0,1] neg_hi:[0,1]
	v_pk_mul_f32 v[64:65], v[46:47], v[60:61]
	v_pk_add_f32 v[24:25], v[24:25], v[62:63]
	v_pk_add_f32 v[62:63], v[58:59], v[60:61]
	v_pk_fma_f32 v[46:47], v[60:61], v[46:47], v[64:65] neg_lo:[0,0,1] neg_hi:[0,0,1]
	v_pk_add_f32 v[58:59], v[62:63], v[58:59] neg_lo:[0,1] neg_hi:[0,1]
	v_pk_fma_f32 v[34:35], v[60:61], v[34:35], v[46:47]
	v_pk_add_f32 v[46:47], v[60:61], v[58:59] neg_lo:[0,1] neg_hi:[0,1]
	v_pk_add_f32 v[58:59], v[64:65], v[34:35]
	v_mov_b32_e32 v56, v50
	v_pk_add_f32 v[60:61], v[58:59], v[64:65] neg_lo:[0,1] neg_hi:[0,1]
	v_pk_add_f32 v[64:65], v[48:49], v[58:59] neg_lo:[0,1] neg_hi:[0,1]
	v_pk_add_f32 v[34:35], v[60:61], v[34:35] neg_lo:[0,1] neg_hi:[0,1]
	v_pk_add_f32 v[48:49], v[48:49], v[64:65] neg_lo:[0,1] neg_hi:[0,1]
	v_mov_b32_e32 v55, v23
	v_pk_add_f32 v[48:49], v[48:49], v[58:59] neg_lo:[0,1] neg_hi:[0,1]
	v_cmp_neq_f32_e32 vcc, s90, v69
	v_pk_add_f32 v[24:25], v[24:25], v[48:49]
	v_min_f32_e32 v17, 0, v17
	v_pk_add_f32 v[24:25], v[34:35], v[24:25]
	s_nop 0
	v_pk_add_f32 v[24:25], v[64:65], v[24:25]
	s_nop 0
	v_pk_mul_f32 v[24:25], v[32:33], v[24:25]
	s_nop 0
	v_pk_add_f32 v[24:25], v[46:47], v[24:25]
	s_nop 0
	v_pk_add_f32 v[32:33], v[62:63], v[24:25]
	s_nop 0
	v_pk_add_f32 v[34:35], v[32:33], v[62:63] neg_lo:[0,1] neg_hi:[0,1]
	v_pk_mul_f32 v[48:49], v[32:33], v[32:33]
	v_pk_add_f32 v[24:25], v[24:25], v[34:35] neg_lo:[0,1] neg_hi:[0,1]
	v_pk_fma_f32 v[34:35], v[48:49], s[44:45], v[18:19] op_sel_hi:[1,0,0]
	v_ldexp_f32 v46, v32, 1
	v_ldexp_f32 v47, v33, 1
	v_pk_mul_f32 v[32:33], v[32:33], v[48:49]
	v_pk_fma_f32 v[34:35], v[48:49], v[34:35], s[46:47] op_sel_hi:[1,1,0]
	v_ldexp_f32 v53, v25, 1
	v_pk_mul_f32 v[32:33], v[32:33], v[34:35]
	v_ldexp_f32 v24, v24, 1
	v_pk_add_f32 v[34:35], v[46:47], v[32:33]
	v_mov_b32_e32 v25, v53
	v_pk_add_f32 v[46:47], v[34:35], v[46:47] neg_lo:[0,1] neg_hi:[0,1]
	v_mov_b32_e32 v38, v34
	v_pk_add_f32 v[32:33], v[32:33], v[46:47] neg_lo:[0,1] neg_hi:[0,1]
	s_nop 0
	v_pk_add_f32 v[46:47], v[24:25], v[32:33]
	v_mov_b32_e32 v43, v33
	v_mov_b32_e32 v33, v35
	v_mov_b32_e32 v25, v47
	v_pk_add_f32 v[48:49], v[34:35], v[46:47]
	v_pk_add_f32 v[24:25], v[24:25], v[32:33]
	v_pk_add_f32 v[32:33], v[50:51], v[48:49]
	v_pk_add_f32 v[42:43], v[42:43], v[52:53]
	v_mov_b32_e32 v52, v48
	v_mov_b32_e32 v53, v33
	v_pk_add_f32 v[38:39], v[52:53], v[38:39] neg_lo:[0,1] neg_hi:[0,1]
	v_mov_b32_e32 v36, v32
	v_mov_b32_e32 v57, v33
	v_mov_b32_e32 v41, v39
	v_mov_b32_e32 v54, v48
	v_pk_add_f32 v[36:37], v[36:37], v[44:45] neg_lo:[0,1] neg_hi:[0,1]
	v_pk_add_f32 v[40:41], v[56:57], v[40:41] neg_lo:[0,1] neg_hi:[0,1]
	v_pk_add_f32 v[44:45], v[54:55], v[36:37] neg_lo:[0,1] neg_hi:[0,1]
	v_mov_b32_e32 v52, v40
	v_mov_b32_e32 v53, v37
	v_mov_b32_e32 v54, v32
	v_mov_b32_e32 v55, v49
	v_mov_b32_e32 v37, v35
	v_pk_add_f32 v[52:53], v[22:23], v[52:53] neg_lo:[0,1] neg_hi:[0,1]
	v_pk_add_f32 v[36:37], v[54:55], v[36:37] neg_lo:[0,1] neg_hi:[0,1]
	v_mov_b32_e32 v23, v51
	v_pk_add_f32 v[36:37], v[42:43], v[36:37] neg_lo:[0,1] neg_hi:[0,1]
	v_pk_add_f32 v[22:23], v[22:23], v[40:41] neg_lo:[0,1] neg_hi:[0,1]
	v_pk_add_f32 v[24:25], v[24:25], v[38:39] neg_lo:[0,1] neg_hi:[0,1]
	v_pk_add_f32 v[40:41], v[44:45], v[36:37]
	v_pk_add_f32 v[38:39], v[24:25], v[22:23]
	v_mov_b32_e32 v23, v45
	v_mov_b32_e32 v25, v37
	v_pk_add_f32 v[24:25], v[22:23], v[24:25]
	v_pk_add_f32 v[34:35], v[48:49], v[34:35] neg_lo:[0,1] neg_hi:[0,1]
	v_pk_add_f32 v[24:25], v[24:25], v[52:53] neg_lo:[0,1] neg_hi:[0,1]
	v_mov_b32_e32 v36, v38
	v_mov_b32_e32 v37, v41
	v_pk_add_f32 v[34:35], v[46:47], v[34:35] neg_lo:[0,1] neg_hi:[0,1]
	v_pk_add_f32 v[36:37], v[36:37], v[24:25] neg_lo:[0,1] neg_hi:[0,1]
	v_pk_add_f32 v[24:25], v[34:35], v[24:25] neg_lo:[0,1] neg_hi:[0,1]
	v_pk_add_f32 v[22:23], v[22:23], v[36:37] neg_lo:[0,1] neg_hi:[0,1]
	s_nop 0
	v_pk_add_f32 v[22:23], v[24:25], v[22:23]
	v_pk_add_f32 v[24:25], v[40:41], v[38:39]
	s_nop 0
	v_pk_add_f32 v[34:35], v[32:33], v[24:25]
	s_nop 0
	v_pk_add_f32 v[32:33], v[34:35], v[32:33] neg_lo:[0,1] neg_hi:[0,1]
	s_nop 0
	v_pk_add_f32 v[24:25], v[24:25], v[32:33] neg_lo:[0,1] neg_hi:[0,1]
	s_nop 0
	v_pk_add_f32 v[22:23], v[22:23], v[24:25]
	v_add_f32_e32 v24, v26, v21
	v_pk_add_f32 v[22:23], v[34:35], v[22:23]
	v_mul_f32_e64 v25, |v24|, s88
	v_cndmask_b32_e32 v22, v205, v22, vcc
	v_cmp_neq_f32_e32 vcc, s90, v70
	v_exp_f32_e32 v54, v25
	v_add_f32_e32 v21, v27, v21
	v_cndmask_b32_e32 v23, v205, v23, vcc
	v_cmp_ngt_f32_e32 vcc, -1.0, v70
	s_nop 1
	v_cndmask_b32_e32 v23, v206, v23, vcc
	v_cmp_ngt_f32_e32 vcc, -1.0, v69
	s_nop 1
	v_cndmask_b32_e32 v22, v206, v22, vcc
	v_cmp_neq_f32_e32 vcc, -1.0, v69
	s_nop 1
	v_cndmask_b32_e32 v22, v207, v22, vcc
	v_cmp_neq_f32_e32 vcc, -1.0, v70
	s_nop 1
	v_cndmask_b32_e32 v23, v207, v23, vcc
	v_cmp_lt_f32_e64 vcc, |v70|, s91
	s_nop 1
	v_cndmask_b32_e32 v23, v23, v70, vcc
	v_cmp_lt_f32_e64 vcc, |v69|, s91
	s_nop 1
	v_cndmask_b32_e32 v22, v22, v69, vcc
	v_pk_add_f32 v[16:17], v[16:17], v[22:23] neg_lo:[0,1] neg_hi:[0,1]
	v_add_f32_e32 v23, 1.0, v54
	v_min_f32_e32 v22, 0, v24
	v_add_f32_e32 v24, -1.0, v23
	v_sub_f32_e32 v25, v24, v23
	v_add_f32_e32 v25, 1.0, v25
	v_sub_f32_e32 v24, v54, v24
	v_add_f32_e32 v26, v24, v25
	v_frexp_mant_f32_e32 v32, v23
	v_cvt_f64_f32_e32 v[24:25], v23
	v_frexp_exp_i32_f64_e32 v24, v[24:25]
	v_cmp_gt_f32_e32 vcc, s89, v32
	s_nop 1
	v_subbrev_co_u32_e32 v48, vcc, 0, v24, vcc
	v_mul_f32_e64 v24, |v21|, s88
	v_exp_f32_e32 v55, v24
	v_sub_u32_e32 v25, 0, v48
	v_ldexp_f32 v24, v23, v25
	v_min_f32_e32 v23, 0, v21
	v_add_f32_e32 v21, 1.0, v55
	v_ldexp_f32 v26, v26, v25
	v_add_f32_e32 v25, -1.0, v21
	v_sub_f32_e32 v27, v25, v21
	v_add_f32_e32 v27, 1.0, v27
	v_sub_f32_e32 v25, v55, v25
	v_add_f32_e32 v27, v25, v27
	v_frexp_mant_f32_e32 v25, v21
	v_cvt_f64_f32_e32 v[32:33], v21
	v_frexp_exp_i32_f64_e32 v32, v[32:33]
	v_cmp_gt_f32_e32 vcc, s89, v25
	s_nop 1
	v_subbrev_co_u32_e32 v49, vcc, 0, v32, vcc
	v_sub_u32_e32 v32, 0, v49
	v_ldexp_f32 v25, v21, v32
	v_ldexp_f32 v27, v27, v32
	v_pk_add_f32 v[32:33], v[24:25], 1.0 op_sel_hi:[1,0]
	v_pk_add_f32 v[40:41], v[24:25], -1.0 op_sel_hi:[1,0]
	v_pk_add_f32 v[34:35], v[32:33], -1.0 op_sel_hi:[1,0]
	v_pk_add_f32 v[42:43], v[40:41], 1.0 op_sel_hi:[1,0]
	v_pk_add_f32 v[34:35], v[24:25], v[34:35] neg_lo:[0,1] neg_hi:[0,1]
	v_pk_add_f32 v[24:25], v[24:25], v[42:43] neg_lo:[0,1] neg_hi:[0,1]
	v_pk_add_f32 v[34:35], v[26:27], v[34:35]
	v_pk_add_f32 v[24:25], v[26:27], v[24:25]
	v_pk_add_f32 v[36:37], v[32:33], v[34:35]
	v_pk_add_f32 v[26:27], v[40:41], v[24:25]
	v_rcp_f32_e32 v38, v36
	v_rcp_f32_e32 v39, v37
	v_pk_add_f32 v[32:33], v[36:37], v[32:33] neg_lo:[0,1] neg_hi:[0,1]
	v_pk_add_f32 v[40:41], v[26:27], v[40:41] neg_lo:[0,1] neg_hi:[0,1]
	v_pk_add_f32 v[32:33], v[34:35], v[32:33] neg_lo:[0,1] neg_hi:[0,1]
	v_pk_mul_f32 v[34:35], v[26:27], v[38:39]
	v_pk_add_f32 v[24:25], v[24:25], v[40:41] neg_lo:[0,1] neg_hi:[0,1]
	v_pk_mul_f32 v[40:41], v[36:37], v[34:35]
	v_cmp_neq_f32_e32 vcc, s90, v54
	v_pk_fma_f32 v[42:43], v[34:35], v[36:37], v[40:41] neg_lo:[0,0,1] neg_hi:[0,0,1]
	v_ashrrev_i32_e32 v21, 31, v20
	v_pk_fma_f32 v[42:43], v[34:35], v[32:33], v[42:43]
	s_nop 0
	v_pk_add_f32 v[44:45], v[40:41], v[42:43]
	s_nop 0
	v_pk_add_f32 v[46:47], v[26:27], v[44:45] neg_lo:[0,1] neg_hi:[0,1]
	v_pk_add_f32 v[40:41], v[44:45], v[40:41] neg_lo:[0,1] neg_hi:[0,1]
	v_pk_add_f32 v[26:27], v[26:27], v[46:47] neg_lo:[0,1] neg_hi:[0,1]
	s_nop 0
	v_pk_add_f32 v[26:27], v[26:27], v[44:45] neg_lo:[0,1] neg_hi:[0,1]
	s_nop 0
	v_pk_add_f32 v[24:25], v[24:25], v[26:27]
	v_pk_add_f32 v[26:27], v[40:41], v[42:43] neg_lo:[0,1] neg_hi:[0,1]
	s_nop 0
	v_pk_add_f32 v[24:25], v[26:27], v[24:25]
	s_nop 0
	v_pk_add_f32 v[26:27], v[46:47], v[24:25]
	s_nop 0
	v_pk_mul_f32 v[40:41], v[38:39], v[26:27]
	s_nop 0
	v_pk_mul_f32 v[42:43], v[36:37], v[40:41]
	s_nop 0
	v_pk_fma_f32 v[36:37], v[40:41], v[36:37], v[42:43] neg_lo:[0,0,1] neg_hi:[0,0,1]
	s_nop 0
	v_pk_fma_f32 v[32:33], v[40:41], v[32:33], v[36:37]
	v_pk_add_f32 v[36:37], v[46:47], v[26:27] neg_lo:[0,1] neg_hi:[0,1]
	s_nop 0
	v_pk_add_f32 v[24:25], v[24:25], v[36:37]
	v_pk_add_f32 v[36:37], v[42:43], v[32:33]
	s_nop 0
	v_pk_add_f32 v[44:45], v[26:27], v[36:37] neg_lo:[0,1] neg_hi:[0,1]
	v_pk_add_f32 v[42:43], v[36:37], v[42:43] neg_lo:[0,1] neg_hi:[0,1]
	v_pk_add_f32 v[26:27], v[26:27], v[44:45] neg_lo:[0,1] neg_hi:[0,1]
	s_nop 0
	v_pk_add_f32 v[26:27], v[26:27], v[36:37] neg_lo:[0,1] neg_hi:[0,1]
	v_cvt_f32_i32_e32 v37, v49
	v_pk_add_f32 v[24:25], v[24:25], v[26:27]
	v_pk_add_f32 v[26:27], v[42:43], v[32:33] neg_lo:[0,1] neg_hi:[0,1]
	v_cvt_f32_i32_e32 v36, v48
	v_pk_add_f32 v[24:25], v[26:27], v[24:25]
	v_pk_add_f32 v[26:27], v[34:35], v[40:41]
	v_pk_add_f32 v[24:25], v[44:45], v[24:25]
	v_pk_add_f32 v[32:33], v[26:27], v[34:35] neg_lo:[0,1] neg_hi:[0,1]
	v_pk_mul_f32 v[24:25], v[38:39], v[24:25]
	v_pk_add_f32 v[32:33], v[40:41], v[32:33] neg_lo:[0,1] neg_hi:[0,1]
	s_nop 0
	v_pk_add_f32 v[24:25], v[32:33], v[24:25]
	s_nop 0
	v_pk_add_f32 v[32:33], v[26:27], v[24:25]
	s_nop 0
	v_pk_mul_f32 v[34:35], v[32:33], v[32:33]
	v_pk_add_f32 v[26:27], v[32:33], v[26:27] neg_lo:[0,1] neg_hi:[0,1]
	v_pk_fma_f32 v[18:19], v[34:35], s[44:45], v[18:19] op_sel_hi:[1,0,0]
	v_pk_add_f32 v[24:25], v[24:25], v[26:27] neg_lo:[0,1] neg_hi:[0,1]
	v_ldexp_f32 v26, v32, 1
	v_pk_fma_f32 v[18:19], v[34:35], v[18:19], s[46:47] op_sel_hi:[1,1,0]
	v_ldexp_f32 v27, v33, 1
	v_pk_mul_f32 v[32:33], v[32:33], v[34:35]
	v_pk_mul_f32 v[34:35], v[36:37], s[48:49] op_sel_hi:[1,0]
	v_pk_mul_f32 v[18:19], v[32:33], v[18:19]
	v_pk_fma_f32 v[40:41], v[36:37], s[48:49], v[34:35] op_sel_hi:[1,0,1] neg_lo:[0,0,1] neg_hi:[0,0,1]
	v_pk_add_f32 v[32:33], v[26:27], v[18:19]
	v_ldexp_f32 v39, v25, 1
	v_pk_add_f32 v[26:27], v[32:33], v[26:27] neg_lo:[0,1] neg_hi:[0,1]
	v_pk_fma_f32 v[36:37], v[36:37], s[50:51], v[40:41] op_sel_hi:[1,0,1]
	v_pk_add_f32 v[18:19], v[18:19], v[26:27] neg_lo:[0,1] neg_hi:[0,1]
	v_ldexp_f32 v24, v24, 1
	v_mov_b32_e32 v26, v34
	v_mov_b32_e32 v27, v19
	v_mov_b32_e32 v38, v36
	v_mov_b32_e32 v25, v39
	v_pk_add_f32 v[26:27], v[26:27], v[38:39]
	v_pk_add_f32 v[38:39], v[24:25], v[18:19]
	v_mov_b32_e32 v19, v33
	v_mov_b32_e32 v25, v39
	v_pk_add_f32 v[40:41], v[34:35], v[36:37]
	v_pk_add_f32 v[18:19], v[24:25], v[18:19]
	v_pk_add_f32 v[24:25], v[32:33], v[38:39]
	v_mov_b32_e32 v50, v32
	v_pk_add_f32 v[42:43], v[40:41], v[24:25]
	v_mov_b32_e32 v48, v24
	v_mov_b32_e32 v49, v43
	v_mov_b32_e32 v51, v41
	v_pk_add_f32 v[48:49], v[48:49], v[50:51] neg_lo:[0,1] neg_hi:[0,1]
	v_mov_b32_e32 v44, v42
	v_mov_b32_e32 v45, v41
	v_mov_b32_e32 v46, v40
	v_mov_b32_e32 v47, v35
	v_mov_b32_e32 v50, v40
	v_mov_b32_e32 v51, v43
	v_mov_b32_e32 v35, v49
	v_pk_add_f32 v[44:45], v[44:45], v[46:47] neg_lo:[0,1] neg_hi:[0,1]
	v_mov_b32_e32 v46, v24
	v_mov_b32_e32 v47, v37
	v_pk_add_f32 v[34:35], v[50:51], v[34:35] neg_lo:[0,1] neg_hi:[0,1]
	v_pk_add_f32 v[46:47], v[46:47], v[44:45] neg_lo:[0,1] neg_hi:[0,1]
	v_mov_b32_e32 v50, v34
	v_mov_b32_e32 v51, v45
	v_mov_b32_e32 v52, v42
	v_mov_b32_e32 v53, v25
	v_mov_b32_e32 v45, v33
	v_pk_add_f32 v[50:51], v[36:37], v[50:51] neg_lo:[0,1] neg_hi:[0,1]
	v_pk_add_f32 v[44:45], v[52:53], v[44:45] neg_lo:[0,1] neg_hi:[0,1]
	v_mov_b32_e32 v37, v41
	v_pk_add_f32 v[24:25], v[24:25], v[32:33] neg_lo:[0,1] neg_hi:[0,1]
	v_pk_add_f32 v[26:27], v[26:27], v[44:45] neg_lo:[0,1] neg_hi:[0,1]
	v_pk_add_f32 v[32:33], v[36:37], v[34:35] neg_lo:[0,1] neg_hi:[0,1]
	v_pk_add_f32 v[18:19], v[18:19], v[48:49] neg_lo:[0,1] neg_hi:[0,1]
	v_pk_add_f32 v[36:37], v[46:47], v[26:27]
	v_pk_add_f32 v[34:35], v[18:19], v[32:33]
	v_mov_b32_e32 v33, v47
	v_mov_b32_e32 v19, v27
	v_pk_add_f32 v[18:19], v[32:33], v[18:19]
	v_mov_b32_e32 v26, v34
	v_pk_add_f32 v[18:19], v[18:19], v[50:51] neg_lo:[0,1] neg_hi:[0,1]
	v_mov_b32_e32 v27, v37
	v_pk_add_f32 v[24:25], v[38:39], v[24:25] neg_lo:[0,1] neg_hi:[0,1]
	v_pk_add_f32 v[26:27], v[26:27], v[18:19] neg_lo:[0,1] neg_hi:[0,1]
	v_pk_add_f32 v[18:19], v[24:25], v[18:19] neg_lo:[0,1] neg_hi:[0,1]
	v_pk_add_f32 v[26:27], v[32:33], v[26:27] neg_lo:[0,1] neg_hi:[0,1]
	v_pk_add_f32 v[24:25], v[36:37], v[34:35]
	v_pk_add_f32 v[18:19], v[18:19], v[26:27]
	v_pk_add_f32 v[26:27], v[42:43], v[24:25]
	s_nop 0
	v_pk_add_f32 v[32:33], v[26:27], v[42:43] neg_lo:[0,1] neg_hi:[0,1]
	s_nop 0
	v_pk_add_f32 v[24:25], v[24:25], v[32:33] neg_lo:[0,1] neg_hi:[0,1]
	s_nop 0
	v_pk_add_f32 v[18:19], v[18:19], v[24:25]
	s_nop 0
	v_pk_add_f32 v[18:19], v[26:27], v[18:19]
	s_nop 0
	v_cndmask_b32_e32 v18, v205, v18, vcc
	v_cmp_neq_f32_e32 vcc, s90, v55
	s_nop 1
	v_cndmask_b32_e32 v19, v205, v19, vcc
	v_cmp_ngt_f32_e32 vcc, -1.0, v55
	s_nop 1
	v_cndmask_b32_e32 v19, v206, v19, vcc
	v_cmp_ngt_f32_e32 vcc, -1.0, v54
	s_nop 1
	v_cndmask_b32_e32 v18, v206, v18, vcc
	v_cmp_neq_f32_e32 vcc, -1.0, v54
	s_nop 1
	v_cndmask_b32_e32 v18, v207, v18, vcc
	v_cmp_neq_f32_e32 vcc, -1.0, v55
	s_nop 1
	v_cndmask_b32_e32 v19, v207, v19, vcc
	v_cmp_lt_f32_e64 vcc, |v55|, s91
	s_nop 1
	v_cndmask_b32_e32 v19, v19, v55, vcc
	v_cmp_lt_f32_e64 vcc, |v54|, s91
	s_nop 1
	v_cndmask_b32_e32 v18, v18, v54, vcc
	v_pk_add_f32 v[18:19], v[22:23], v[18:19] neg_lo:[0,1] neg_hi:[0,1]
	v_lshlrev_b64 v[22:23], s53, v[20:21]
	v_lshl_add_u64 v[22:23], v[22:23], 2, s[78:79]
	v_lshl_add_u64 v[22:23], v[22:23], 0, v[152:153]
	s_and_b64 vcc, exec, s[6:7]
	v_mov_b32_e32 v21, s54
	global_store_dwordx4 v[22:23], v[16:19], off nt
	s_cbranch_vccnz .LBB0_246
	v_readlane_b32 s62, v250, 0
	v_readlane_b32 s63, v250, 1
	s_nop 1
	v_mov_b64_e32 v[22:23], s[62:63]
	v_mad_i64_i32 v[20:21], s[62:63], v20, s92, v[22:23]
	v_lshl_add_u64 v[20:21], v[20:21], 0, v[152:153]
	v_add_co_u32_e32 v20, vcc, 0x10c06000, v20
	s_nop 1
	v_addc_co_u32_e32 v21, vcc, 0, v21, vcc
	global_store_dwordx4 v[20:21], v[16:19], off offset:256 nt
	v_mov_b32_e32 v21, v187
.LBB0_246:
	global_load_dword v20, v[158:159], off
	v_or_b32_e32 v16, s55, v188
	v_cndmask_b32_e64 v64, v16, v189, s[4:5]
	v_mov_b64_e32 v[18:19], s[42:43]
	v_lshlrev_b32_e32 v152, 2, v64
	s_waitcnt vmcnt(0)
	v_add_f32_e32 v16, v28, v20
	v_mul_f32_e64 v22, |v16|, s88
	v_add_f32_e32 v17, v29, v20
	v_exp_f32_e32 v65, v22
	v_mul_f32_e64 v23, |v17|, s88
	v_exp_f32_e32 v66, v23
	v_min_f32_e32 v16, 0, v16
	v_add_f32_e32 v26, 1.0, v65
	v_frexp_mant_f32_e32 v29, v26
	v_cvt_f64_f32_e32 v[22:23], v26
	v_add_f32_e32 v27, 1.0, v66
	v_frexp_exp_i32_f64_e32 v22, v[22:23]
	v_cmp_gt_f32_e32 vcc, s89, v29
	v_add_f32_e32 v28, -1.0, v26
	v_add_f32_e32 v32, -1.0, v27
	v_frexp_mant_f32_e32 v33, v27
	v_cvt_f64_f32_e32 v[24:25], v27
	v_subbrev_co_u32_e32 v22, vcc, 0, v22, vcc
	v_sub_f32_e32 v34, v28, v26
	v_sub_f32_e32 v23, v32, v27
	v_frexp_exp_i32_f64_e32 v24, v[24:25]
	v_cmp_gt_f32_e32 vcc, s89, v33
	v_sub_f32_e32 v28, v65, v28
	v_sub_f32_e32 v32, v66, v32
	v_add_f32_e32 v25, 1.0, v34
	v_add_f32_e32 v23, 1.0, v23
	v_subbrev_co_u32_e32 v24, vcc, 0, v24, vcc
	v_add_f32_e32 v25, v28, v25
	v_sub_u32_e32 v28, 0, v22
	v_add_f32_e32 v29, v32, v23
	v_sub_u32_e32 v32, 0, v24
	v_cvt_f32_i32_e32 v23, v24
	v_cvt_f32_i32_e32 v22, v22
	v_ldexp_f32 v24, v26, v28
	v_ldexp_f32 v26, v25, v28
	v_ldexp_f32 v25, v27, v32
	v_ldexp_f32 v27, v29, v32
	v_pk_add_f32 v[28:29], v[24:25], 1.0 op_sel_hi:[1,0]
	v_pk_add_f32 v[32:33], v[24:25], -1.0 op_sel_hi:[1,0]
	v_pk_add_f32 v[34:35], v[28:29], -1.0 op_sel_hi:[1,0]
	v_pk_add_f32 v[36:37], v[32:33], 1.0 op_sel_hi:[1,0]
	v_pk_add_f32 v[34:35], v[24:25], v[34:35] neg_lo:[0,1] neg_hi:[0,1]
	v_pk_add_f32 v[24:25], v[24:25], v[36:37] neg_lo:[0,1] neg_hi:[0,1]
	v_pk_mul_f32 v[36:37], v[22:23], s[48:49] op_sel_hi:[1,0]
	v_pk_add_f32 v[34:35], v[26:27], v[34:35]
	v_pk_add_f32 v[24:25], v[26:27], v[24:25]
	v_pk_fma_f32 v[26:27], v[22:23], s[48:49], v[36:37] op_sel_hi:[1,0,1] neg_lo:[0,0,1] neg_hi:[0,0,1]
	v_pk_add_f32 v[42:43], v[28:29], v[34:35]
	v_pk_fma_f32 v[22:23], v[22:23], s[50:51], v[26:27] op_sel_hi:[1,0,1]
	v_rcp_f32_e32 v26, v42
	v_rcp_f32_e32 v27, v43
	v_pk_add_f32 v[44:45], v[32:33], v[24:25]
	v_pk_add_f32 v[28:29], v[42:43], v[28:29] neg_lo:[0,1] neg_hi:[0,1]
	v_pk_add_f32 v[32:33], v[44:45], v[32:33] neg_lo:[0,1] neg_hi:[0,1]
	v_pk_mul_f32 v[54:55], v[44:45], v[26:27]
	v_pk_add_f32 v[28:29], v[34:35], v[28:29] neg_lo:[0,1] neg_hi:[0,1]
	v_pk_mul_f32 v[56:57], v[42:43], v[54:55]
	v_pk_add_f32 v[24:25], v[24:25], v[32:33] neg_lo:[0,1] neg_hi:[0,1]
	v_pk_fma_f32 v[58:59], v[54:55], v[42:43], v[56:57] neg_lo:[0,0,1] neg_hi:[0,0,1]
	v_pk_add_f32 v[46:47], v[36:37], v[22:23]
	v_pk_fma_f32 v[58:59], v[54:55], v[28:29], v[58:59]
	v_mov_b32_e32 v38, v36
	v_pk_add_f32 v[60:61], v[56:57], v[58:59]
	v_mov_b32_e32 v48, v22
	v_pk_add_f32 v[62:63], v[44:45], v[60:61] neg_lo:[0,1] neg_hi:[0,1]
	v_pk_add_f32 v[56:57], v[60:61], v[56:57] neg_lo:[0,1] neg_hi:[0,1]
	v_pk_add_f32 v[44:45], v[44:45], v[62:63] neg_lo:[0,1] neg_hi:[0,1]
	v_pk_add_f32 v[56:57], v[56:57], v[58:59] neg_lo:[0,1] neg_hi:[0,1]
	v_pk_add_f32 v[44:45], v[44:45], v[60:61] neg_lo:[0,1] neg_hi:[0,1]
	v_mov_b32_e32 v35, v47
	v_pk_add_f32 v[24:25], v[24:25], v[44:45]
	v_mov_b32_e32 v41, v37
	v_pk_add_f32 v[24:25], v[56:57], v[24:25]
	v_mov_b32_e32 v33, v47
	v_pk_add_f32 v[44:45], v[62:63], v[24:25]
	v_mov_b32_e32 v40, v46
	v_pk_mul_f32 v[56:57], v[26:27], v[44:45]
	v_pk_add_f32 v[58:59], v[62:63], v[44:45] neg_lo:[0,1] neg_hi:[0,1]
	v_pk_mul_f32 v[60:61], v[42:43], v[56:57]
	v_pk_add_f32 v[24:25], v[24:25], v[58:59]
	v_pk_add_f32 v[58:59], v[54:55], v[56:57]
	v_pk_fma_f32 v[42:43], v[56:57], v[42:43], v[60:61] neg_lo:[0,0,1] neg_hi:[0,0,1]
	v_pk_add_f32 v[54:55], v[58:59], v[54:55] neg_lo:[0,1] neg_hi:[0,1]
	v_pk_fma_f32 v[28:29], v[56:57], v[28:29], v[42:43]
	v_pk_add_f32 v[42:43], v[56:57], v[54:55] neg_lo:[0,1] neg_hi:[0,1]
	v_pk_add_f32 v[54:55], v[60:61], v[28:29]
	v_mov_b32_e32 v52, v46
	v_pk_add_f32 v[56:57], v[54:55], v[60:61] neg_lo:[0,1] neg_hi:[0,1]
	v_pk_add_f32 v[60:61], v[44:45], v[54:55] neg_lo:[0,1] neg_hi:[0,1]
	v_pk_add_f32 v[28:29], v[56:57], v[28:29] neg_lo:[0,1] neg_hi:[0,1]
	v_pk_add_f32 v[44:45], v[44:45], v[60:61] neg_lo:[0,1] neg_hi:[0,1]
	v_mov_b32_e32 v51, v23
	v_pk_add_f32 v[44:45], v[44:45], v[54:55] neg_lo:[0,1] neg_hi:[0,1]
	v_cmp_neq_f32_e32 vcc, s90, v65
	v_pk_add_f32 v[24:25], v[24:25], v[44:45]
	v_min_f32_e32 v17, 0, v17
	v_pk_add_f32 v[24:25], v[28:29], v[24:25]
	s_nop 0
	v_pk_add_f32 v[24:25], v[60:61], v[24:25]
	s_nop 0
	v_pk_mul_f32 v[24:25], v[26:27], v[24:25]
	s_nop 0
	v_pk_add_f32 v[24:25], v[42:43], v[24:25]
	s_nop 0
	v_pk_add_f32 v[26:27], v[58:59], v[24:25]
	s_nop 0
	v_pk_add_f32 v[28:29], v[26:27], v[58:59] neg_lo:[0,1] neg_hi:[0,1]
	v_pk_mul_f32 v[44:45], v[26:27], v[26:27]
	v_pk_add_f32 v[24:25], v[24:25], v[28:29] neg_lo:[0,1] neg_hi:[0,1]
	v_pk_fma_f32 v[28:29], v[44:45], s[44:45], v[18:19] op_sel_hi:[1,0,0]
	v_ldexp_f32 v42, v26, 1
	v_ldexp_f32 v43, v27, 1
	v_pk_mul_f32 v[26:27], v[26:27], v[44:45]
	v_pk_fma_f32 v[28:29], v[44:45], v[28:29], s[46:47] op_sel_hi:[1,1,0]
	v_ldexp_f32 v49, v25, 1
	v_pk_mul_f32 v[26:27], v[26:27], v[28:29]
	v_ldexp_f32 v24, v24, 1
	v_pk_add_f32 v[28:29], v[42:43], v[26:27]
	v_mov_b32_e32 v25, v49
	v_pk_add_f32 v[42:43], v[28:29], v[42:43] neg_lo:[0,1] neg_hi:[0,1]
	v_mov_b32_e32 v34, v28
	v_pk_add_f32 v[26:27], v[26:27], v[42:43] neg_lo:[0,1] neg_hi:[0,1]
	s_nop 0
	v_pk_add_f32 v[42:43], v[24:25], v[26:27]
	v_mov_b32_e32 v39, v27
	v_mov_b32_e32 v27, v29
	v_mov_b32_e32 v25, v43
	v_pk_add_f32 v[44:45], v[28:29], v[42:43]
	v_pk_add_f32 v[24:25], v[24:25], v[26:27]
	v_pk_add_f32 v[26:27], v[46:47], v[44:45]
	v_pk_add_f32 v[38:39], v[38:39], v[48:49]
	v_mov_b32_e32 v48, v44
	v_mov_b32_e32 v49, v27
	v_pk_add_f32 v[34:35], v[48:49], v[34:35] neg_lo:[0,1] neg_hi:[0,1]
	v_mov_b32_e32 v32, v26
	v_mov_b32_e32 v53, v27
	v_mov_b32_e32 v37, v35
	v_mov_b32_e32 v50, v44
	v_pk_add_f32 v[32:33], v[32:33], v[40:41] neg_lo:[0,1] neg_hi:[0,1]
	v_pk_add_f32 v[36:37], v[52:53], v[36:37] neg_lo:[0,1] neg_hi:[0,1]
	v_pk_add_f32 v[40:41], v[50:51], v[32:33] neg_lo:[0,1] neg_hi:[0,1]
	v_mov_b32_e32 v48, v36
	v_mov_b32_e32 v49, v33
	v_mov_b32_e32 v50, v26
	v_mov_b32_e32 v51, v45
	v_mov_b32_e32 v33, v29
	v_pk_add_f32 v[48:49], v[22:23], v[48:49] neg_lo:[0,1] neg_hi:[0,1]
	v_pk_add_f32 v[32:33], v[50:51], v[32:33] neg_lo:[0,1] neg_hi:[0,1]
	v_mov_b32_e32 v23, v47
	v_pk_add_f32 v[32:33], v[38:39], v[32:33] neg_lo:[0,1] neg_hi:[0,1]
	v_pk_add_f32 v[22:23], v[22:23], v[36:37] neg_lo:[0,1] neg_hi:[0,1]
	v_pk_add_f32 v[24:25], v[24:25], v[34:35] neg_lo:[0,1] neg_hi:[0,1]
	v_pk_add_f32 v[36:37], v[40:41], v[32:33]
	v_pk_add_f32 v[34:35], v[24:25], v[22:23]
	v_mov_b32_e32 v23, v41
	v_mov_b32_e32 v25, v33
	v_pk_add_f32 v[24:25], v[22:23], v[24:25]
	v_pk_add_f32 v[28:29], v[44:45], v[28:29] neg_lo:[0,1] neg_hi:[0,1]
	v_pk_add_f32 v[24:25], v[24:25], v[48:49] neg_lo:[0,1] neg_hi:[0,1]
	v_mov_b32_e32 v32, v34
	v_mov_b32_e32 v33, v37
	v_pk_add_f32 v[28:29], v[42:43], v[28:29] neg_lo:[0,1] neg_hi:[0,1]
	v_pk_add_f32 v[32:33], v[32:33], v[24:25] neg_lo:[0,1] neg_hi:[0,1]
	v_pk_add_f32 v[24:25], v[28:29], v[24:25] neg_lo:[0,1] neg_hi:[0,1]
	v_pk_add_f32 v[22:23], v[22:23], v[32:33] neg_lo:[0,1] neg_hi:[0,1]
	s_nop 0
	v_pk_add_f32 v[22:23], v[24:25], v[22:23]
	v_pk_add_f32 v[24:25], v[36:37], v[34:35]
	s_nop 0
	v_pk_add_f32 v[28:29], v[26:27], v[24:25]
	s_nop 0
	v_pk_add_f32 v[26:27], v[28:29], v[26:27] neg_lo:[0,1] neg_hi:[0,1]
	s_nop 0
	v_pk_add_f32 v[24:25], v[24:25], v[26:27] neg_lo:[0,1] neg_hi:[0,1]
	s_nop 0
	v_pk_add_f32 v[22:23], v[22:23], v[24:25]
	v_add_f32_e32 v24, v30, v20
	v_pk_add_f32 v[22:23], v[28:29], v[22:23]
	v_mul_f32_e64 v25, |v24|, s88
	v_cndmask_b32_e32 v22, v205, v22, vcc
	v_cmp_neq_f32_e32 vcc, s90, v66
	v_exp_f32_e32 v50, v25
	v_add_f32_e32 v20, v31, v20
	v_cndmask_b32_e32 v23, v205, v23, vcc
	v_cmp_ngt_f32_e32 vcc, -1.0, v66
	s_nop 1
	v_cndmask_b32_e32 v23, v206, v23, vcc
	v_cmp_ngt_f32_e32 vcc, -1.0, v65
	s_nop 1
	v_cndmask_b32_e32 v22, v206, v22, vcc
	v_cmp_neq_f32_e32 vcc, -1.0, v65
	s_nop 1
	v_cndmask_b32_e32 v22, v207, v22, vcc
	v_cmp_neq_f32_e32 vcc, -1.0, v66
	s_nop 1
	v_cndmask_b32_e32 v23, v207, v23, vcc
	v_cmp_lt_f32_e64 vcc, |v66|, s91
	s_nop 1
	v_cndmask_b32_e32 v23, v23, v66, vcc
	v_cmp_lt_f32_e64 vcc, |v65|, s91
	s_nop 1
	v_cndmask_b32_e32 v22, v22, v65, vcc
	v_pk_add_f32 v[16:17], v[16:17], v[22:23] neg_lo:[0,1] neg_hi:[0,1]
	v_add_f32_e32 v23, 1.0, v50
	v_min_f32_e32 v22, 0, v24
	v_add_f32_e32 v24, -1.0, v23
	v_sub_f32_e32 v25, v24, v23
	v_add_f32_e32 v25, 1.0, v25
	v_sub_f32_e32 v24, v50, v24
	v_add_f32_e32 v26, v24, v25
	v_frexp_mant_f32_e32 v27, v23
	v_cvt_f64_f32_e32 v[24:25], v23
	v_frexp_exp_i32_f64_e32 v24, v[24:25]
	v_cmp_gt_f32_e32 vcc, s89, v27
	s_nop 1
	v_subbrev_co_u32_e32 v44, vcc, 0, v24, vcc
	v_mul_f32_e64 v24, |v20|, s88
	v_exp_f32_e32 v51, v24
	v_sub_u32_e32 v25, 0, v44
	v_ldexp_f32 v24, v23, v25
	v_min_f32_e32 v23, 0, v20
	v_add_f32_e32 v20, 1.0, v51
	v_ldexp_f32 v26, v26, v25
	v_add_f32_e32 v25, -1.0, v20
	v_sub_f32_e32 v27, v25, v20
	v_add_f32_e32 v27, 1.0, v27
	v_sub_f32_e32 v25, v51, v25
	v_add_f32_e32 v27, v25, v27
	v_frexp_mant_f32_e32 v25, v20
	v_cvt_f64_f32_e32 v[28:29], v20
	v_frexp_exp_i32_f64_e32 v28, v[28:29]
	v_cmp_gt_f32_e32 vcc, s89, v25
	s_nop 1
	v_subbrev_co_u32_e32 v45, vcc, 0, v28, vcc
	v_sub_u32_e32 v28, 0, v45
	v_ldexp_f32 v25, v20, v28
	v_ldexp_f32 v27, v27, v28
	v_pk_add_f32 v[28:29], v[24:25], 1.0 op_sel_hi:[1,0]
	v_pk_add_f32 v[36:37], v[24:25], -1.0 op_sel_hi:[1,0]
	v_pk_add_f32 v[30:31], v[28:29], -1.0 op_sel_hi:[1,0]
	v_pk_add_f32 v[38:39], v[36:37], 1.0 op_sel_hi:[1,0]
	v_pk_add_f32 v[30:31], v[24:25], v[30:31] neg_lo:[0,1] neg_hi:[0,1]
	v_pk_add_f32 v[24:25], v[24:25], v[38:39] neg_lo:[0,1] neg_hi:[0,1]
	v_pk_add_f32 v[30:31], v[26:27], v[30:31]
	v_pk_add_f32 v[24:25], v[26:27], v[24:25]
	v_pk_add_f32 v[32:33], v[28:29], v[30:31]
	v_pk_add_f32 v[26:27], v[36:37], v[24:25]
	v_rcp_f32_e32 v34, v32
	v_rcp_f32_e32 v35, v33
	v_pk_add_f32 v[28:29], v[32:33], v[28:29] neg_lo:[0,1] neg_hi:[0,1]
	v_pk_add_f32 v[36:37], v[26:27], v[36:37] neg_lo:[0,1] neg_hi:[0,1]
	v_pk_add_f32 v[28:29], v[30:31], v[28:29] neg_lo:[0,1] neg_hi:[0,1]
	v_pk_mul_f32 v[30:31], v[26:27], v[34:35]
	v_pk_add_f32 v[24:25], v[24:25], v[36:37] neg_lo:[0,1] neg_hi:[0,1]
	v_pk_mul_f32 v[36:37], v[32:33], v[30:31]
	v_cmp_neq_f32_e32 vcc, s90, v50
	v_pk_fma_f32 v[38:39], v[30:31], v[32:33], v[36:37] neg_lo:[0,0,1] neg_hi:[0,0,1]
	v_lshl_or_b32 v20, v21, 3, v161
	v_pk_fma_f32 v[38:39], v[30:31], v[28:29], v[38:39]
	v_ashrrev_i32_e32 v21, 31, v20
	v_pk_add_f32 v[40:41], v[36:37], v[38:39]
	s_nop 0
	v_pk_add_f32 v[42:43], v[26:27], v[40:41] neg_lo:[0,1] neg_hi:[0,1]
	v_pk_add_f32 v[36:37], v[40:41], v[36:37] neg_lo:[0,1] neg_hi:[0,1]
	v_pk_add_f32 v[26:27], v[26:27], v[42:43] neg_lo:[0,1] neg_hi:[0,1]
	s_nop 0
	v_pk_add_f32 v[26:27], v[26:27], v[40:41] neg_lo:[0,1] neg_hi:[0,1]
	s_nop 0
	v_pk_add_f32 v[24:25], v[24:25], v[26:27]
	v_pk_add_f32 v[26:27], v[36:37], v[38:39] neg_lo:[0,1] neg_hi:[0,1]
	s_nop 0
	v_pk_add_f32 v[24:25], v[26:27], v[24:25]
	s_nop 0
	v_pk_add_f32 v[26:27], v[42:43], v[24:25]
	s_nop 0
	v_pk_mul_f32 v[36:37], v[34:35], v[26:27]
	s_nop 0
	v_pk_mul_f32 v[38:39], v[32:33], v[36:37]
	s_nop 0
	v_pk_fma_f32 v[32:33], v[36:37], v[32:33], v[38:39] neg_lo:[0,0,1] neg_hi:[0,0,1]
	s_nop 0
	v_pk_fma_f32 v[28:29], v[36:37], v[28:29], v[32:33]
	v_pk_add_f32 v[32:33], v[42:43], v[26:27] neg_lo:[0,1] neg_hi:[0,1]
	s_nop 0
	v_pk_add_f32 v[24:25], v[24:25], v[32:33]
	v_pk_add_f32 v[32:33], v[38:39], v[28:29]
	s_nop 0
	v_pk_add_f32 v[40:41], v[26:27], v[32:33] neg_lo:[0,1] neg_hi:[0,1]
	v_pk_add_f32 v[38:39], v[32:33], v[38:39] neg_lo:[0,1] neg_hi:[0,1]
	v_pk_add_f32 v[26:27], v[26:27], v[40:41] neg_lo:[0,1] neg_hi:[0,1]
	s_nop 0
	v_pk_add_f32 v[26:27], v[26:27], v[32:33] neg_lo:[0,1] neg_hi:[0,1]
	v_cvt_f32_i32_e32 v33, v45
	v_pk_add_f32 v[24:25], v[24:25], v[26:27]
	v_pk_add_f32 v[26:27], v[38:39], v[28:29] neg_lo:[0,1] neg_hi:[0,1]
	v_cvt_f32_i32_e32 v32, v44
	v_pk_add_f32 v[24:25], v[26:27], v[24:25]
	v_pk_add_f32 v[26:27], v[30:31], v[36:37]
	v_pk_add_f32 v[24:25], v[40:41], v[24:25]
	v_pk_add_f32 v[28:29], v[26:27], v[30:31] neg_lo:[0,1] neg_hi:[0,1]
	v_pk_mul_f32 v[24:25], v[34:35], v[24:25]
	v_pk_add_f32 v[28:29], v[36:37], v[28:29] neg_lo:[0,1] neg_hi:[0,1]
	s_nop 0
	v_pk_add_f32 v[24:25], v[28:29], v[24:25]
	s_nop 0
	v_pk_add_f32 v[28:29], v[26:27], v[24:25]
	s_nop 0
	v_pk_mul_f32 v[30:31], v[28:29], v[28:29]
	v_pk_add_f32 v[26:27], v[28:29], v[26:27] neg_lo:[0,1] neg_hi:[0,1]
	v_pk_fma_f32 v[18:19], v[30:31], s[44:45], v[18:19] op_sel_hi:[1,0,0]
	v_pk_add_f32 v[24:25], v[24:25], v[26:27] neg_lo:[0,1] neg_hi:[0,1]
	v_ldexp_f32 v26, v28, 1
	v_pk_fma_f32 v[18:19], v[30:31], v[18:19], s[46:47] op_sel_hi:[1,1,0]
	v_ldexp_f32 v27, v29, 1
	v_pk_mul_f32 v[28:29], v[28:29], v[30:31]
	v_pk_mul_f32 v[30:31], v[32:33], s[48:49] op_sel_hi:[1,0]
	v_pk_mul_f32 v[18:19], v[28:29], v[18:19]
	v_pk_fma_f32 v[36:37], v[32:33], s[48:49], v[30:31] op_sel_hi:[1,0,1] neg_lo:[0,0,1] neg_hi:[0,0,1]
	v_pk_add_f32 v[28:29], v[26:27], v[18:19]
	v_ldexp_f32 v35, v25, 1
	v_pk_add_f32 v[26:27], v[28:29], v[26:27] neg_lo:[0,1] neg_hi:[0,1]
	v_pk_fma_f32 v[32:33], v[32:33], s[50:51], v[36:37] op_sel_hi:[1,0,1]
	v_pk_add_f32 v[18:19], v[18:19], v[26:27] neg_lo:[0,1] neg_hi:[0,1]
	v_ldexp_f32 v24, v24, 1
	v_mov_b32_e32 v26, v30
	v_mov_b32_e32 v27, v19
	v_mov_b32_e32 v34, v32
	v_mov_b32_e32 v25, v35
	v_pk_add_f32 v[26:27], v[26:27], v[34:35]
	v_pk_add_f32 v[34:35], v[24:25], v[18:19]
	v_mov_b32_e32 v19, v29
	v_mov_b32_e32 v25, v35
	v_pk_add_f32 v[36:37], v[30:31], v[32:33]
	v_pk_add_f32 v[18:19], v[24:25], v[18:19]
	v_pk_add_f32 v[24:25], v[28:29], v[34:35]
	v_mov_b32_e32 v46, v28
	v_pk_add_f32 v[38:39], v[36:37], v[24:25]
	v_mov_b32_e32 v44, v24
	v_mov_b32_e32 v45, v39
	v_mov_b32_e32 v47, v37
	v_pk_add_f32 v[44:45], v[44:45], v[46:47] neg_lo:[0,1] neg_hi:[0,1]
	v_mov_b32_e32 v40, v38
	v_mov_b32_e32 v41, v37
	v_mov_b32_e32 v42, v36
	v_mov_b32_e32 v43, v31
	v_mov_b32_e32 v46, v36
	v_mov_b32_e32 v47, v39
	v_mov_b32_e32 v31, v45
	v_pk_add_f32 v[40:41], v[40:41], v[42:43] neg_lo:[0,1] neg_hi:[0,1]
	v_mov_b32_e32 v42, v24
	v_mov_b32_e32 v43, v33
	v_pk_add_f32 v[30:31], v[46:47], v[30:31] neg_lo:[0,1] neg_hi:[0,1]
	v_pk_add_f32 v[42:43], v[42:43], v[40:41] neg_lo:[0,1] neg_hi:[0,1]
	v_mov_b32_e32 v46, v30
	v_mov_b32_e32 v47, v41
	v_mov_b32_e32 v48, v38
	v_mov_b32_e32 v49, v25
	v_mov_b32_e32 v41, v29
	v_pk_add_f32 v[46:47], v[32:33], v[46:47] neg_lo:[0,1] neg_hi:[0,1]
	v_pk_add_f32 v[40:41], v[48:49], v[40:41] neg_lo:[0,1] neg_hi:[0,1]
	v_mov_b32_e32 v33, v37
	v_pk_add_f32 v[24:25], v[24:25], v[28:29] neg_lo:[0,1] neg_hi:[0,1]
	v_pk_add_f32 v[26:27], v[26:27], v[40:41] neg_lo:[0,1] neg_hi:[0,1]
	v_pk_add_f32 v[28:29], v[32:33], v[30:31] neg_lo:[0,1] neg_hi:[0,1]
	v_pk_add_f32 v[18:19], v[18:19], v[44:45] neg_lo:[0,1] neg_hi:[0,1]
	v_pk_add_f32 v[32:33], v[42:43], v[26:27]
	v_pk_add_f32 v[30:31], v[18:19], v[28:29]
	v_mov_b32_e32 v29, v43
	v_mov_b32_e32 v19, v27
	v_pk_add_f32 v[18:19], v[28:29], v[18:19]
	v_mov_b32_e32 v26, v30
	v_pk_add_f32 v[18:19], v[18:19], v[46:47] neg_lo:[0,1] neg_hi:[0,1]
	v_mov_b32_e32 v27, v33
	v_pk_add_f32 v[24:25], v[34:35], v[24:25] neg_lo:[0,1] neg_hi:[0,1]
	v_pk_add_f32 v[26:27], v[26:27], v[18:19] neg_lo:[0,1] neg_hi:[0,1]
	v_pk_add_f32 v[18:19], v[24:25], v[18:19] neg_lo:[0,1] neg_hi:[0,1]
	v_pk_add_f32 v[26:27], v[28:29], v[26:27] neg_lo:[0,1] neg_hi:[0,1]
	v_pk_add_f32 v[24:25], v[32:33], v[30:31]
	v_pk_add_f32 v[18:19], v[18:19], v[26:27]
	v_pk_add_f32 v[26:27], v[38:39], v[24:25]
	s_nop 0
	v_pk_add_f32 v[28:29], v[26:27], v[38:39] neg_lo:[0,1] neg_hi:[0,1]
	s_nop 0
	v_pk_add_f32 v[24:25], v[24:25], v[28:29] neg_lo:[0,1] neg_hi:[0,1]
	s_nop 0
	v_pk_add_f32 v[18:19], v[18:19], v[24:25]
	s_nop 0
	v_pk_add_f32 v[18:19], v[26:27], v[18:19]
	s_nop 0
	v_cndmask_b32_e32 v18, v205, v18, vcc
	v_cmp_neq_f32_e32 vcc, s90, v51
	s_nop 1
	v_cndmask_b32_e32 v19, v205, v19, vcc
	v_cmp_ngt_f32_e32 vcc, -1.0, v51
	s_nop 1
	v_cndmask_b32_e32 v19, v206, v19, vcc
	v_cmp_ngt_f32_e32 vcc, -1.0, v50
	s_nop 1
	v_cndmask_b32_e32 v18, v206, v18, vcc
	v_cmp_neq_f32_e32 vcc, -1.0, v50
	s_nop 1
	v_cndmask_b32_e32 v18, v207, v18, vcc
	v_cmp_neq_f32_e32 vcc, -1.0, v51
	s_nop 1
	v_cndmask_b32_e32 v19, v207, v19, vcc
	v_cmp_lt_f32_e64 vcc, |v51|, s91
	s_nop 1
	v_cndmask_b32_e32 v19, v19, v51, vcc
	v_cmp_lt_f32_e64 vcc, |v50|, s91
	s_nop 1
	v_cndmask_b32_e32 v18, v18, v50, vcc
	v_pk_add_f32 v[18:19], v[22:23], v[18:19] neg_lo:[0,1] neg_hi:[0,1]
	v_lshlrev_b64 v[22:23], s53, v[20:21]
	v_lshl_add_u64 v[22:23], v[22:23], 2, s[78:79]
	v_lshl_add_u64 v[22:23], v[22:23], 0, v[152:153]
	s_and_b64 vcc, exec, s[6:7]
	v_mov_b32_e32 v21, s54
	global_store_dwordx4 v[22:23], v[16:19], off nt
	s_cbranch_vccnz .LBB0_248
	v_readlane_b32 s62, v250, 0
	v_readlane_b32 s63, v250, 1
	s_nop 1
	v_mov_b64_e32 v[22:23], s[62:63]
	v_mad_i64_i32 v[20:21], s[62:63], v20, s92, v[22:23]
	v_lshl_add_u64 v[20:21], v[20:21], 0, v[152:153]
	v_add_co_u32_e32 v20, vcc, 0x10c06000, v20
	s_nop 1
	v_addc_co_u32_e32 v21, vcc, 0, v21, vcc
	global_store_dwordx4 v[20:21], v[16:19], off offset:256 nt
	v_mov_b32_e32 v21, v190
.LBB0_248:
	global_load_dword v20, v[158:159], off
	v_or_b32_e32 v18, s55, v191
	v_cndmask_b32_e64 v60, v18, v182, s[4:5]
	v_mov_b64_e32 v[16:17], s[42:43]
	v_lshlrev_b32_e32 v152, 2, v60
	s_waitcnt vmcnt(0)
	v_add_f32_e32 v0, v0, v20
	v_mul_f32_e64 v18, |v0|, s88
	v_add_f32_e32 v1, v1, v20
	v_exp_f32_e32 v61, v18
	v_mul_f32_e64 v19, |v1|, s88
	v_exp_f32_e32 v62, v19
	v_add_f32_e32 v2, v2, v20
	v_add_f32_e32 v24, 1.0, v61
	v_frexp_mant_f32_e32 v27, v24
	v_cvt_f64_f32_e32 v[18:19], v24
	v_add_f32_e32 v25, 1.0, v62
	v_frexp_exp_i32_f64_e32 v18, v[18:19]
	v_cmp_gt_f32_e32 vcc, s89, v27
	v_add_f32_e32 v26, -1.0, v24
	v_add_f32_e32 v28, -1.0, v25
	v_frexp_mant_f32_e32 v29, v25
	v_cvt_f64_f32_e32 v[22:23], v25
	v_subbrev_co_u32_e32 v18, vcc, 0, v18, vcc
	v_sub_f32_e32 v30, v26, v24
	v_sub_f32_e32 v19, v28, v25
	v_frexp_exp_i32_f64_e32 v22, v[22:23]
	v_cmp_gt_f32_e32 vcc, s89, v29
	v_sub_f32_e32 v26, v61, v26
	v_sub_f32_e32 v28, v62, v28
	v_add_f32_e32 v23, 1.0, v30
	v_add_f32_e32 v19, 1.0, v19
	v_subbrev_co_u32_e32 v22, vcc, 0, v22, vcc
	v_add_f32_e32 v23, v26, v23
	v_sub_u32_e32 v26, 0, v18
	v_add_f32_e32 v27, v28, v19
	v_sub_u32_e32 v28, 0, v22
	v_cvt_f32_i32_e32 v19, v22
	v_cvt_f32_i32_e32 v18, v18
	v_ldexp_f32 v22, v24, v26
	v_ldexp_f32 v24, v23, v26
	v_ldexp_f32 v23, v25, v28
	v_ldexp_f32 v25, v27, v28
	v_pk_add_f32 v[26:27], v[22:23], 1.0 op_sel_hi:[1,0]
	v_pk_add_f32 v[28:29], v[22:23], -1.0 op_sel_hi:[1,0]
	v_pk_add_f32 v[30:31], v[26:27], -1.0 op_sel_hi:[1,0]
	v_pk_add_f32 v[32:33], v[28:29], 1.0 op_sel_hi:[1,0]
	v_pk_add_f32 v[30:31], v[22:23], v[30:31] neg_lo:[0,1] neg_hi:[0,1]
	v_pk_add_f32 v[22:23], v[22:23], v[32:33] neg_lo:[0,1] neg_hi:[0,1]
	v_pk_mul_f32 v[32:33], v[18:19], s[48:49] op_sel_hi:[1,0]
	v_pk_add_f32 v[30:31], v[24:25], v[30:31]
	v_pk_add_f32 v[22:23], v[24:25], v[22:23]
	v_pk_fma_f32 v[24:25], v[18:19], s[48:49], v[32:33] op_sel_hi:[1,0,1] neg_lo:[0,0,1] neg_hi:[0,0,1]
	v_pk_add_f32 v[38:39], v[26:27], v[30:31]
	v_pk_fma_f32 v[18:19], v[18:19], s[50:51], v[24:25] op_sel_hi:[1,0,1]
	v_rcp_f32_e32 v24, v38
	v_rcp_f32_e32 v25, v39
	v_pk_add_f32 v[40:41], v[28:29], v[22:23]
	v_pk_add_f32 v[26:27], v[38:39], v[26:27] neg_lo:[0,1] neg_hi:[0,1]
	v_pk_add_f32 v[28:29], v[40:41], v[28:29] neg_lo:[0,1] neg_hi:[0,1]
	v_pk_mul_f32 v[50:51], v[40:41], v[24:25]
	v_pk_add_f32 v[26:27], v[30:31], v[26:27] neg_lo:[0,1] neg_hi:[0,1]
	v_pk_mul_f32 v[52:53], v[38:39], v[50:51]
	v_pk_add_f32 v[22:23], v[22:23], v[28:29] neg_lo:[0,1] neg_hi:[0,1]
	v_pk_fma_f32 v[54:55], v[50:51], v[38:39], v[52:53] neg_lo:[0,0,1] neg_hi:[0,0,1]
	v_pk_add_f32 v[42:43], v[32:33], v[18:19]
	v_pk_fma_f32 v[54:55], v[50:51], v[26:27], v[54:55]
	v_mov_b32_e32 v34, v32
	v_pk_add_f32 v[56:57], v[52:53], v[54:55]
	v_mov_b32_e32 v44, v18
	v_pk_add_f32 v[58:59], v[40:41], v[56:57] neg_lo:[0,1] neg_hi:[0,1]
	v_pk_add_f32 v[52:53], v[56:57], v[52:53] neg_lo:[0,1] neg_hi:[0,1]
	v_pk_add_f32 v[40:41], v[40:41], v[58:59] neg_lo:[0,1] neg_hi:[0,1]
	v_pk_add_f32 v[52:53], v[52:53], v[54:55] neg_lo:[0,1] neg_hi:[0,1]
	v_pk_add_f32 v[40:41], v[40:41], v[56:57] neg_lo:[0,1] neg_hi:[0,1]
	v_mov_b32_e32 v31, v43
	v_pk_add_f32 v[22:23], v[22:23], v[40:41]
	v_mov_b32_e32 v37, v33
	v_pk_add_f32 v[22:23], v[52:53], v[22:23]
	v_mov_b32_e32 v29, v43
	v_pk_add_f32 v[40:41], v[58:59], v[22:23]
	v_mov_b32_e32 v36, v42
	v_pk_mul_f32 v[52:53], v[24:25], v[40:41]
	v_pk_add_f32 v[54:55], v[58:59], v[40:41] neg_lo:[0,1] neg_hi:[0,1]
	v_pk_mul_f32 v[56:57], v[38:39], v[52:53]
	v_pk_add_f32 v[22:23], v[22:23], v[54:55]
	v_pk_add_f32 v[54:55], v[50:51], v[52:53]
	v_pk_fma_f32 v[38:39], v[52:53], v[38:39], v[56:57] neg_lo:[0,0,1] neg_hi:[0,0,1]
	v_pk_add_f32 v[50:51], v[54:55], v[50:51] neg_lo:[0,1] neg_hi:[0,1]
	v_pk_fma_f32 v[26:27], v[52:53], v[26:27], v[38:39]
	v_pk_add_f32 v[38:39], v[52:53], v[50:51] neg_lo:[0,1] neg_hi:[0,1]
	v_pk_add_f32 v[50:51], v[56:57], v[26:27]
	v_mov_b32_e32 v48, v42
	v_pk_add_f32 v[52:53], v[50:51], v[56:57] neg_lo:[0,1] neg_hi:[0,1]
	v_pk_add_f32 v[56:57], v[40:41], v[50:51] neg_lo:[0,1] neg_hi:[0,1]
	v_pk_add_f32 v[26:27], v[52:53], v[26:27] neg_lo:[0,1] neg_hi:[0,1]
	v_pk_add_f32 v[40:41], v[40:41], v[56:57] neg_lo:[0,1] neg_hi:[0,1]
	v_mov_b32_e32 v47, v19
	v_pk_add_f32 v[40:41], v[40:41], v[50:51] neg_lo:[0,1] neg_hi:[0,1]
	v_cmp_neq_f32_e32 vcc, s90, v61
	v_pk_add_f32 v[22:23], v[22:23], v[40:41]
	v_min_f32_e32 v0, 0, v0
	v_pk_add_f32 v[22:23], v[26:27], v[22:23]
	v_min_f32_e32 v1, 0, v1
	v_pk_add_f32 v[22:23], v[56:57], v[22:23]
	v_add_f32_e32 v3, v3, v20
	v_pk_mul_f32 v[22:23], v[24:25], v[22:23]
	s_nop 0
	v_pk_add_f32 v[22:23], v[38:39], v[22:23]
	s_nop 0
	v_pk_add_f32 v[24:25], v[54:55], v[22:23]
	s_nop 0
	v_pk_add_f32 v[26:27], v[24:25], v[54:55] neg_lo:[0,1] neg_hi:[0,1]
	v_pk_mul_f32 v[40:41], v[24:25], v[24:25]
	v_pk_add_f32 v[22:23], v[22:23], v[26:27] neg_lo:[0,1] neg_hi:[0,1]
	v_pk_fma_f32 v[26:27], v[40:41], s[44:45], v[16:17] op_sel_hi:[1,0,0]
	v_ldexp_f32 v38, v24, 1
	v_ldexp_f32 v39, v25, 1
	v_pk_mul_f32 v[24:25], v[24:25], v[40:41]
	v_pk_fma_f32 v[26:27], v[40:41], v[26:27], s[46:47] op_sel_hi:[1,1,0]
	v_ldexp_f32 v45, v23, 1
	v_pk_mul_f32 v[24:25], v[24:25], v[26:27]
	v_ldexp_f32 v22, v22, 1
	v_pk_add_f32 v[26:27], v[38:39], v[24:25]
	v_mov_b32_e32 v23, v45
	v_pk_add_f32 v[38:39], v[26:27], v[38:39] neg_lo:[0,1] neg_hi:[0,1]
	v_mov_b32_e32 v30, v26
	v_pk_add_f32 v[24:25], v[24:25], v[38:39] neg_lo:[0,1] neg_hi:[0,1]
	s_nop 0
	v_pk_add_f32 v[38:39], v[22:23], v[24:25]
	v_mov_b32_e32 v35, v25
	v_mov_b32_e32 v25, v27
	v_mov_b32_e32 v23, v39
	v_pk_add_f32 v[40:41], v[26:27], v[38:39]
	v_pk_add_f32 v[22:23], v[22:23], v[24:25]
	v_pk_add_f32 v[24:25], v[42:43], v[40:41]
	v_pk_add_f32 v[34:35], v[34:35], v[44:45]
	v_mov_b32_e32 v44, v40
	v_mov_b32_e32 v45, v25
	v_pk_add_f32 v[30:31], v[44:45], v[30:31] neg_lo:[0,1] neg_hi:[0,1]
	v_mov_b32_e32 v28, v24
	v_mov_b32_e32 v49, v25
	v_mov_b32_e32 v33, v31
	v_mov_b32_e32 v46, v40
	v_pk_add_f32 v[28:29], v[28:29], v[36:37] neg_lo:[0,1] neg_hi:[0,1]
	v_pk_add_f32 v[32:33], v[48:49], v[32:33] neg_lo:[0,1] neg_hi:[0,1]
	v_pk_add_f32 v[36:37], v[46:47], v[28:29] neg_lo:[0,1] neg_hi:[0,1]
	v_mov_b32_e32 v44, v32
	v_mov_b32_e32 v45, v29
	v_mov_b32_e32 v46, v24
	v_mov_b32_e32 v47, v41
	v_mov_b32_e32 v29, v27
	v_pk_add_f32 v[44:45], v[18:19], v[44:45] neg_lo:[0,1] neg_hi:[0,1]
	v_pk_add_f32 v[28:29], v[46:47], v[28:29] neg_lo:[0,1] neg_hi:[0,1]
	v_mov_b32_e32 v19, v43
	v_pk_add_f32 v[28:29], v[34:35], v[28:29] neg_lo:[0,1] neg_hi:[0,1]
	v_pk_add_f32 v[18:19], v[18:19], v[32:33] neg_lo:[0,1] neg_hi:[0,1]
	v_pk_add_f32 v[22:23], v[22:23], v[30:31] neg_lo:[0,1] neg_hi:[0,1]
	v_pk_add_f32 v[32:33], v[36:37], v[28:29]
	v_pk_add_f32 v[30:31], v[22:23], v[18:19]
	v_mov_b32_e32 v19, v37
	v_mov_b32_e32 v23, v29
	v_pk_add_f32 v[22:23], v[18:19], v[22:23]
	v_pk_add_f32 v[26:27], v[40:41], v[26:27] neg_lo:[0,1] neg_hi:[0,1]
	v_pk_add_f32 v[22:23], v[22:23], v[44:45] neg_lo:[0,1] neg_hi:[0,1]
	v_mov_b32_e32 v28, v30
	v_mov_b32_e32 v29, v33
	v_pk_add_f32 v[26:27], v[38:39], v[26:27] neg_lo:[0,1] neg_hi:[0,1]
	v_pk_add_f32 v[28:29], v[28:29], v[22:23] neg_lo:[0,1] neg_hi:[0,1]
	v_pk_add_f32 v[22:23], v[26:27], v[22:23] neg_lo:[0,1] neg_hi:[0,1]
	v_pk_add_f32 v[18:19], v[18:19], v[28:29] neg_lo:[0,1] neg_hi:[0,1]
	s_nop 0
	v_pk_add_f32 v[18:19], v[22:23], v[18:19]
	v_pk_add_f32 v[22:23], v[32:33], v[30:31]
	s_nop 0
	v_pk_add_f32 v[26:27], v[24:25], v[22:23]
	s_nop 0
	v_pk_add_f32 v[24:25], v[26:27], v[24:25] neg_lo:[0,1] neg_hi:[0,1]
	s_nop 0
	v_pk_add_f32 v[22:23], v[22:23], v[24:25] neg_lo:[0,1] neg_hi:[0,1]
	s_nop 0
	v_pk_add_f32 v[18:19], v[18:19], v[22:23]
	v_mul_f32_e64 v22, |v2|, s88
	v_pk_add_f32 v[18:19], v[26:27], v[18:19]
	v_exp_f32_e32 v46, v22
	v_cndmask_b32_e32 v18, v205, v18, vcc
	v_cmp_neq_f32_e32 vcc, s90, v62
	v_min_f32_e32 v2, 0, v2
	v_add_f32_e32 v22, 1.0, v46
	v_cndmask_b32_e32 v19, v205, v19, vcc
	v_cmp_ngt_f32_e32 vcc, -1.0, v62
	v_frexp_mant_f32_e32 v24, v22
	s_nop 0
	v_cndmask_b32_e32 v19, v206, v19, vcc
	v_cmp_ngt_f32_e32 vcc, -1.0, v61
	s_nop 1
	v_cndmask_b32_e32 v18, v206, v18, vcc
	v_cmp_neq_f32_e32 vcc, -1.0, v61
	s_nop 1
	v_cndmask_b32_e32 v18, v207, v18, vcc
	v_cmp_neq_f32_e32 vcc, -1.0, v62
	s_nop 1
	v_cndmask_b32_e32 v19, v207, v19, vcc
	v_cmp_lt_f32_e64 vcc, |v62|, s91
	s_nop 1
	v_cndmask_b32_e32 v19, v19, v62, vcc
	v_cmp_lt_f32_e64 vcc, |v61|, s91
	s_nop 1
	v_cndmask_b32_e32 v18, v18, v61, vcc
	v_pk_add_f32 v[0:1], v[0:1], v[18:19] neg_lo:[0,1] neg_hi:[0,1]
	v_add_f32_e32 v18, -1.0, v22
	v_sub_f32_e32 v19, v18, v22
	v_add_f32_e32 v19, 1.0, v19
	v_sub_f32_e32 v18, v46, v18
	v_add_f32_e32 v23, v18, v19
	v_cvt_f64_f32_e32 v[18:19], v22
	v_frexp_exp_i32_f64_e32 v18, v[18:19]
	v_cmp_gt_f32_e32 vcc, s89, v24
	s_nop 1
	v_subbrev_co_u32_e32 v40, vcc, 0, v18, vcc
	v_mul_f32_e64 v18, |v3|, s88
	v_exp_f32_e32 v20, v18
	v_sub_u32_e32 v19, 0, v40
	v_ldexp_f32 v18, v22, v19
	v_ldexp_f32 v22, v23, v19
	v_add_f32_e32 v19, 1.0, v20
	v_add_f32_e32 v23, -1.0, v19
	v_sub_f32_e32 v24, v23, v19
	v_add_f32_e32 v24, 1.0, v24
	v_sub_f32_e32 v23, v20, v23
	v_add_f32_e32 v23, v23, v24
	v_frexp_mant_f32_e32 v26, v19
	v_cvt_f64_f32_e32 v[24:25], v19
	v_frexp_exp_i32_f64_e32 v24, v[24:25]
	v_cmp_gt_f32_e32 vcc, s89, v26
	v_min_f32_e32 v3, 0, v3
	s_nop 0
	v_subbrev_co_u32_e32 v41, vcc, 0, v24, vcc
	v_sub_u32_e32 v24, 0, v41
	v_ldexp_f32 v19, v19, v24
	v_ldexp_f32 v23, v23, v24
	v_pk_add_f32 v[24:25], v[18:19], 1.0 op_sel_hi:[1,0]
	v_pk_add_f32 v[32:33], v[18:19], -1.0 op_sel_hi:[1,0]
	v_pk_add_f32 v[26:27], v[24:25], -1.0 op_sel_hi:[1,0]
	v_pk_add_f32 v[34:35], v[32:33], 1.0 op_sel_hi:[1,0]
	v_pk_add_f32 v[26:27], v[18:19], v[26:27] neg_lo:[0,1] neg_hi:[0,1]
	v_pk_add_f32 v[18:19], v[18:19], v[34:35] neg_lo:[0,1] neg_hi:[0,1]
	v_pk_add_f32 v[26:27], v[22:23], v[26:27]
	v_pk_add_f32 v[18:19], v[22:23], v[18:19]
	v_pk_add_f32 v[28:29], v[24:25], v[26:27]
	v_pk_add_f32 v[22:23], v[32:33], v[18:19]
	v_rcp_f32_e32 v30, v28
	v_rcp_f32_e32 v31, v29
	v_pk_add_f32 v[24:25], v[28:29], v[24:25] neg_lo:[0,1] neg_hi:[0,1]
	v_pk_add_f32 v[32:33], v[22:23], v[32:33] neg_lo:[0,1] neg_hi:[0,1]
	v_pk_add_f32 v[24:25], v[26:27], v[24:25] neg_lo:[0,1] neg_hi:[0,1]
	v_pk_mul_f32 v[26:27], v[22:23], v[30:31]
	v_pk_add_f32 v[18:19], v[18:19], v[32:33] neg_lo:[0,1] neg_hi:[0,1]
	v_pk_mul_f32 v[32:33], v[28:29], v[26:27]
	v_cmp_neq_f32_e32 vcc, s90, v46
	v_pk_fma_f32 v[34:35], v[26:27], v[28:29], v[32:33] neg_lo:[0,0,1] neg_hi:[0,0,1]
	s_nop 0
	v_pk_fma_f32 v[34:35], v[26:27], v[24:25], v[34:35]
	s_nop 0
	v_pk_add_f32 v[36:37], v[32:33], v[34:35]
	s_nop 0
	v_pk_add_f32 v[38:39], v[22:23], v[36:37] neg_lo:[0,1] neg_hi:[0,1]
	v_pk_add_f32 v[32:33], v[36:37], v[32:33] neg_lo:[0,1] neg_hi:[0,1]
	v_pk_add_f32 v[22:23], v[22:23], v[38:39] neg_lo:[0,1] neg_hi:[0,1]
	s_nop 0
	v_pk_add_f32 v[22:23], v[22:23], v[36:37] neg_lo:[0,1] neg_hi:[0,1]
	s_nop 0
	v_pk_add_f32 v[18:19], v[18:19], v[22:23]
	v_pk_add_f32 v[22:23], v[32:33], v[34:35] neg_lo:[0,1] neg_hi:[0,1]
	s_nop 0
	v_pk_add_f32 v[18:19], v[22:23], v[18:19]
	s_nop 0
	v_pk_add_f32 v[22:23], v[38:39], v[18:19]
	s_nop 0
	v_pk_mul_f32 v[32:33], v[30:31], v[22:23]
	s_nop 0
	v_pk_mul_f32 v[34:35], v[28:29], v[32:33]
	s_nop 0
	v_pk_fma_f32 v[28:29], v[32:33], v[28:29], v[34:35] neg_lo:[0,0,1] neg_hi:[0,0,1]
	s_nop 0
	v_pk_fma_f32 v[24:25], v[32:33], v[24:25], v[28:29]
	v_pk_add_f32 v[28:29], v[38:39], v[22:23] neg_lo:[0,1] neg_hi:[0,1]
	s_nop 0
	v_pk_add_f32 v[18:19], v[18:19], v[28:29]
	v_pk_add_f32 v[28:29], v[34:35], v[24:25]
	s_nop 0
	v_pk_add_f32 v[36:37], v[22:23], v[28:29] neg_lo:[0,1] neg_hi:[0,1]
	v_pk_add_f32 v[34:35], v[28:29], v[34:35] neg_lo:[0,1] neg_hi:[0,1]
	v_pk_add_f32 v[22:23], v[22:23], v[36:37] neg_lo:[0,1] neg_hi:[0,1]
	s_nop 0
	v_pk_add_f32 v[22:23], v[22:23], v[28:29] neg_lo:[0,1] neg_hi:[0,1]
	v_cvt_f32_i32_e32 v29, v41
	v_pk_add_f32 v[18:19], v[18:19], v[22:23]
	v_pk_add_f32 v[22:23], v[34:35], v[24:25] neg_lo:[0,1] neg_hi:[0,1]
	v_cvt_f32_i32_e32 v28, v40
	v_pk_add_f32 v[18:19], v[22:23], v[18:19]
	v_pk_add_f32 v[22:23], v[26:27], v[32:33]
	v_pk_add_f32 v[18:19], v[36:37], v[18:19]
	v_pk_add_f32 v[24:25], v[22:23], v[26:27] neg_lo:[0,1] neg_hi:[0,1]
	v_pk_mul_f32 v[18:19], v[30:31], v[18:19]
	v_pk_add_f32 v[24:25], v[32:33], v[24:25] neg_lo:[0,1] neg_hi:[0,1]
	s_nop 0
	v_pk_add_f32 v[18:19], v[24:25], v[18:19]
	s_nop 0
	v_pk_add_f32 v[24:25], v[22:23], v[18:19]
	s_nop 0
	v_pk_mul_f32 v[26:27], v[24:25], v[24:25]
	v_pk_add_f32 v[22:23], v[24:25], v[22:23] neg_lo:[0,1] neg_hi:[0,1]
	v_pk_fma_f32 v[16:17], v[26:27], s[44:45], v[16:17] op_sel_hi:[1,0,0]
	v_pk_add_f32 v[18:19], v[18:19], v[22:23] neg_lo:[0,1] neg_hi:[0,1]
	v_ldexp_f32 v22, v24, 1
	v_pk_fma_f32 v[16:17], v[26:27], v[16:17], s[46:47] op_sel_hi:[1,1,0]
	v_ldexp_f32 v23, v25, 1
	v_pk_mul_f32 v[24:25], v[24:25], v[26:27]
	v_pk_mul_f32 v[26:27], v[28:29], s[48:49] op_sel_hi:[1,0]
	v_pk_mul_f32 v[16:17], v[24:25], v[16:17]
	v_pk_fma_f32 v[32:33], v[28:29], s[48:49], v[26:27] op_sel_hi:[1,0,1] neg_lo:[0,0,1] neg_hi:[0,0,1]
	v_pk_add_f32 v[24:25], v[22:23], v[16:17]
	v_ldexp_f32 v31, v19, 1
	v_pk_add_f32 v[22:23], v[24:25], v[22:23] neg_lo:[0,1] neg_hi:[0,1]
	v_pk_fma_f32 v[28:29], v[28:29], s[50:51], v[32:33] op_sel_hi:[1,0,1]
	v_pk_add_f32 v[16:17], v[16:17], v[22:23] neg_lo:[0,1] neg_hi:[0,1]
	v_ldexp_f32 v18, v18, 1
	v_mov_b32_e32 v22, v26
	v_mov_b32_e32 v23, v17
	v_mov_b32_e32 v30, v28
	v_mov_b32_e32 v19, v31
	v_pk_add_f32 v[22:23], v[22:23], v[30:31]
	v_pk_add_f32 v[30:31], v[18:19], v[16:17]
	v_mov_b32_e32 v17, v25
	v_mov_b32_e32 v19, v31
	v_pk_add_f32 v[32:33], v[26:27], v[28:29]
	v_pk_add_f32 v[16:17], v[18:19], v[16:17]
	v_pk_add_f32 v[18:19], v[24:25], v[30:31]
	v_mov_b32_e32 v42, v24
	v_pk_add_f32 v[34:35], v[32:33], v[18:19]
	v_mov_b32_e32 v40, v18
	v_mov_b32_e32 v41, v35
	v_mov_b32_e32 v43, v33
	v_pk_add_f32 v[40:41], v[40:41], v[42:43] neg_lo:[0,1] neg_hi:[0,1]
	v_mov_b32_e32 v36, v34
	v_mov_b32_e32 v37, v33
	v_mov_b32_e32 v38, v32
	v_mov_b32_e32 v39, v27
	v_mov_b32_e32 v42, v32
	v_mov_b32_e32 v43, v35
	v_mov_b32_e32 v27, v41
	v_pk_add_f32 v[36:37], v[36:37], v[38:39] neg_lo:[0,1] neg_hi:[0,1]
	v_mov_b32_e32 v38, v18
	v_mov_b32_e32 v39, v29
	v_pk_add_f32 v[26:27], v[42:43], v[26:27] neg_lo:[0,1] neg_hi:[0,1]
	v_pk_add_f32 v[38:39], v[38:39], v[36:37] neg_lo:[0,1] neg_hi:[0,1]
	v_mov_b32_e32 v42, v26
	v_mov_b32_e32 v43, v37
	v_mov_b32_e32 v44, v34
	v_mov_b32_e32 v45, v19
	v_mov_b32_e32 v37, v25
	v_pk_add_f32 v[42:43], v[28:29], v[42:43] neg_lo:[0,1] neg_hi:[0,1]
	v_pk_add_f32 v[36:37], v[44:45], v[36:37] neg_lo:[0,1] neg_hi:[0,1]
	v_mov_b32_e32 v29, v33
	v_pk_add_f32 v[18:19], v[18:19], v[24:25] neg_lo:[0,1] neg_hi:[0,1]
	v_pk_add_f32 v[22:23], v[22:23], v[36:37] neg_lo:[0,1] neg_hi:[0,1]
	v_pk_add_f32 v[24:25], v[28:29], v[26:27] neg_lo:[0,1] neg_hi:[0,1]
	v_pk_add_f32 v[16:17], v[16:17], v[40:41] neg_lo:[0,1] neg_hi:[0,1]
	v_pk_add_f32 v[28:29], v[38:39], v[22:23]
	v_pk_add_f32 v[26:27], v[16:17], v[24:25]
	v_mov_b32_e32 v25, v39
	v_mov_b32_e32 v17, v23
	v_pk_add_f32 v[16:17], v[24:25], v[16:17]
	v_mov_b32_e32 v22, v26
	v_pk_add_f32 v[16:17], v[16:17], v[42:43] neg_lo:[0,1] neg_hi:[0,1]
	v_mov_b32_e32 v23, v29
	v_pk_add_f32 v[18:19], v[30:31], v[18:19] neg_lo:[0,1] neg_hi:[0,1]
	v_pk_add_f32 v[22:23], v[22:23], v[16:17] neg_lo:[0,1] neg_hi:[0,1]
	v_pk_add_f32 v[16:17], v[18:19], v[16:17] neg_lo:[0,1] neg_hi:[0,1]
	v_pk_add_f32 v[22:23], v[24:25], v[22:23] neg_lo:[0,1] neg_hi:[0,1]
	v_pk_add_f32 v[18:19], v[28:29], v[26:27]
	v_pk_add_f32 v[16:17], v[16:17], v[22:23]
	v_pk_add_f32 v[22:23], v[34:35], v[18:19]
	s_nop 0
	v_pk_add_f32 v[24:25], v[22:23], v[34:35] neg_lo:[0,1] neg_hi:[0,1]
	s_nop 0
	v_pk_add_f32 v[18:19], v[18:19], v[24:25] neg_lo:[0,1] neg_hi:[0,1]
	s_nop 0
	v_pk_add_f32 v[16:17], v[16:17], v[18:19]
	s_nop 0
	v_pk_add_f32 v[16:17], v[22:23], v[16:17]
	s_nop 0
	v_cndmask_b32_e32 v16, v205, v16, vcc
	v_cmp_neq_f32_e32 vcc, s90, v20
	s_nop 1
	v_cndmask_b32_e32 v17, v205, v17, vcc
	v_cmp_ngt_f32_e32 vcc, -1.0, v20
	s_nop 1
	v_cndmask_b32_e32 v17, v206, v17, vcc
	v_cmp_ngt_f32_e32 vcc, -1.0, v46
	s_nop 1
	v_cndmask_b32_e32 v16, v206, v16, vcc
	v_cmp_neq_f32_e32 vcc, -1.0, v46
	s_nop 1
	v_cndmask_b32_e32 v16, v207, v16, vcc
	v_cmp_neq_f32_e32 vcc, -1.0, v20
	s_nop 1
	v_cndmask_b32_e32 v17, v207, v17, vcc
	v_cmp_lt_f32_e64 vcc, |v20|, s91
	s_nop 1
	v_cndmask_b32_e32 v17, v17, v20, vcc
	v_cmp_lt_f32_e64 vcc, |v46|, s91
	s_nop 1
	v_cndmask_b32_e32 v16, v16, v46, vcc
	v_pk_add_f32 v[2:3], v[2:3], v[16:17] neg_lo:[0,1] neg_hi:[0,1]
	v_lshl_or_b32 v16, v21, 3, v161
	v_ashrrev_i32_e32 v17, 31, v16
	v_lshlrev_b64 v[18:19], s53, v[16:17]
	v_lshl_add_u64 v[18:19], v[18:19], 2, s[78:79]
	v_lshl_add_u64 v[18:19], v[18:19], 0, v[152:153]
	s_and_b64 vcc, exec, s[6:7]
	v_mov_b32_e32 v17, s54
	global_store_dwordx4 v[18:19], v[0:3], off nt
	s_cbranch_vccnz .LBB0_250
	v_readlane_b32 s62, v250, 0
	v_readlane_b32 s63, v250, 1
	s_nop 1
	v_mov_b64_e32 v[18:19], s[62:63]
	v_mad_i64_i32 v[16:17], s[62:63], v16, s92, v[18:19]
	v_lshl_add_u64 v[16:17], v[16:17], 0, v[152:153]
	v_add_co_u32_e32 v16, vcc, 0x10c06000, v16
	s_nop 1
	v_addc_co_u32_e32 v17, vcc, 0, v17, vcc
	global_store_dwordx4 v[16:17], v[0:3], off offset:256 nt
	v_mov_b32_e32 v17, v195
.LBB0_250:
	global_load_dword v16, v[158:159], off
	v_or_b32_e32 v0, s55, v196
	v_cndmask_b32_e64 v56, v0, v189, s[4:5]
	v_mov_b64_e32 v[2:3], s[42:43]
	v_lshlrev_b32_e32 v152, 2, v56
	s_waitcnt vmcnt(0)
	v_add_f32_e32 v0, v4, v16
	v_mul_f32_e64 v4, |v0|, s88
	v_add_f32_e32 v1, v5, v16
	v_exp_f32_e32 v57, v4
	v_mul_f32_e64 v5, |v1|, s88
	v_exp_f32_e32 v58, v5
	v_add_f32_e32 v6, v6, v16
	v_add_f32_e32 v20, 1.0, v57
	v_frexp_mant_f32_e32 v23, v20
	v_cvt_f64_f32_e32 v[4:5], v20
	v_add_f32_e32 v21, 1.0, v58
	v_frexp_exp_i32_f64_e32 v4, v[4:5]
	v_cmp_gt_f32_e32 vcc, s89, v23
	v_add_f32_e32 v22, -1.0, v20
	v_add_f32_e32 v24, -1.0, v21
	v_frexp_mant_f32_e32 v25, v21
	v_cvt_f64_f32_e32 v[18:19], v21
	v_subbrev_co_u32_e32 v4, vcc, 0, v4, vcc
	v_sub_f32_e32 v26, v22, v20
	v_sub_f32_e32 v5, v24, v21
	v_frexp_exp_i32_f64_e32 v18, v[18:19]
	v_cmp_gt_f32_e32 vcc, s89, v25
	v_sub_f32_e32 v22, v57, v22
	v_sub_f32_e32 v24, v58, v24
	v_add_f32_e32 v19, 1.0, v26
	v_add_f32_e32 v5, 1.0, v5
	v_subbrev_co_u32_e32 v18, vcc, 0, v18, vcc
	v_add_f32_e32 v19, v22, v19
	v_sub_u32_e32 v22, 0, v4
	v_add_f32_e32 v23, v24, v5
	v_sub_u32_e32 v24, 0, v18
	v_cvt_f32_i32_e32 v5, v18
	v_cvt_f32_i32_e32 v4, v4
	v_ldexp_f32 v18, v20, v22
	v_ldexp_f32 v20, v19, v22
	v_ldexp_f32 v19, v21, v24
	v_ldexp_f32 v21, v23, v24
	v_pk_add_f32 v[22:23], v[18:19], 1.0 op_sel_hi:[1,0]
	v_pk_add_f32 v[24:25], v[18:19], -1.0 op_sel_hi:[1,0]
	v_pk_add_f32 v[26:27], v[22:23], -1.0 op_sel_hi:[1,0]
	v_pk_add_f32 v[28:29], v[24:25], 1.0 op_sel_hi:[1,0]
	v_pk_add_f32 v[26:27], v[18:19], v[26:27] neg_lo:[0,1] neg_hi:[0,1]
	v_pk_add_f32 v[18:19], v[18:19], v[28:29] neg_lo:[0,1] neg_hi:[0,1]
	v_pk_mul_f32 v[28:29], v[4:5], s[48:49] op_sel_hi:[1,0]
	v_pk_add_f32 v[26:27], v[20:21], v[26:27]
	v_pk_add_f32 v[18:19], v[20:21], v[18:19]
	v_pk_fma_f32 v[20:21], v[4:5], s[48:49], v[28:29] op_sel_hi:[1,0,1] neg_lo:[0,0,1] neg_hi:[0,0,1]
	v_pk_add_f32 v[34:35], v[22:23], v[26:27]
	v_pk_fma_f32 v[4:5], v[4:5], s[50:51], v[20:21] op_sel_hi:[1,0,1]
	v_rcp_f32_e32 v20, v34
	v_rcp_f32_e32 v21, v35
	v_pk_add_f32 v[36:37], v[24:25], v[18:19]
	v_pk_add_f32 v[22:23], v[34:35], v[22:23] neg_lo:[0,1] neg_hi:[0,1]
	v_pk_add_f32 v[24:25], v[36:37], v[24:25] neg_lo:[0,1] neg_hi:[0,1]
	v_pk_mul_f32 v[46:47], v[36:37], v[20:21]
	v_pk_add_f32 v[22:23], v[26:27], v[22:23] neg_lo:[0,1] neg_hi:[0,1]
	v_pk_mul_f32 v[48:49], v[34:35], v[46:47]
	v_pk_add_f32 v[18:19], v[18:19], v[24:25] neg_lo:[0,1] neg_hi:[0,1]
	v_pk_fma_f32 v[50:51], v[46:47], v[34:35], v[48:49] neg_lo:[0,0,1] neg_hi:[0,0,1]
	v_pk_add_f32 v[38:39], v[28:29], v[4:5]
	v_pk_fma_f32 v[50:51], v[46:47], v[22:23], v[50:51]
	v_mov_b32_e32 v30, v28
	v_pk_add_f32 v[52:53], v[48:49], v[50:51]
	v_mov_b32_e32 v40, v4
	v_pk_add_f32 v[54:55], v[36:37], v[52:53] neg_lo:[0,1] neg_hi:[0,1]
	v_pk_add_f32 v[48:49], v[52:53], v[48:49] neg_lo:[0,1] neg_hi:[0,1]
	v_pk_add_f32 v[36:37], v[36:37], v[54:55] neg_lo:[0,1] neg_hi:[0,1]
	v_pk_add_f32 v[48:49], v[48:49], v[50:51] neg_lo:[0,1] neg_hi:[0,1]
	v_pk_add_f32 v[36:37], v[36:37], v[52:53] neg_lo:[0,1] neg_hi:[0,1]
	v_mov_b32_e32 v27, v39
	v_pk_add_f32 v[18:19], v[18:19], v[36:37]
	v_mov_b32_e32 v33, v29
	v_pk_add_f32 v[18:19], v[48:49], v[18:19]
	v_mov_b32_e32 v25, v39
	v_pk_add_f32 v[36:37], v[54:55], v[18:19]
	v_mov_b32_e32 v32, v38
	v_pk_mul_f32 v[48:49], v[20:21], v[36:37]
	v_pk_add_f32 v[50:51], v[54:55], v[36:37] neg_lo:[0,1] neg_hi:[0,1]
	v_pk_mul_f32 v[52:53], v[34:35], v[48:49]
	v_pk_add_f32 v[18:19], v[18:19], v[50:51]
	v_pk_add_f32 v[50:51], v[46:47], v[48:49]
	v_pk_fma_f32 v[34:35], v[48:49], v[34:35], v[52:53] neg_lo:[0,0,1] neg_hi:[0,0,1]
	v_pk_add_f32 v[46:47], v[50:51], v[46:47] neg_lo:[0,1] neg_hi:[0,1]
	v_pk_fma_f32 v[22:23], v[48:49], v[22:23], v[34:35]
	v_pk_add_f32 v[34:35], v[48:49], v[46:47] neg_lo:[0,1] neg_hi:[0,1]
	v_pk_add_f32 v[46:47], v[52:53], v[22:23]
	v_mov_b32_e32 v44, v38
	v_pk_add_f32 v[48:49], v[46:47], v[52:53] neg_lo:[0,1] neg_hi:[0,1]
	v_pk_add_f32 v[52:53], v[36:37], v[46:47] neg_lo:[0,1] neg_hi:[0,1]
	v_pk_add_f32 v[22:23], v[48:49], v[22:23] neg_lo:[0,1] neg_hi:[0,1]
	v_pk_add_f32 v[36:37], v[36:37], v[52:53] neg_lo:[0,1] neg_hi:[0,1]
	v_mov_b32_e32 v43, v5
	v_pk_add_f32 v[36:37], v[36:37], v[46:47] neg_lo:[0,1] neg_hi:[0,1]
	v_cmp_neq_f32_e32 vcc, s90, v57
	v_pk_add_f32 v[18:19], v[18:19], v[36:37]
	v_min_f32_e32 v0, 0, v0
	v_pk_add_f32 v[18:19], v[22:23], v[18:19]
	v_min_f32_e32 v1, 0, v1
	v_pk_add_f32 v[18:19], v[52:53], v[18:19]
	v_add_f32_e32 v7, v7, v16
	v_pk_mul_f32 v[18:19], v[20:21], v[18:19]
	s_nop 0
	v_pk_add_f32 v[18:19], v[34:35], v[18:19]
	s_nop 0
	v_pk_add_f32 v[20:21], v[50:51], v[18:19]
	s_nop 0
	v_pk_add_f32 v[22:23], v[20:21], v[50:51] neg_lo:[0,1] neg_hi:[0,1]
	v_pk_mul_f32 v[36:37], v[20:21], v[20:21]
	v_pk_add_f32 v[18:19], v[18:19], v[22:23] neg_lo:[0,1] neg_hi:[0,1]
	v_pk_fma_f32 v[22:23], v[36:37], s[44:45], v[2:3] op_sel_hi:[1,0,0]
	v_ldexp_f32 v34, v20, 1
	v_ldexp_f32 v35, v21, 1
	v_pk_mul_f32 v[20:21], v[20:21], v[36:37]
	v_pk_fma_f32 v[22:23], v[36:37], v[22:23], s[46:47] op_sel_hi:[1,1,0]
	v_ldexp_f32 v41, v19, 1
	v_pk_mul_f32 v[20:21], v[20:21], v[22:23]
	v_ldexp_f32 v18, v18, 1
	v_pk_add_f32 v[22:23], v[34:35], v[20:21]
	v_mov_b32_e32 v19, v41
	v_pk_add_f32 v[34:35], v[22:23], v[34:35] neg_lo:[0,1] neg_hi:[0,1]
	v_mov_b32_e32 v26, v22
	v_pk_add_f32 v[20:21], v[20:21], v[34:35] neg_lo:[0,1] neg_hi:[0,1]
	s_nop 0
	v_pk_add_f32 v[34:35], v[18:19], v[20:21]
	v_mov_b32_e32 v31, v21
	v_mov_b32_e32 v21, v23
	v_mov_b32_e32 v19, v35
	v_pk_add_f32 v[36:37], v[22:23], v[34:35]
	v_pk_add_f32 v[18:19], v[18:19], v[20:21]
	v_pk_add_f32 v[20:21], v[38:39], v[36:37]
	v_pk_add_f32 v[30:31], v[30:31], v[40:41]
	v_mov_b32_e32 v40, v36
	v_mov_b32_e32 v41, v21
	v_pk_add_f32 v[26:27], v[40:41], v[26:27] neg_lo:[0,1] neg_hi:[0,1]
	v_mov_b32_e32 v24, v20
	v_mov_b32_e32 v45, v21
	v_mov_b32_e32 v29, v27
	v_mov_b32_e32 v42, v36
	v_pk_add_f32 v[24:25], v[24:25], v[32:33] neg_lo:[0,1] neg_hi:[0,1]
	v_pk_add_f32 v[28:29], v[44:45], v[28:29] neg_lo:[0,1] neg_hi:[0,1]
	v_pk_add_f32 v[32:33], v[42:43], v[24:25] neg_lo:[0,1] neg_hi:[0,1]
	v_mov_b32_e32 v40, v28
	v_mov_b32_e32 v41, v25
	v_mov_b32_e32 v42, v20
	v_mov_b32_e32 v43, v37
	v_mov_b32_e32 v25, v23
	v_pk_add_f32 v[40:41], v[4:5], v[40:41] neg_lo:[0,1] neg_hi:[0,1]
	v_pk_add_f32 v[24:25], v[42:43], v[24:25] neg_lo:[0,1] neg_hi:[0,1]
	v_mov_b32_e32 v5, v39
	v_pk_add_f32 v[24:25], v[30:31], v[24:25] neg_lo:[0,1] neg_hi:[0,1]
	v_pk_add_f32 v[4:5], v[4:5], v[28:29] neg_lo:[0,1] neg_hi:[0,1]
	v_pk_add_f32 v[18:19], v[18:19], v[26:27] neg_lo:[0,1] neg_hi:[0,1]
	v_pk_add_f32 v[28:29], v[32:33], v[24:25]
	v_pk_add_f32 v[26:27], v[18:19], v[4:5]
	v_mov_b32_e32 v5, v33
	v_mov_b32_e32 v19, v25
	v_pk_add_f32 v[18:19], v[4:5], v[18:19]
	v_pk_add_f32 v[22:23], v[36:37], v[22:23] neg_lo:[0,1] neg_hi:[0,1]
	v_pk_add_f32 v[18:19], v[18:19], v[40:41] neg_lo:[0,1] neg_hi:[0,1]
	v_mov_b32_e32 v24, v26
	v_mov_b32_e32 v25, v29
	v_pk_add_f32 v[22:23], v[34:35], v[22:23] neg_lo:[0,1] neg_hi:[0,1]
	v_pk_add_f32 v[24:25], v[24:25], v[18:19] neg_lo:[0,1] neg_hi:[0,1]
	v_pk_add_f32 v[18:19], v[22:23], v[18:19] neg_lo:[0,1] neg_hi:[0,1]
	v_pk_add_f32 v[4:5], v[4:5], v[24:25] neg_lo:[0,1] neg_hi:[0,1]
	s_nop 0
	v_pk_add_f32 v[4:5], v[18:19], v[4:5]
	v_pk_add_f32 v[18:19], v[28:29], v[26:27]
	s_nop 0
	v_pk_add_f32 v[22:23], v[20:21], v[18:19]
	s_nop 0
	v_pk_add_f32 v[20:21], v[22:23], v[20:21] neg_lo:[0,1] neg_hi:[0,1]
	s_nop 0
	v_pk_add_f32 v[18:19], v[18:19], v[20:21] neg_lo:[0,1] neg_hi:[0,1]
	s_nop 0
	v_pk_add_f32 v[4:5], v[4:5], v[18:19]
	v_mul_f32_e64 v18, |v6|, s88
	v_pk_add_f32 v[4:5], v[22:23], v[4:5]
	v_exp_f32_e32 v42, v18
	v_cndmask_b32_e32 v4, v205, v4, vcc
	v_cmp_neq_f32_e32 vcc, s90, v58
	s_nop 1
	v_cndmask_b32_e32 v5, v205, v5, vcc
	v_cmp_ngt_f32_e32 vcc, -1.0, v58
	s_nop 1
	v_cndmask_b32_e32 v5, v206, v5, vcc
	v_cmp_ngt_f32_e32 vcc, -1.0, v57
	s_nop 1
	v_cndmask_b32_e32 v4, v206, v4, vcc
	v_cmp_neq_f32_e32 vcc, -1.0, v57
	s_nop 1
	v_cndmask_b32_e32 v4, v207, v4, vcc
	v_cmp_neq_f32_e32 vcc, -1.0, v58
	s_nop 1
	v_cndmask_b32_e32 v5, v207, v5, vcc
	v_cmp_lt_f32_e64 vcc, |v58|, s91
	s_nop 1
	v_cndmask_b32_e32 v5, v5, v58, vcc
	v_cmp_lt_f32_e64 vcc, |v57|, s91
	s_nop 1
	v_cndmask_b32_e32 v4, v4, v57, vcc
	v_pk_add_f32 v[0:1], v[0:1], v[4:5] neg_lo:[0,1] neg_hi:[0,1]
	v_add_f32_e32 v5, 1.0, v42
	v_min_f32_e32 v4, 0, v6
	v_add_f32_e32 v6, -1.0, v5
	v_sub_f32_e32 v18, v6, v5
	v_add_f32_e32 v18, 1.0, v18
	v_sub_f32_e32 v6, v42, v6
	v_add_f32_e32 v20, v6, v18
	v_frexp_mant_f32_e32 v6, v5
	v_cmp_gt_f32_e32 vcc, s89, v6
	v_mul_f32_e64 v6, |v7|, s88
	v_cvt_f64_f32_e32 v[18:19], v5
	v_exp_f32_e32 v16, v6
	v_frexp_exp_i32_f64_e32 v18, v[18:19]
	v_subbrev_co_u32_e32 v36, vcc, 0, v18, vcc
	v_sub_u32_e32 v18, 0, v36
	v_ldexp_f32 v6, v5, v18
	v_min_f32_e32 v5, 0, v7
	v_add_f32_e32 v7, 1.0, v16
	v_add_f32_e32 v19, -1.0, v7
	v_ldexp_f32 v18, v20, v18
	v_sub_f32_e32 v20, v19, v7
	v_add_f32_e32 v20, 1.0, v20
	v_sub_f32_e32 v19, v16, v19
	v_add_f32_e32 v19, v19, v20
	v_frexp_mant_f32_e32 v22, v7
	v_cvt_f64_f32_e32 v[20:21], v7
	v_frexp_exp_i32_f64_e32 v20, v[20:21]
	v_cmp_gt_f32_e32 vcc, s89, v22
	s_nop 1
	v_subbrev_co_u32_e32 v37, vcc, 0, v20, vcc
	v_sub_u32_e32 v20, 0, v37
	v_ldexp_f32 v7, v7, v20
	v_ldexp_f32 v19, v19, v20
	v_pk_add_f32 v[20:21], v[6:7], 1.0 op_sel_hi:[1,0]
	v_pk_add_f32 v[28:29], v[6:7], -1.0 op_sel_hi:[1,0]
	v_pk_add_f32 v[22:23], v[20:21], -1.0 op_sel_hi:[1,0]
	v_pk_add_f32 v[30:31], v[28:29], 1.0 op_sel_hi:[1,0]
	v_pk_add_f32 v[22:23], v[6:7], v[22:23] neg_lo:[0,1] neg_hi:[0,1]
	v_pk_add_f32 v[6:7], v[6:7], v[30:31] neg_lo:[0,1] neg_hi:[0,1]
	v_pk_add_f32 v[22:23], v[18:19], v[22:23]
	v_pk_add_f32 v[6:7], v[18:19], v[6:7]
	v_pk_add_f32 v[24:25], v[20:21], v[22:23]
	v_pk_add_f32 v[18:19], v[28:29], v[6:7]
	v_rcp_f32_e32 v26, v24
	v_rcp_f32_e32 v27, v25
	v_pk_add_f32 v[20:21], v[24:25], v[20:21] neg_lo:[0,1] neg_hi:[0,1]
	v_pk_add_f32 v[28:29], v[18:19], v[28:29] neg_lo:[0,1] neg_hi:[0,1]
	v_pk_add_f32 v[20:21], v[22:23], v[20:21] neg_lo:[0,1] neg_hi:[0,1]
	v_pk_mul_f32 v[22:23], v[18:19], v[26:27]
	v_pk_add_f32 v[6:7], v[6:7], v[28:29] neg_lo:[0,1] neg_hi:[0,1]
	v_pk_mul_f32 v[28:29], v[24:25], v[22:23]
	v_cmp_neq_f32_e32 vcc, s90, v42
	v_pk_fma_f32 v[30:31], v[22:23], v[24:25], v[28:29] neg_lo:[0,0,1] neg_hi:[0,0,1]
	s_nop 0
	v_pk_fma_f32 v[30:31], v[22:23], v[20:21], v[30:31]
	s_nop 0
	v_pk_add_f32 v[32:33], v[28:29], v[30:31]
	s_nop 0
	v_pk_add_f32 v[34:35], v[18:19], v[32:33] neg_lo:[0,1] neg_hi:[0,1]
	v_pk_add_f32 v[28:29], v[32:33], v[28:29] neg_lo:[0,1] neg_hi:[0,1]
	v_pk_add_f32 v[18:19], v[18:19], v[34:35] neg_lo:[0,1] neg_hi:[0,1]
	s_nop 0
	v_pk_add_f32 v[18:19], v[18:19], v[32:33] neg_lo:[0,1] neg_hi:[0,1]
	s_nop 0
	v_pk_add_f32 v[6:7], v[6:7], v[18:19]
	v_pk_add_f32 v[18:19], v[28:29], v[30:31] neg_lo:[0,1] neg_hi:[0,1]
	s_nop 0
	v_pk_add_f32 v[6:7], v[18:19], v[6:7]
	s_nop 0
	v_pk_add_f32 v[18:19], v[34:35], v[6:7]
	s_nop 0
	v_pk_mul_f32 v[28:29], v[26:27], v[18:19]
	s_nop 0
	v_pk_mul_f32 v[30:31], v[24:25], v[28:29]
	s_nop 0
	v_pk_fma_f32 v[24:25], v[28:29], v[24:25], v[30:31] neg_lo:[0,0,1] neg_hi:[0,0,1]
	s_nop 0
	v_pk_fma_f32 v[20:21], v[28:29], v[20:21], v[24:25]
	v_pk_add_f32 v[24:25], v[34:35], v[18:19] neg_lo:[0,1] neg_hi:[0,1]
	s_nop 0
	v_pk_add_f32 v[6:7], v[6:7], v[24:25]
	v_pk_add_f32 v[24:25], v[30:31], v[20:21]
	s_nop 0
	v_pk_add_f32 v[32:33], v[18:19], v[24:25] neg_lo:[0,1] neg_hi:[0,1]
	v_pk_add_f32 v[30:31], v[24:25], v[30:31] neg_lo:[0,1] neg_hi:[0,1]
	v_pk_add_f32 v[18:19], v[18:19], v[32:33] neg_lo:[0,1] neg_hi:[0,1]
	s_nop 0
	v_pk_add_f32 v[18:19], v[18:19], v[24:25] neg_lo:[0,1] neg_hi:[0,1]
	v_cvt_f32_i32_e32 v25, v37
	v_pk_add_f32 v[6:7], v[6:7], v[18:19]
	v_pk_add_f32 v[18:19], v[30:31], v[20:21] neg_lo:[0,1] neg_hi:[0,1]
	v_cvt_f32_i32_e32 v24, v36
	v_pk_add_f32 v[6:7], v[18:19], v[6:7]
	v_pk_add_f32 v[18:19], v[22:23], v[28:29]
	v_pk_add_f32 v[6:7], v[32:33], v[6:7]
	v_pk_add_f32 v[20:21], v[18:19], v[22:23] neg_lo:[0,1] neg_hi:[0,1]
	v_pk_mul_f32 v[6:7], v[26:27], v[6:7]
	v_pk_add_f32 v[20:21], v[28:29], v[20:21] neg_lo:[0,1] neg_hi:[0,1]
	s_nop 0
	v_pk_add_f32 v[6:7], v[20:21], v[6:7]
	s_nop 0
	v_pk_add_f32 v[20:21], v[18:19], v[6:7]
	s_nop 0
	v_pk_mul_f32 v[22:23], v[20:21], v[20:21]
	v_pk_add_f32 v[18:19], v[20:21], v[18:19] neg_lo:[0,1] neg_hi:[0,1]
	v_pk_fma_f32 v[2:3], v[22:23], s[44:45], v[2:3] op_sel_hi:[1,0,0]
	v_pk_add_f32 v[6:7], v[6:7], v[18:19] neg_lo:[0,1] neg_hi:[0,1]
	v_ldexp_f32 v18, v20, 1
	v_pk_fma_f32 v[2:3], v[22:23], v[2:3], s[46:47] op_sel_hi:[1,1,0]
	v_ldexp_f32 v19, v21, 1
	v_pk_mul_f32 v[20:21], v[20:21], v[22:23]
	v_pk_mul_f32 v[22:23], v[24:25], s[48:49] op_sel_hi:[1,0]
	v_pk_mul_f32 v[2:3], v[20:21], v[2:3]
	v_pk_fma_f32 v[28:29], v[24:25], s[48:49], v[22:23] op_sel_hi:[1,0,1] neg_lo:[0,0,1] neg_hi:[0,0,1]
	v_pk_add_f32 v[20:21], v[18:19], v[2:3]
	v_ldexp_f32 v27, v7, 1
	v_pk_add_f32 v[18:19], v[20:21], v[18:19] neg_lo:[0,1] neg_hi:[0,1]
	v_pk_fma_f32 v[24:25], v[24:25], s[50:51], v[28:29] op_sel_hi:[1,0,1]
	v_pk_add_f32 v[2:3], v[2:3], v[18:19] neg_lo:[0,1] neg_hi:[0,1]
	v_ldexp_f32 v6, v6, 1
	v_mov_b32_e32 v18, v22
	v_mov_b32_e32 v19, v3
	v_mov_b32_e32 v26, v24
	v_mov_b32_e32 v7, v27
	v_pk_add_f32 v[18:19], v[18:19], v[26:27]
	v_pk_add_f32 v[26:27], v[6:7], v[2:3]
	v_mov_b32_e32 v3, v21
	v_mov_b32_e32 v7, v27
	v_pk_add_f32 v[28:29], v[22:23], v[24:25]
	v_pk_add_f32 v[2:3], v[6:7], v[2:3]
	v_pk_add_f32 v[6:7], v[20:21], v[26:27]
	v_mov_b32_e32 v38, v20
	v_pk_add_f32 v[30:31], v[28:29], v[6:7]
	v_mov_b32_e32 v36, v6
	v_mov_b32_e32 v37, v31
	v_mov_b32_e32 v39, v29
	v_pk_add_f32 v[36:37], v[36:37], v[38:39] neg_lo:[0,1] neg_hi:[0,1]
	v_mov_b32_e32 v32, v30
	v_mov_b32_e32 v33, v29
	v_mov_b32_e32 v34, v28
	v_mov_b32_e32 v35, v23
	v_mov_b32_e32 v38, v28
	v_mov_b32_e32 v39, v31
	v_mov_b32_e32 v23, v37
	v_pk_add_f32 v[32:33], v[32:33], v[34:35] neg_lo:[0,1] neg_hi:[0,1]
	v_mov_b32_e32 v34, v6
	v_mov_b32_e32 v35, v25
	v_pk_add_f32 v[22:23], v[38:39], v[22:23] neg_lo:[0,1] neg_hi:[0,1]
	v_pk_add_f32 v[34:35], v[34:35], v[32:33] neg_lo:[0,1] neg_hi:[0,1]
	v_mov_b32_e32 v38, v22
	v_mov_b32_e32 v39, v33
	v_mov_b32_e32 v40, v30
	v_mov_b32_e32 v41, v7
	v_mov_b32_e32 v33, v21
	v_pk_add_f32 v[38:39], v[24:25], v[38:39] neg_lo:[0,1] neg_hi:[0,1]
	v_pk_add_f32 v[32:33], v[40:41], v[32:33] neg_lo:[0,1] neg_hi:[0,1]
	v_mov_b32_e32 v25, v29
	v_pk_add_f32 v[6:7], v[6:7], v[20:21] neg_lo:[0,1] neg_hi:[0,1]
	v_pk_add_f32 v[18:19], v[18:19], v[32:33] neg_lo:[0,1] neg_hi:[0,1]
	v_pk_add_f32 v[20:21], v[24:25], v[22:23] neg_lo:[0,1] neg_hi:[0,1]
	v_pk_add_f32 v[2:3], v[2:3], v[36:37] neg_lo:[0,1] neg_hi:[0,1]
	v_pk_add_f32 v[24:25], v[34:35], v[18:19]
	v_pk_add_f32 v[22:23], v[2:3], v[20:21]
	v_mov_b32_e32 v21, v35
	v_mov_b32_e32 v3, v19
	v_pk_add_f32 v[2:3], v[20:21], v[2:3]
	v_mov_b32_e32 v18, v22
	v_pk_add_f32 v[2:3], v[2:3], v[38:39] neg_lo:[0,1] neg_hi:[0,1]
	v_mov_b32_e32 v19, v25
	v_pk_add_f32 v[6:7], v[26:27], v[6:7] neg_lo:[0,1] neg_hi:[0,1]
	v_pk_add_f32 v[18:19], v[18:19], v[2:3] neg_lo:[0,1] neg_hi:[0,1]
	v_pk_add_f32 v[2:3], v[6:7], v[2:3] neg_lo:[0,1] neg_hi:[0,1]
	v_pk_add_f32 v[18:19], v[20:21], v[18:19] neg_lo:[0,1] neg_hi:[0,1]
	v_pk_add_f32 v[6:7], v[24:25], v[22:23]
	v_pk_add_f32 v[2:3], v[2:3], v[18:19]
	v_pk_add_f32 v[18:19], v[30:31], v[6:7]
	s_nop 0
	v_pk_add_f32 v[20:21], v[18:19], v[30:31] neg_lo:[0,1] neg_hi:[0,1]
	s_nop 0
	v_pk_add_f32 v[6:7], v[6:7], v[20:21] neg_lo:[0,1] neg_hi:[0,1]
	s_nop 0
	v_pk_add_f32 v[2:3], v[2:3], v[6:7]
	s_nop 0
	v_pk_add_f32 v[2:3], v[18:19], v[2:3]
	s_nop 0
	v_cndmask_b32_e32 v2, v205, v2, vcc
	v_cmp_neq_f32_e32 vcc, s90, v16
	s_nop 1
	v_cndmask_b32_e32 v3, v205, v3, vcc
	v_cmp_ngt_f32_e32 vcc, -1.0, v16
	s_nop 1
	v_cndmask_b32_e32 v3, v206, v3, vcc
	v_cmp_ngt_f32_e32 vcc, -1.0, v42
	s_nop 1
	v_cndmask_b32_e32 v2, v206, v2, vcc
	v_cmp_neq_f32_e32 vcc, -1.0, v42
	s_nop 1
	v_cndmask_b32_e32 v2, v207, v2, vcc
	v_cmp_neq_f32_e32 vcc, -1.0, v16
	s_nop 1
	v_cndmask_b32_e32 v3, v207, v3, vcc
	v_cmp_lt_f32_e64 vcc, |v16|, s91
	s_nop 1
	v_cndmask_b32_e32 v3, v3, v16, vcc
	v_cmp_lt_f32_e64 vcc, |v42|, s91
	s_nop 1
	v_cndmask_b32_e32 v2, v2, v42, vcc
	v_pk_add_f32 v[2:3], v[4:5], v[2:3] neg_lo:[0,1] neg_hi:[0,1]
	v_lshl_or_b32 v4, v17, 3, v161
	v_ashrrev_i32_e32 v5, 31, v4
	v_lshlrev_b64 v[6:7], s53, v[4:5]
	v_lshl_add_u64 v[6:7], v[6:7], 2, s[78:79]
	v_lshl_add_u64 v[6:7], v[6:7], 0, v[152:153]
	s_and_b64 vcc, exec, s[6:7]
	v_mov_b32_e32 v5, s54
	global_store_dwordx4 v[6:7], v[0:3], off nt
	s_cbranch_vccnz .LBB0_252
	v_readlane_b32 s62, v250, 0
	v_readlane_b32 s63, v250, 1
	s_nop 1
	v_mov_b64_e32 v[6:7], s[62:63]
	v_mad_i64_i32 v[4:5], s[62:63], v4, s92, v[6:7]
	v_lshl_add_u64 v[4:5], v[4:5], 0, v[152:153]
	v_add_co_u32_e32 v4, vcc, 0x10c06000, v4
	s_nop 1
	v_addc_co_u32_e32 v5, vcc, 0, v5, vcc
	global_store_dwordx4 v[4:5], v[0:3], off offset:256 nt
	v_mov_b32_e32 v5, v197
.LBB0_252:
	global_load_dword v4, v[158:159], off
	v_or_b32_e32 v0, s55, v198
	v_cndmask_b32_e64 v52, v0, v182, s[4:5]
	v_mov_b64_e32 v[2:3], s[42:43]
	v_lshlrev_b32_e32 v152, 2, v52
	s_waitcnt vmcnt(0)
	v_add_f32_e32 v0, v8, v4
	v_mul_f32_e64 v6, |v0|, s88
	v_add_f32_e32 v1, v9, v4
	v_exp_f32_e32 v53, v6
	v_mul_f32_e64 v7, |v1|, s88
	v_exp_f32_e32 v54, v7
	v_min_f32_e32 v0, 0, v0
	v_add_f32_e32 v16, 1.0, v53
	v_frexp_mant_f32_e32 v19, v16
	v_cvt_f64_f32_e32 v[6:7], v16
	v_add_f32_e32 v17, 1.0, v54
	v_frexp_exp_i32_f64_e32 v6, v[6:7]
	v_cmp_gt_f32_e32 vcc, s89, v19
	v_add_f32_e32 v18, -1.0, v16
	v_add_f32_e32 v20, -1.0, v17
	v_frexp_mant_f32_e32 v21, v17
	v_cvt_f64_f32_e32 v[8:9], v17
	v_subbrev_co_u32_e32 v6, vcc, 0, v6, vcc
	v_sub_f32_e32 v22, v18, v16
	v_sub_f32_e32 v7, v20, v17
	v_frexp_exp_i32_f64_e32 v8, v[8:9]
	v_cmp_gt_f32_e32 vcc, s89, v21
	v_sub_f32_e32 v18, v53, v18
	v_sub_f32_e32 v20, v54, v20
	v_add_f32_e32 v9, 1.0, v22
	v_add_f32_e32 v7, 1.0, v7
	v_subbrev_co_u32_e32 v8, vcc, 0, v8, vcc
	v_add_f32_e32 v9, v18, v9
	v_sub_u32_e32 v18, 0, v6
	v_add_f32_e32 v19, v20, v7
	v_sub_u32_e32 v20, 0, v8
	v_cvt_f32_i32_e32 v7, v8
	v_cvt_f32_i32_e32 v6, v6
	v_ldexp_f32 v8, v16, v18
	v_ldexp_f32 v16, v9, v18
	v_ldexp_f32 v9, v17, v20
	v_ldexp_f32 v17, v19, v20
	v_pk_add_f32 v[18:19], v[8:9], 1.0 op_sel_hi:[1,0]
	v_pk_add_f32 v[20:21], v[8:9], -1.0 op_sel_hi:[1,0]
	v_pk_add_f32 v[22:23], v[18:19], -1.0 op_sel_hi:[1,0]
	v_pk_add_f32 v[24:25], v[20:21], 1.0 op_sel_hi:[1,0]
	v_pk_add_f32 v[22:23], v[8:9], v[22:23] neg_lo:[0,1] neg_hi:[0,1]
	v_pk_add_f32 v[8:9], v[8:9], v[24:25] neg_lo:[0,1] neg_hi:[0,1]
	v_pk_mul_f32 v[24:25], v[6:7], s[48:49] op_sel_hi:[1,0]
	v_pk_add_f32 v[22:23], v[16:17], v[22:23]
	v_pk_add_f32 v[8:9], v[16:17], v[8:9]
	v_pk_fma_f32 v[16:17], v[6:7], s[48:49], v[24:25] op_sel_hi:[1,0,1] neg_lo:[0,0,1] neg_hi:[0,0,1]
	v_pk_add_f32 v[30:31], v[18:19], v[22:23]
	v_pk_fma_f32 v[6:7], v[6:7], s[50:51], v[16:17] op_sel_hi:[1,0,1]
	v_rcp_f32_e32 v16, v30
	v_rcp_f32_e32 v17, v31
	v_pk_add_f32 v[32:33], v[20:21], v[8:9]
	v_pk_add_f32 v[18:19], v[30:31], v[18:19] neg_lo:[0,1] neg_hi:[0,1]
	v_pk_add_f32 v[20:21], v[32:33], v[20:21] neg_lo:[0,1] neg_hi:[0,1]
	v_pk_mul_f32 v[42:43], v[32:33], v[16:17]
	v_pk_add_f32 v[18:19], v[22:23], v[18:19] neg_lo:[0,1] neg_hi:[0,1]
	v_pk_mul_f32 v[44:45], v[30:31], v[42:43]
	v_pk_add_f32 v[8:9], v[8:9], v[20:21] neg_lo:[0,1] neg_hi:[0,1]
	v_pk_fma_f32 v[46:47], v[42:43], v[30:31], v[44:45] neg_lo:[0,0,1] neg_hi:[0,0,1]
	v_pk_add_f32 v[34:35], v[24:25], v[6:7]
	v_pk_fma_f32 v[46:47], v[42:43], v[18:19], v[46:47]
	v_mov_b32_e32 v26, v24
	v_pk_add_f32 v[48:49], v[44:45], v[46:47]
	v_mov_b32_e32 v36, v6
	v_pk_add_f32 v[50:51], v[32:33], v[48:49] neg_lo:[0,1] neg_hi:[0,1]
	v_pk_add_f32 v[44:45], v[48:49], v[44:45] neg_lo:[0,1] neg_hi:[0,1]
	v_pk_add_f32 v[32:33], v[32:33], v[50:51] neg_lo:[0,1] neg_hi:[0,1]
	v_pk_add_f32 v[44:45], v[44:45], v[46:47] neg_lo:[0,1] neg_hi:[0,1]
	v_pk_add_f32 v[32:33], v[32:33], v[48:49] neg_lo:[0,1] neg_hi:[0,1]
	v_mov_b32_e32 v23, v35
	v_pk_add_f32 v[8:9], v[8:9], v[32:33]
	v_mov_b32_e32 v29, v25
	v_pk_add_f32 v[8:9], v[44:45], v[8:9]
	v_mov_b32_e32 v21, v35
	v_pk_add_f32 v[32:33], v[50:51], v[8:9]
	v_mov_b32_e32 v28, v34
	v_pk_mul_f32 v[44:45], v[16:17], v[32:33]
	v_pk_add_f32 v[46:47], v[50:51], v[32:33] neg_lo:[0,1] neg_hi:[0,1]
	v_pk_mul_f32 v[48:49], v[30:31], v[44:45]
	v_pk_add_f32 v[8:9], v[8:9], v[46:47]
	v_pk_add_f32 v[46:47], v[42:43], v[44:45]
	v_pk_fma_f32 v[30:31], v[44:45], v[30:31], v[48:49] neg_lo:[0,0,1] neg_hi:[0,0,1]
	v_pk_add_f32 v[42:43], v[46:47], v[42:43] neg_lo:[0,1] neg_hi:[0,1]
	v_pk_fma_f32 v[18:19], v[44:45], v[18:19], v[30:31]
	v_pk_add_f32 v[30:31], v[44:45], v[42:43] neg_lo:[0,1] neg_hi:[0,1]
	v_pk_add_f32 v[42:43], v[48:49], v[18:19]
	v_mov_b32_e32 v40, v34
	v_pk_add_f32 v[44:45], v[42:43], v[48:49] neg_lo:[0,1] neg_hi:[0,1]
	v_pk_add_f32 v[48:49], v[32:33], v[42:43] neg_lo:[0,1] neg_hi:[0,1]
	v_pk_add_f32 v[18:19], v[44:45], v[18:19] neg_lo:[0,1] neg_hi:[0,1]
	v_pk_add_f32 v[32:33], v[32:33], v[48:49] neg_lo:[0,1] neg_hi:[0,1]
	v_mov_b32_e32 v39, v7
	v_pk_add_f32 v[32:33], v[32:33], v[42:43] neg_lo:[0,1] neg_hi:[0,1]
	v_cmp_neq_f32_e32 vcc, s90, v53
	v_pk_add_f32 v[8:9], v[8:9], v[32:33]
	v_min_f32_e32 v1, 0, v1
	v_pk_add_f32 v[8:9], v[18:19], v[8:9]
	s_nop 0
	v_pk_add_f32 v[8:9], v[48:49], v[8:9]
	s_nop 0
	v_pk_mul_f32 v[8:9], v[16:17], v[8:9]
	s_nop 0
	v_pk_add_f32 v[8:9], v[30:31], v[8:9]
	s_nop 0
	v_pk_add_f32 v[16:17], v[46:47], v[8:9]
	s_nop 0
	v_pk_add_f32 v[18:19], v[16:17], v[46:47] neg_lo:[0,1] neg_hi:[0,1]
	v_pk_mul_f32 v[32:33], v[16:17], v[16:17]
	v_pk_add_f32 v[8:9], v[8:9], v[18:19] neg_lo:[0,1] neg_hi:[0,1]
	v_pk_fma_f32 v[18:19], v[32:33], s[44:45], v[2:3] op_sel_hi:[1,0,0]
	v_ldexp_f32 v30, v16, 1
	v_ldexp_f32 v31, v17, 1
	v_pk_mul_f32 v[16:17], v[16:17], v[32:33]
	v_pk_fma_f32 v[18:19], v[32:33], v[18:19], s[46:47] op_sel_hi:[1,1,0]
	v_ldexp_f32 v37, v9, 1
	v_pk_mul_f32 v[16:17], v[16:17], v[18:19]
	v_ldexp_f32 v8, v8, 1
	v_pk_add_f32 v[18:19], v[30:31], v[16:17]
	v_mov_b32_e32 v9, v37
	v_pk_add_f32 v[30:31], v[18:19], v[30:31] neg_lo:[0,1] neg_hi:[0,1]
	v_mov_b32_e32 v22, v18
	v_pk_add_f32 v[16:17], v[16:17], v[30:31] neg_lo:[0,1] neg_hi:[0,1]
	s_nop 0
	v_pk_add_f32 v[30:31], v[8:9], v[16:17]
	v_mov_b32_e32 v27, v17
	v_mov_b32_e32 v17, v19
	v_mov_b32_e32 v9, v31
	v_pk_add_f32 v[32:33], v[18:19], v[30:31]
	v_pk_add_f32 v[8:9], v[8:9], v[16:17]
	v_pk_add_f32 v[16:17], v[34:35], v[32:33]
	v_pk_add_f32 v[26:27], v[26:27], v[36:37]
	v_mov_b32_e32 v36, v32
	v_mov_b32_e32 v37, v17
	v_pk_add_f32 v[22:23], v[36:37], v[22:23] neg_lo:[0,1] neg_hi:[0,1]
	v_mov_b32_e32 v20, v16
	v_mov_b32_e32 v41, v17
	v_mov_b32_e32 v25, v23
	v_mov_b32_e32 v38, v32
	v_pk_add_f32 v[20:21], v[20:21], v[28:29] neg_lo:[0,1] neg_hi:[0,1]
	v_pk_add_f32 v[24:25], v[40:41], v[24:25] neg_lo:[0,1] neg_hi:[0,1]
	v_pk_add_f32 v[28:29], v[38:39], v[20:21] neg_lo:[0,1] neg_hi:[0,1]
	v_mov_b32_e32 v36, v24
	v_mov_b32_e32 v37, v21
	v_mov_b32_e32 v38, v16
	v_mov_b32_e32 v39, v33
	v_mov_b32_e32 v21, v19
	v_pk_add_f32 v[36:37], v[6:7], v[36:37] neg_lo:[0,1] neg_hi:[0,1]
	v_pk_add_f32 v[20:21], v[38:39], v[20:21] neg_lo:[0,1] neg_hi:[0,1]
	v_mov_b32_e32 v7, v35
	v_pk_add_f32 v[20:21], v[26:27], v[20:21] neg_lo:[0,1] neg_hi:[0,1]
	v_pk_add_f32 v[6:7], v[6:7], v[24:25] neg_lo:[0,1] neg_hi:[0,1]
	v_pk_add_f32 v[8:9], v[8:9], v[22:23] neg_lo:[0,1] neg_hi:[0,1]
	v_pk_add_f32 v[24:25], v[28:29], v[20:21]
	v_pk_add_f32 v[22:23], v[8:9], v[6:7]
	v_mov_b32_e32 v7, v29
	v_mov_b32_e32 v9, v21
	v_pk_add_f32 v[8:9], v[6:7], v[8:9]
	v_pk_add_f32 v[18:19], v[32:33], v[18:19] neg_lo:[0,1] neg_hi:[0,1]
	v_pk_add_f32 v[8:9], v[8:9], v[36:37] neg_lo:[0,1] neg_hi:[0,1]
	v_mov_b32_e32 v20, v22
	v_mov_b32_e32 v21, v25
	v_pk_add_f32 v[18:19], v[30:31], v[18:19] neg_lo:[0,1] neg_hi:[0,1]
	v_pk_add_f32 v[20:21], v[20:21], v[8:9] neg_lo:[0,1] neg_hi:[0,1]
	v_pk_add_f32 v[8:9], v[18:19], v[8:9] neg_lo:[0,1] neg_hi:[0,1]
	v_pk_add_f32 v[6:7], v[6:7], v[20:21] neg_lo:[0,1] neg_hi:[0,1]
	s_nop 0
	v_pk_add_f32 v[6:7], v[8:9], v[6:7]
	v_pk_add_f32 v[8:9], v[24:25], v[22:23]
	s_nop 0
	v_pk_add_f32 v[18:19], v[16:17], v[8:9]
	s_nop 0
	v_pk_add_f32 v[16:17], v[18:19], v[16:17] neg_lo:[0,1] neg_hi:[0,1]
	s_nop 0
	v_pk_add_f32 v[8:9], v[8:9], v[16:17] neg_lo:[0,1] neg_hi:[0,1]
	s_nop 0
	v_pk_add_f32 v[6:7], v[6:7], v[8:9]
	v_add_f32_e32 v8, v10, v4
	v_pk_add_f32 v[6:7], v[18:19], v[6:7]
	v_mul_f32_e64 v9, |v8|, s88
	v_cndmask_b32_e32 v6, v205, v6, vcc
	v_cmp_neq_f32_e32 vcc, s90, v54
	v_exp_f32_e32 v38, v9
	v_add_f32_e32 v4, v11, v4
	v_cndmask_b32_e32 v7, v205, v7, vcc
	v_cmp_ngt_f32_e32 vcc, -1.0, v54
	s_nop 1
	v_cndmask_b32_e32 v7, v206, v7, vcc
	v_cmp_ngt_f32_e32 vcc, -1.0, v53
	s_nop 1
	v_cndmask_b32_e32 v6, v206, v6, vcc
	v_cmp_neq_f32_e32 vcc, -1.0, v53
	s_nop 1
	v_cndmask_b32_e32 v6, v207, v6, vcc
	v_cmp_neq_f32_e32 vcc, -1.0, v54
	s_nop 1
	v_cndmask_b32_e32 v7, v207, v7, vcc
	v_cmp_lt_f32_e64 vcc, |v54|, s91
	s_nop 1
	v_cndmask_b32_e32 v7, v7, v54, vcc
	v_cmp_lt_f32_e64 vcc, |v53|, s91
	s_nop 1
	v_cndmask_b32_e32 v6, v6, v53, vcc
	v_pk_add_f32 v[0:1], v[0:1], v[6:7] neg_lo:[0,1] neg_hi:[0,1]
	v_add_f32_e32 v7, 1.0, v38
	v_min_f32_e32 v6, 0, v8
	v_add_f32_e32 v8, -1.0, v7
	v_sub_f32_e32 v9, v8, v7
	v_add_f32_e32 v9, 1.0, v9
	v_sub_f32_e32 v8, v38, v8
	v_add_f32_e32 v10, v8, v9
	v_frexp_mant_f32_e32 v16, v7
	v_cvt_f64_f32_e32 v[8:9], v7
	v_frexp_exp_i32_f64_e32 v8, v[8:9]
	v_cmp_gt_f32_e32 vcc, s89, v16
	s_nop 1
	v_subbrev_co_u32_e32 v32, vcc, 0, v8, vcc
	v_mul_f32_e64 v8, |v4|, s88
	v_exp_f32_e32 v39, v8
	v_sub_u32_e32 v9, 0, v32
	v_ldexp_f32 v8, v7, v9
	v_min_f32_e32 v7, 0, v4
	v_add_f32_e32 v4, 1.0, v39
	v_ldexp_f32 v10, v10, v9
	v_add_f32_e32 v9, -1.0, v4
	v_sub_f32_e32 v11, v9, v4
	v_add_f32_e32 v11, 1.0, v11
	v_sub_f32_e32 v9, v39, v9
	v_add_f32_e32 v11, v9, v11
	v_frexp_mant_f32_e32 v9, v4
	v_cvt_f64_f32_e32 v[16:17], v4
	v_frexp_exp_i32_f64_e32 v16, v[16:17]
	v_cmp_gt_f32_e32 vcc, s89, v9
	s_nop 1
	v_subbrev_co_u32_e32 v33, vcc, 0, v16, vcc
	v_sub_u32_e32 v16, 0, v33
	v_ldexp_f32 v9, v4, v16
	v_ldexp_f32 v11, v11, v16
	v_pk_add_f32 v[16:17], v[8:9], 1.0 op_sel_hi:[1,0]
	v_pk_add_f32 v[24:25], v[8:9], -1.0 op_sel_hi:[1,0]
	v_pk_add_f32 v[18:19], v[16:17], -1.0 op_sel_hi:[1,0]
	v_pk_add_f32 v[26:27], v[24:25], 1.0 op_sel_hi:[1,0]
	v_pk_add_f32 v[18:19], v[8:9], v[18:19] neg_lo:[0,1] neg_hi:[0,1]
	v_pk_add_f32 v[8:9], v[8:9], v[26:27] neg_lo:[0,1] neg_hi:[0,1]
	v_pk_add_f32 v[18:19], v[10:11], v[18:19]
	v_pk_add_f32 v[8:9], v[10:11], v[8:9]
	v_pk_add_f32 v[20:21], v[16:17], v[18:19]
	v_pk_add_f32 v[10:11], v[24:25], v[8:9]
	v_rcp_f32_e32 v22, v20
	v_rcp_f32_e32 v23, v21
	v_pk_add_f32 v[16:17], v[20:21], v[16:17] neg_lo:[0,1] neg_hi:[0,1]
	v_pk_add_f32 v[24:25], v[10:11], v[24:25] neg_lo:[0,1] neg_hi:[0,1]
	v_pk_add_f32 v[16:17], v[18:19], v[16:17] neg_lo:[0,1] neg_hi:[0,1]
	v_pk_mul_f32 v[18:19], v[10:11], v[22:23]
	v_pk_add_f32 v[8:9], v[8:9], v[24:25] neg_lo:[0,1] neg_hi:[0,1]
	v_pk_mul_f32 v[24:25], v[20:21], v[18:19]
	v_cmp_neq_f32_e32 vcc, s90, v38
	v_pk_fma_f32 v[26:27], v[18:19], v[20:21], v[24:25] neg_lo:[0,0,1] neg_hi:[0,0,1]
	v_lshl_or_b32 v4, v5, 3, v161
	v_pk_fma_f32 v[26:27], v[18:19], v[16:17], v[26:27]
	v_ashrrev_i32_e32 v5, 31, v4
	v_pk_add_f32 v[28:29], v[24:25], v[26:27]
	s_nop 0
	v_pk_add_f32 v[30:31], v[10:11], v[28:29] neg_lo:[0,1] neg_hi:[0,1]
	v_pk_add_f32 v[24:25], v[28:29], v[24:25] neg_lo:[0,1] neg_hi:[0,1]
	v_pk_add_f32 v[10:11], v[10:11], v[30:31] neg_lo:[0,1] neg_hi:[0,1]
	s_nop 0
	v_pk_add_f32 v[10:11], v[10:11], v[28:29] neg_lo:[0,1] neg_hi:[0,1]
	s_nop 0
	v_pk_add_f32 v[8:9], v[8:9], v[10:11]
	v_pk_add_f32 v[10:11], v[24:25], v[26:27] neg_lo:[0,1] neg_hi:[0,1]
	s_nop 0
	v_pk_add_f32 v[8:9], v[10:11], v[8:9]
	s_nop 0
	v_pk_add_f32 v[10:11], v[30:31], v[8:9]
	s_nop 0
	v_pk_mul_f32 v[24:25], v[22:23], v[10:11]
	s_nop 0
	v_pk_mul_f32 v[26:27], v[20:21], v[24:25]
	s_nop 0
	v_pk_fma_f32 v[20:21], v[24:25], v[20:21], v[26:27] neg_lo:[0,0,1] neg_hi:[0,0,1]
	s_nop 0
	v_pk_fma_f32 v[16:17], v[24:25], v[16:17], v[20:21]
	v_pk_add_f32 v[20:21], v[30:31], v[10:11] neg_lo:[0,1] neg_hi:[0,1]
	s_nop 0
	v_pk_add_f32 v[8:9], v[8:9], v[20:21]
	v_pk_add_f32 v[20:21], v[26:27], v[16:17]
	s_nop 0
	v_pk_add_f32 v[28:29], v[10:11], v[20:21] neg_lo:[0,1] neg_hi:[0,1]
	v_pk_add_f32 v[26:27], v[20:21], v[26:27] neg_lo:[0,1] neg_hi:[0,1]
	v_pk_add_f32 v[10:11], v[10:11], v[28:29] neg_lo:[0,1] neg_hi:[0,1]
	s_nop 0
	v_pk_add_f32 v[10:11], v[10:11], v[20:21] neg_lo:[0,1] neg_hi:[0,1]
	v_cvt_f32_i32_e32 v21, v33
	v_pk_add_f32 v[8:9], v[8:9], v[10:11]
	v_pk_add_f32 v[10:11], v[26:27], v[16:17] neg_lo:[0,1] neg_hi:[0,1]
	v_cvt_f32_i32_e32 v20, v32
	v_pk_add_f32 v[8:9], v[10:11], v[8:9]
	v_pk_add_f32 v[10:11], v[18:19], v[24:25]
	v_pk_add_f32 v[8:9], v[28:29], v[8:9]
	v_pk_add_f32 v[16:17], v[10:11], v[18:19] neg_lo:[0,1] neg_hi:[0,1]
	v_pk_mul_f32 v[8:9], v[22:23], v[8:9]
	v_pk_add_f32 v[16:17], v[24:25], v[16:17] neg_lo:[0,1] neg_hi:[0,1]
	s_nop 0
	v_pk_add_f32 v[8:9], v[16:17], v[8:9]
	s_nop 0
	v_pk_add_f32 v[16:17], v[10:11], v[8:9]
	s_nop 0
	v_pk_mul_f32 v[18:19], v[16:17], v[16:17]
	v_pk_add_f32 v[10:11], v[16:17], v[10:11] neg_lo:[0,1] neg_hi:[0,1]
	v_pk_fma_f32 v[2:3], v[18:19], s[44:45], v[2:3] op_sel_hi:[1,0,0]
	v_pk_add_f32 v[8:9], v[8:9], v[10:11] neg_lo:[0,1] neg_hi:[0,1]
	v_ldexp_f32 v10, v16, 1
	v_pk_fma_f32 v[2:3], v[18:19], v[2:3], s[46:47] op_sel_hi:[1,1,0]
	v_ldexp_f32 v11, v17, 1
	v_pk_mul_f32 v[16:17], v[16:17], v[18:19]
	v_pk_mul_f32 v[18:19], v[20:21], s[48:49] op_sel_hi:[1,0]
	v_pk_mul_f32 v[2:3], v[16:17], v[2:3]
	v_pk_fma_f32 v[24:25], v[20:21], s[48:49], v[18:19] op_sel_hi:[1,0,1] neg_lo:[0,0,1] neg_hi:[0,0,1]
	v_pk_add_f32 v[16:17], v[10:11], v[2:3]
	v_ldexp_f32 v23, v9, 1
	v_pk_add_f32 v[10:11], v[16:17], v[10:11] neg_lo:[0,1] neg_hi:[0,1]
	v_pk_fma_f32 v[20:21], v[20:21], s[50:51], v[24:25] op_sel_hi:[1,0,1]
	v_pk_add_f32 v[2:3], v[2:3], v[10:11] neg_lo:[0,1] neg_hi:[0,1]
	v_ldexp_f32 v8, v8, 1
	v_mov_b32_e32 v10, v18
	v_mov_b32_e32 v11, v3
	v_mov_b32_e32 v22, v20
	v_mov_b32_e32 v9, v23
	v_pk_add_f32 v[10:11], v[10:11], v[22:23]
	v_pk_add_f32 v[22:23], v[8:9], v[2:3]
	v_mov_b32_e32 v3, v17
	v_mov_b32_e32 v9, v23
	v_pk_add_f32 v[24:25], v[18:19], v[20:21]
	v_pk_add_f32 v[2:3], v[8:9], v[2:3]
	v_pk_add_f32 v[8:9], v[16:17], v[22:23]
	v_mov_b32_e32 v34, v16
	v_pk_add_f32 v[26:27], v[24:25], v[8:9]
	v_mov_b32_e32 v32, v8
	v_mov_b32_e32 v33, v27
	v_mov_b32_e32 v35, v25
	v_pk_add_f32 v[32:33], v[32:33], v[34:35] neg_lo:[0,1] neg_hi:[0,1]
	v_mov_b32_e32 v28, v26
	v_mov_b32_e32 v29, v25
	v_mov_b32_e32 v30, v24
	v_mov_b32_e32 v31, v19
	v_mov_b32_e32 v34, v24
	v_mov_b32_e32 v35, v27
	v_mov_b32_e32 v19, v33
	v_pk_add_f32 v[28:29], v[28:29], v[30:31] neg_lo:[0,1] neg_hi:[0,1]
	v_mov_b32_e32 v30, v8
	v_mov_b32_e32 v31, v21
	v_pk_add_f32 v[18:19], v[34:35], v[18:19] neg_lo:[0,1] neg_hi:[0,1]
	v_pk_add_f32 v[30:31], v[30:31], v[28:29] neg_lo:[0,1] neg_hi:[0,1]
	v_mov_b32_e32 v34, v18
	v_mov_b32_e32 v35, v29
	v_mov_b32_e32 v36, v26
	v_mov_b32_e32 v37, v9
	v_mov_b32_e32 v29, v17
	v_pk_add_f32 v[34:35], v[20:21], v[34:35] neg_lo:[0,1] neg_hi:[0,1]
	v_pk_add_f32 v[28:29], v[36:37], v[28:29] neg_lo:[0,1] neg_hi:[0,1]
	v_mov_b32_e32 v21, v25
	v_pk_add_f32 v[8:9], v[8:9], v[16:17] neg_lo:[0,1] neg_hi:[0,1]
	v_pk_add_f32 v[10:11], v[10:11], v[28:29] neg_lo:[0,1] neg_hi:[0,1]
	v_pk_add_f32 v[16:17], v[20:21], v[18:19] neg_lo:[0,1] neg_hi:[0,1]
	v_pk_add_f32 v[2:3], v[2:3], v[32:33] neg_lo:[0,1] neg_hi:[0,1]
	v_pk_add_f32 v[20:21], v[30:31], v[10:11]
	v_pk_add_f32 v[18:19], v[2:3], v[16:17]
	v_mov_b32_e32 v17, v31
	v_mov_b32_e32 v3, v11
	v_pk_add_f32 v[2:3], v[16:17], v[2:3]
	v_mov_b32_e32 v10, v18
	v_pk_add_f32 v[2:3], v[2:3], v[34:35] neg_lo:[0,1] neg_hi:[0,1]
	v_mov_b32_e32 v11, v21
	v_pk_add_f32 v[8:9], v[22:23], v[8:9] neg_lo:[0,1] neg_hi:[0,1]
	v_pk_add_f32 v[10:11], v[10:11], v[2:3] neg_lo:[0,1] neg_hi:[0,1]
	v_pk_add_f32 v[2:3], v[8:9], v[2:3] neg_lo:[0,1] neg_hi:[0,1]
	v_pk_add_f32 v[10:11], v[16:17], v[10:11] neg_lo:[0,1] neg_hi:[0,1]
	v_pk_add_f32 v[8:9], v[20:21], v[18:19]
	v_pk_add_f32 v[2:3], v[2:3], v[10:11]
	v_pk_add_f32 v[10:11], v[26:27], v[8:9]
	s_nop 0
	v_pk_add_f32 v[16:17], v[10:11], v[26:27] neg_lo:[0,1] neg_hi:[0,1]
	s_nop 0
	v_pk_add_f32 v[8:9], v[8:9], v[16:17] neg_lo:[0,1] neg_hi:[0,1]
	s_nop 0
	v_pk_add_f32 v[2:3], v[2:3], v[8:9]
	s_nop 0
	v_pk_add_f32 v[2:3], v[10:11], v[2:3]
	s_nop 0
	v_cndmask_b32_e32 v2, v205, v2, vcc
	v_cmp_neq_f32_e32 vcc, s90, v39
	s_nop 1
	v_cndmask_b32_e32 v3, v205, v3, vcc
	v_cmp_ngt_f32_e32 vcc, -1.0, v39
	s_nop 1
	v_cndmask_b32_e32 v3, v206, v3, vcc
	v_cmp_ngt_f32_e32 vcc, -1.0, v38
	s_nop 1
	v_cndmask_b32_e32 v2, v206, v2, vcc
	v_cmp_neq_f32_e32 vcc, -1.0, v38
	s_nop 1
	v_cndmask_b32_e32 v2, v207, v2, vcc
	v_cmp_neq_f32_e32 vcc, -1.0, v39
	s_nop 1
	v_cndmask_b32_e32 v3, v207, v3, vcc
	v_cmp_lt_f32_e64 vcc, |v39|, s91
	s_nop 1
	v_cndmask_b32_e32 v3, v3, v39, vcc
	v_cmp_lt_f32_e64 vcc, |v38|, s91
	s_nop 1
	v_cndmask_b32_e32 v2, v2, v38, vcc
	v_pk_add_f32 v[2:3], v[6:7], v[2:3] neg_lo:[0,1] neg_hi:[0,1]
	v_lshlrev_b64 v[6:7], s53, v[4:5]
	v_lshl_add_u64 v[6:7], v[6:7], 2, s[78:79]
	v_lshl_add_u64 v[6:7], v[6:7], 0, v[152:153]
	s_and_b64 vcc, exec, s[6:7]
	v_mov_b32_e32 v5, s54
	global_store_dwordx4 v[6:7], v[0:3], off nt
	s_cbranch_vccnz .LBB0_254
	v_readlane_b32 s62, v250, 0
	v_readlane_b32 s63, v250, 1
	s_nop 1
	v_mov_b64_e32 v[6:7], s[62:63]
	v_mad_i64_i32 v[4:5], s[62:63], v4, s92, v[6:7]
	v_lshl_add_u64 v[4:5], v[4:5], 0, v[152:153]
	v_add_co_u32_e32 v4, vcc, 0x10c06000, v4
	s_nop 1
	v_addc_co_u32_e32 v5, vcc, 0, v5, vcc
	global_store_dwordx4 v[4:5], v[0:3], off offset:256 nt
	v_mov_b32_e32 v5, v199
.LBB0_254:
	global_load_dword v4, v[158:159], off
	v_or_b32_e32 v0, s55, v200
	v_cndmask_b32_e64 v48, v0, v189, s[4:5]
	v_mov_b64_e32 v[2:3], s[42:43]
	v_lshlrev_b32_e32 v152, 2, v48
	s_waitcnt vmcnt(0)
	v_add_f32_e32 v0, v12, v4
	v_mul_f32_e64 v6, |v0|, s88
	v_add_f32_e32 v1, v13, v4
	v_exp_f32_e32 v49, v6
	v_mul_f32_e64 v7, |v1|, s88
	v_exp_f32_e32 v50, v7
	v_min_f32_e32 v0, 0, v0
	v_add_f32_e32 v10, 1.0, v49
	v_frexp_mant_f32_e32 v13, v10
	v_cvt_f64_f32_e32 v[6:7], v10
	v_add_f32_e32 v11, 1.0, v50
	v_frexp_exp_i32_f64_e32 v6, v[6:7]
	v_cmp_gt_f32_e32 vcc, s89, v13
	v_add_f32_e32 v12, -1.0, v10
	v_add_f32_e32 v16, -1.0, v11
	v_frexp_mant_f32_e32 v17, v11
	v_cvt_f64_f32_e32 v[8:9], v11
	v_subbrev_co_u32_e32 v6, vcc, 0, v6, vcc
	v_sub_f32_e32 v18, v12, v10
	v_sub_f32_e32 v7, v16, v11
	v_frexp_exp_i32_f64_e32 v8, v[8:9]
	v_cmp_gt_f32_e32 vcc, s89, v17
	v_sub_f32_e32 v12, v49, v12
	v_sub_f32_e32 v16, v50, v16
	v_add_f32_e32 v9, 1.0, v18
	v_add_f32_e32 v7, 1.0, v7
	v_subbrev_co_u32_e32 v8, vcc, 0, v8, vcc
	v_add_f32_e32 v9, v12, v9
	v_sub_u32_e32 v12, 0, v6
	v_add_f32_e32 v13, v16, v7
	v_sub_u32_e32 v16, 0, v8
	v_cvt_f32_i32_e32 v7, v8
	v_cvt_f32_i32_e32 v6, v6
	v_ldexp_f32 v8, v10, v12
	v_ldexp_f32 v10, v9, v12
	v_ldexp_f32 v9, v11, v16
	v_ldexp_f32 v11, v13, v16
	v_pk_add_f32 v[12:13], v[8:9], 1.0 op_sel_hi:[1,0]
	v_pk_add_f32 v[16:17], v[8:9], -1.0 op_sel_hi:[1,0]
	v_pk_add_f32 v[18:19], v[12:13], -1.0 op_sel_hi:[1,0]
	v_pk_add_f32 v[20:21], v[16:17], 1.0 op_sel_hi:[1,0]
	v_pk_add_f32 v[18:19], v[8:9], v[18:19] neg_lo:[0,1] neg_hi:[0,1]
	v_pk_add_f32 v[8:9], v[8:9], v[20:21] neg_lo:[0,1] neg_hi:[0,1]
	v_pk_mul_f32 v[20:21], v[6:7], s[48:49] op_sel_hi:[1,0]
	v_pk_add_f32 v[18:19], v[10:11], v[18:19]
	v_pk_add_f32 v[8:9], v[10:11], v[8:9]
	v_pk_fma_f32 v[10:11], v[6:7], s[48:49], v[20:21] op_sel_hi:[1,0,1] neg_lo:[0,0,1] neg_hi:[0,0,1]
	v_pk_add_f32 v[26:27], v[12:13], v[18:19]
	v_pk_fma_f32 v[6:7], v[6:7], s[50:51], v[10:11] op_sel_hi:[1,0,1]
	v_rcp_f32_e32 v10, v26
	v_rcp_f32_e32 v11, v27
	v_pk_add_f32 v[28:29], v[16:17], v[8:9]
	v_pk_add_f32 v[12:13], v[26:27], v[12:13] neg_lo:[0,1] neg_hi:[0,1]
	v_pk_add_f32 v[16:17], v[28:29], v[16:17] neg_lo:[0,1] neg_hi:[0,1]
	v_pk_mul_f32 v[38:39], v[28:29], v[10:11]
	v_pk_add_f32 v[12:13], v[18:19], v[12:13] neg_lo:[0,1] neg_hi:[0,1]
	v_pk_mul_f32 v[40:41], v[26:27], v[38:39]
	v_pk_add_f32 v[8:9], v[8:9], v[16:17] neg_lo:[0,1] neg_hi:[0,1]
	v_pk_fma_f32 v[42:43], v[38:39], v[26:27], v[40:41] neg_lo:[0,0,1] neg_hi:[0,0,1]
	v_pk_add_f32 v[30:31], v[20:21], v[6:7]
	v_pk_fma_f32 v[42:43], v[38:39], v[12:13], v[42:43]
	v_mov_b32_e32 v22, v20
	v_pk_add_f32 v[44:45], v[40:41], v[42:43]
	v_mov_b32_e32 v32, v6
	v_pk_add_f32 v[46:47], v[28:29], v[44:45] neg_lo:[0,1] neg_hi:[0,1]
	v_pk_add_f32 v[40:41], v[44:45], v[40:41] neg_lo:[0,1] neg_hi:[0,1]
	v_pk_add_f32 v[28:29], v[28:29], v[46:47] neg_lo:[0,1] neg_hi:[0,1]
	v_pk_add_f32 v[40:41], v[40:41], v[42:43] neg_lo:[0,1] neg_hi:[0,1]
	v_pk_add_f32 v[28:29], v[28:29], v[44:45] neg_lo:[0,1] neg_hi:[0,1]
	v_mov_b32_e32 v19, v31
	v_pk_add_f32 v[8:9], v[8:9], v[28:29]
	v_mov_b32_e32 v25, v21
	v_pk_add_f32 v[8:9], v[40:41], v[8:9]
	v_mov_b32_e32 v17, v31
	v_pk_add_f32 v[28:29], v[46:47], v[8:9]
	v_mov_b32_e32 v24, v30
	v_pk_mul_f32 v[40:41], v[10:11], v[28:29]
	v_pk_add_f32 v[42:43], v[46:47], v[28:29] neg_lo:[0,1] neg_hi:[0,1]
	v_pk_mul_f32 v[44:45], v[26:27], v[40:41]
	v_pk_add_f32 v[8:9], v[8:9], v[42:43]
	v_pk_add_f32 v[42:43], v[38:39], v[40:41]
	v_pk_fma_f32 v[26:27], v[40:41], v[26:27], v[44:45] neg_lo:[0,0,1] neg_hi:[0,0,1]
	v_pk_add_f32 v[38:39], v[42:43], v[38:39] neg_lo:[0,1] neg_hi:[0,1]
	v_pk_fma_f32 v[12:13], v[40:41], v[12:13], v[26:27]
	v_pk_add_f32 v[26:27], v[40:41], v[38:39] neg_lo:[0,1] neg_hi:[0,1]
	v_pk_add_f32 v[38:39], v[44:45], v[12:13]
	v_mov_b32_e32 v36, v30
	v_pk_add_f32 v[40:41], v[38:39], v[44:45] neg_lo:[0,1] neg_hi:[0,1]
	v_pk_add_f32 v[44:45], v[28:29], v[38:39] neg_lo:[0,1] neg_hi:[0,1]
	v_pk_add_f32 v[12:13], v[40:41], v[12:13] neg_lo:[0,1] neg_hi:[0,1]
	v_pk_add_f32 v[28:29], v[28:29], v[44:45] neg_lo:[0,1] neg_hi:[0,1]
	v_mov_b32_e32 v35, v7
	v_pk_add_f32 v[28:29], v[28:29], v[38:39] neg_lo:[0,1] neg_hi:[0,1]
	v_cmp_neq_f32_e32 vcc, s90, v49
	v_pk_add_f32 v[8:9], v[8:9], v[28:29]
	v_min_f32_e32 v1, 0, v1
	v_pk_add_f32 v[8:9], v[12:13], v[8:9]
	s_nop 0
	v_pk_add_f32 v[8:9], v[44:45], v[8:9]
	s_nop 0
	v_pk_mul_f32 v[8:9], v[10:11], v[8:9]
	s_nop 0
	v_pk_add_f32 v[8:9], v[26:27], v[8:9]
	s_nop 0
	v_pk_add_f32 v[10:11], v[42:43], v[8:9]
	s_nop 0
	v_pk_add_f32 v[12:13], v[10:11], v[42:43] neg_lo:[0,1] neg_hi:[0,1]
	v_pk_mul_f32 v[28:29], v[10:11], v[10:11]
	v_pk_add_f32 v[8:9], v[8:9], v[12:13] neg_lo:[0,1] neg_hi:[0,1]
	v_pk_fma_f32 v[12:13], v[28:29], s[44:45], v[2:3] op_sel_hi:[1,0,0]
	v_ldexp_f32 v26, v10, 1
	v_ldexp_f32 v27, v11, 1
	v_pk_mul_f32 v[10:11], v[10:11], v[28:29]
	v_pk_fma_f32 v[12:13], v[28:29], v[12:13], s[46:47] op_sel_hi:[1,1,0]
	v_ldexp_f32 v33, v9, 1
	v_pk_mul_f32 v[10:11], v[10:11], v[12:13]
	v_ldexp_f32 v8, v8, 1
	v_pk_add_f32 v[12:13], v[26:27], v[10:11]
	v_mov_b32_e32 v9, v33
	v_pk_add_f32 v[26:27], v[12:13], v[26:27] neg_lo:[0,1] neg_hi:[0,1]
	v_mov_b32_e32 v18, v12
	v_pk_add_f32 v[10:11], v[10:11], v[26:27] neg_lo:[0,1] neg_hi:[0,1]
	s_nop 0
	v_pk_add_f32 v[26:27], v[8:9], v[10:11]
	v_mov_b32_e32 v23, v11
	v_mov_b32_e32 v11, v13
	v_mov_b32_e32 v9, v27
	v_pk_add_f32 v[28:29], v[12:13], v[26:27]
	v_pk_add_f32 v[8:9], v[8:9], v[10:11]
	v_pk_add_f32 v[10:11], v[30:31], v[28:29]
	v_pk_add_f32 v[22:23], v[22:23], v[32:33]
	v_mov_b32_e32 v32, v28
	v_mov_b32_e32 v33, v11
	v_pk_add_f32 v[18:19], v[32:33], v[18:19] neg_lo:[0,1] neg_hi:[0,1]
	v_mov_b32_e32 v16, v10
	v_mov_b32_e32 v37, v11
	v_mov_b32_e32 v21, v19
	v_mov_b32_e32 v34, v28
	v_pk_add_f32 v[16:17], v[16:17], v[24:25] neg_lo:[0,1] neg_hi:[0,1]
	v_pk_add_f32 v[20:21], v[36:37], v[20:21] neg_lo:[0,1] neg_hi:[0,1]
	v_pk_add_f32 v[24:25], v[34:35], v[16:17] neg_lo:[0,1] neg_hi:[0,1]
	v_mov_b32_e32 v32, v20
	v_mov_b32_e32 v33, v17
	v_mov_b32_e32 v34, v10
	v_mov_b32_e32 v35, v29
	v_mov_b32_e32 v17, v13
	v_pk_add_f32 v[32:33], v[6:7], v[32:33] neg_lo:[0,1] neg_hi:[0,1]
	v_pk_add_f32 v[16:17], v[34:35], v[16:17] neg_lo:[0,1] neg_hi:[0,1]
	v_mov_b32_e32 v7, v31
	v_pk_add_f32 v[16:17], v[22:23], v[16:17] neg_lo:[0,1] neg_hi:[0,1]
	v_pk_add_f32 v[6:7], v[6:7], v[20:21] neg_lo:[0,1] neg_hi:[0,1]
	v_pk_add_f32 v[8:9], v[8:9], v[18:19] neg_lo:[0,1] neg_hi:[0,1]
	v_pk_add_f32 v[20:21], v[24:25], v[16:17]
	v_pk_add_f32 v[18:19], v[8:9], v[6:7]
	v_mov_b32_e32 v7, v25
	v_mov_b32_e32 v9, v17
	v_pk_add_f32 v[8:9], v[6:7], v[8:9]
	v_pk_add_f32 v[12:13], v[28:29], v[12:13] neg_lo:[0,1] neg_hi:[0,1]
	v_pk_add_f32 v[8:9], v[8:9], v[32:33] neg_lo:[0,1] neg_hi:[0,1]
	v_mov_b32_e32 v16, v18
	v_mov_b32_e32 v17, v21
	v_pk_add_f32 v[12:13], v[26:27], v[12:13] neg_lo:[0,1] neg_hi:[0,1]
	v_pk_add_f32 v[16:17], v[16:17], v[8:9] neg_lo:[0,1] neg_hi:[0,1]
	v_pk_add_f32 v[8:9], v[12:13], v[8:9] neg_lo:[0,1] neg_hi:[0,1]
	v_pk_add_f32 v[6:7], v[6:7], v[16:17] neg_lo:[0,1] neg_hi:[0,1]
	s_nop 0
	v_pk_add_f32 v[6:7], v[8:9], v[6:7]
	v_pk_add_f32 v[8:9], v[20:21], v[18:19]
	s_nop 0
	v_pk_add_f32 v[12:13], v[10:11], v[8:9]
	s_nop 0
	v_pk_add_f32 v[10:11], v[12:13], v[10:11] neg_lo:[0,1] neg_hi:[0,1]
	s_nop 0
	v_pk_add_f32 v[8:9], v[8:9], v[10:11] neg_lo:[0,1] neg_hi:[0,1]
	s_nop 0
	v_pk_add_f32 v[6:7], v[6:7], v[8:9]
	v_add_f32_e32 v8, v14, v4
	v_pk_add_f32 v[6:7], v[12:13], v[6:7]
	v_mul_f32_e64 v9, |v8|, s88
	v_cndmask_b32_e32 v6, v205, v6, vcc
	v_cmp_neq_f32_e32 vcc, s90, v50
	v_exp_f32_e32 v34, v9
	v_add_f32_e32 v4, v15, v4
	v_cndmask_b32_e32 v7, v205, v7, vcc
	v_cmp_ngt_f32_e32 vcc, -1.0, v50
	s_nop 1
	v_cndmask_b32_e32 v7, v206, v7, vcc
	v_cmp_ngt_f32_e32 vcc, -1.0, v49
	s_nop 1
	v_cndmask_b32_e32 v6, v206, v6, vcc
	v_cmp_neq_f32_e32 vcc, -1.0, v49
	s_nop 1
	v_cndmask_b32_e32 v6, v207, v6, vcc
	v_cmp_neq_f32_e32 vcc, -1.0, v50
	s_nop 1
	v_cndmask_b32_e32 v7, v207, v7, vcc
	v_cmp_lt_f32_e64 vcc, |v50|, s91
	s_nop 1
	v_cndmask_b32_e32 v7, v7, v50, vcc
	v_cmp_lt_f32_e64 vcc, |v49|, s91
	s_nop 1
	v_cndmask_b32_e32 v6, v6, v49, vcc
	v_pk_add_f32 v[0:1], v[0:1], v[6:7] neg_lo:[0,1] neg_hi:[0,1]
	v_add_f32_e32 v7, 1.0, v34
	v_min_f32_e32 v6, 0, v8
	v_add_f32_e32 v8, -1.0, v7
	v_sub_f32_e32 v9, v8, v7
	v_add_f32_e32 v9, 1.0, v9
	v_sub_f32_e32 v8, v34, v8
	v_add_f32_e32 v10, v8, v9
	v_frexp_mant_f32_e32 v11, v7
	v_cvt_f64_f32_e32 v[8:9], v7
	v_frexp_exp_i32_f64_e32 v8, v[8:9]
	v_cmp_gt_f32_e32 vcc, s89, v11
	s_nop 1
	v_subbrev_co_u32_e32 v28, vcc, 0, v8, vcc
	v_mul_f32_e64 v8, |v4|, s88
	v_exp_f32_e32 v35, v8
	v_sub_u32_e32 v9, 0, v28
	v_ldexp_f32 v8, v7, v9
	v_min_f32_e32 v7, 0, v4
	v_add_f32_e32 v4, 1.0, v35
	v_ldexp_f32 v10, v10, v9
	v_add_f32_e32 v9, -1.0, v4
	v_sub_f32_e32 v11, v9, v4
	v_add_f32_e32 v11, 1.0, v11
	v_sub_f32_e32 v9, v35, v9
	v_add_f32_e32 v11, v9, v11
	v_frexp_mant_f32_e32 v9, v4
	v_cvt_f64_f32_e32 v[12:13], v4
	v_frexp_exp_i32_f64_e32 v12, v[12:13]
	v_cmp_gt_f32_e32 vcc, s89, v9
	s_nop 1
	v_subbrev_co_u32_e32 v29, vcc, 0, v12, vcc
	v_sub_u32_e32 v12, 0, v29
	v_ldexp_f32 v9, v4, v12
	v_ldexp_f32 v11, v11, v12
	v_pk_add_f32 v[12:13], v[8:9], 1.0 op_sel_hi:[1,0]
	v_pk_add_f32 v[20:21], v[8:9], -1.0 op_sel_hi:[1,0]
	v_pk_add_f32 v[14:15], v[12:13], -1.0 op_sel_hi:[1,0]
	v_pk_add_f32 v[22:23], v[20:21], 1.0 op_sel_hi:[1,0]
	v_pk_add_f32 v[14:15], v[8:9], v[14:15] neg_lo:[0,1] neg_hi:[0,1]
	v_pk_add_f32 v[8:9], v[8:9], v[22:23] neg_lo:[0,1] neg_hi:[0,1]
	v_pk_add_f32 v[14:15], v[10:11], v[14:15]
	v_pk_add_f32 v[8:9], v[10:11], v[8:9]
	v_pk_add_f32 v[16:17], v[12:13], v[14:15]
	v_pk_add_f32 v[10:11], v[20:21], v[8:9]
	v_rcp_f32_e32 v18, v16
	v_rcp_f32_e32 v19, v17
	v_pk_add_f32 v[12:13], v[16:17], v[12:13] neg_lo:[0,1] neg_hi:[0,1]
	v_pk_add_f32 v[20:21], v[10:11], v[20:21] neg_lo:[0,1] neg_hi:[0,1]
	v_pk_add_f32 v[12:13], v[14:15], v[12:13] neg_lo:[0,1] neg_hi:[0,1]
	v_pk_mul_f32 v[14:15], v[10:11], v[18:19]
	v_pk_add_f32 v[8:9], v[8:9], v[20:21] neg_lo:[0,1] neg_hi:[0,1]
	v_pk_mul_f32 v[20:21], v[16:17], v[14:15]
	v_cmp_neq_f32_e32 vcc, s90, v34
	v_pk_fma_f32 v[22:23], v[14:15], v[16:17], v[20:21] neg_lo:[0,0,1] neg_hi:[0,0,1]
	v_lshl_or_b32 v4, v5, 3, v161
	v_pk_fma_f32 v[22:23], v[14:15], v[12:13], v[22:23]
	v_ashrrev_i32_e32 v5, 31, v4
	v_pk_add_f32 v[24:25], v[20:21], v[22:23]
	s_nop 0
	v_pk_add_f32 v[26:27], v[10:11], v[24:25] neg_lo:[0,1] neg_hi:[0,1]
	v_pk_add_f32 v[20:21], v[24:25], v[20:21] neg_lo:[0,1] neg_hi:[0,1]
	v_pk_add_f32 v[10:11], v[10:11], v[26:27] neg_lo:[0,1] neg_hi:[0,1]
	s_nop 0
	v_pk_add_f32 v[10:11], v[10:11], v[24:25] neg_lo:[0,1] neg_hi:[0,1]
	s_nop 0
	v_pk_add_f32 v[8:9], v[8:9], v[10:11]
	v_pk_add_f32 v[10:11], v[20:21], v[22:23] neg_lo:[0,1] neg_hi:[0,1]
	s_nop 0
	v_pk_add_f32 v[8:9], v[10:11], v[8:9]
	s_nop 0
	v_pk_add_f32 v[10:11], v[26:27], v[8:9]
	s_nop 0
	v_pk_mul_f32 v[20:21], v[18:19], v[10:11]
	s_nop 0
	v_pk_mul_f32 v[22:23], v[16:17], v[20:21]
	s_nop 0
	v_pk_fma_f32 v[16:17], v[20:21], v[16:17], v[22:23] neg_lo:[0,0,1] neg_hi:[0,0,1]
	s_nop 0
	v_pk_fma_f32 v[12:13], v[20:21], v[12:13], v[16:17]
	v_pk_add_f32 v[16:17], v[26:27], v[10:11] neg_lo:[0,1] neg_hi:[0,1]
	s_nop 0
	v_pk_add_f32 v[8:9], v[8:9], v[16:17]
	v_pk_add_f32 v[16:17], v[22:23], v[12:13]
	s_nop 0
	v_pk_add_f32 v[24:25], v[10:11], v[16:17] neg_lo:[0,1] neg_hi:[0,1]
	v_pk_add_f32 v[22:23], v[16:17], v[22:23] neg_lo:[0,1] neg_hi:[0,1]
	v_pk_add_f32 v[10:11], v[10:11], v[24:25] neg_lo:[0,1] neg_hi:[0,1]
	s_nop 0
	v_pk_add_f32 v[10:11], v[10:11], v[16:17] neg_lo:[0,1] neg_hi:[0,1]
	v_cvt_f32_i32_e32 v17, v29
	v_pk_add_f32 v[8:9], v[8:9], v[10:11]
	v_pk_add_f32 v[10:11], v[22:23], v[12:13] neg_lo:[0,1] neg_hi:[0,1]
	v_cvt_f32_i32_e32 v16, v28
	v_pk_add_f32 v[8:9], v[10:11], v[8:9]
	v_pk_add_f32 v[10:11], v[14:15], v[20:21]
	v_pk_add_f32 v[8:9], v[24:25], v[8:9]
	v_pk_add_f32 v[12:13], v[10:11], v[14:15] neg_lo:[0,1] neg_hi:[0,1]
	v_pk_mul_f32 v[8:9], v[18:19], v[8:9]
	v_pk_add_f32 v[12:13], v[20:21], v[12:13] neg_lo:[0,1] neg_hi:[0,1]
	s_nop 0
	v_pk_add_f32 v[8:9], v[12:13], v[8:9]
	s_nop 0
	v_pk_add_f32 v[12:13], v[10:11], v[8:9]
	s_nop 0
	v_pk_mul_f32 v[14:15], v[12:13], v[12:13]
	v_pk_add_f32 v[10:11], v[12:13], v[10:11] neg_lo:[0,1] neg_hi:[0,1]
	v_pk_fma_f32 v[2:3], v[14:15], s[44:45], v[2:3] op_sel_hi:[1,0,0]
	v_pk_add_f32 v[8:9], v[8:9], v[10:11] neg_lo:[0,1] neg_hi:[0,1]
	v_ldexp_f32 v10, v12, 1
	v_pk_fma_f32 v[2:3], v[14:15], v[2:3], s[46:47] op_sel_hi:[1,1,0]
	v_ldexp_f32 v11, v13, 1
	v_pk_mul_f32 v[12:13], v[12:13], v[14:15]
	v_pk_mul_f32 v[14:15], v[16:17], s[48:49] op_sel_hi:[1,0]
	v_pk_mul_f32 v[2:3], v[12:13], v[2:3]
	v_pk_fma_f32 v[20:21], v[16:17], s[48:49], v[14:15] op_sel_hi:[1,0,1] neg_lo:[0,0,1] neg_hi:[0,0,1]
	v_pk_add_f32 v[12:13], v[10:11], v[2:3]
	v_ldexp_f32 v19, v9, 1
	v_pk_add_f32 v[10:11], v[12:13], v[10:11] neg_lo:[0,1] neg_hi:[0,1]
	v_pk_fma_f32 v[16:17], v[16:17], s[50:51], v[20:21] op_sel_hi:[1,0,1]
	v_pk_add_f32 v[2:3], v[2:3], v[10:11] neg_lo:[0,1] neg_hi:[0,1]
	v_ldexp_f32 v8, v8, 1
	v_mov_b32_e32 v10, v14
	v_mov_b32_e32 v11, v3
	v_mov_b32_e32 v18, v16
	v_mov_b32_e32 v9, v19
	v_pk_add_f32 v[10:11], v[10:11], v[18:19]
	v_pk_add_f32 v[18:19], v[8:9], v[2:3]
	v_mov_b32_e32 v3, v13
	v_mov_b32_e32 v9, v19
	v_pk_add_f32 v[20:21], v[14:15], v[16:17]
	v_pk_add_f32 v[2:3], v[8:9], v[2:3]
	v_pk_add_f32 v[8:9], v[12:13], v[18:19]
	v_mov_b32_e32 v30, v12
	v_pk_add_f32 v[22:23], v[20:21], v[8:9]
	v_mov_b32_e32 v28, v8
	v_mov_b32_e32 v29, v23
	v_mov_b32_e32 v31, v21
	v_pk_add_f32 v[28:29], v[28:29], v[30:31] neg_lo:[0,1] neg_hi:[0,1]
	v_mov_b32_e32 v24, v22
	v_mov_b32_e32 v25, v21
	v_mov_b32_e32 v26, v20
	v_mov_b32_e32 v27, v15
	v_mov_b32_e32 v30, v20
	v_mov_b32_e32 v31, v23
	v_mov_b32_e32 v15, v29
	v_pk_add_f32 v[24:25], v[24:25], v[26:27] neg_lo:[0,1] neg_hi:[0,1]
	v_mov_b32_e32 v26, v8
	v_mov_b32_e32 v27, v17
	v_pk_add_f32 v[14:15], v[30:31], v[14:15] neg_lo:[0,1] neg_hi:[0,1]
	v_pk_add_f32 v[26:27], v[26:27], v[24:25] neg_lo:[0,1] neg_hi:[0,1]
	v_mov_b32_e32 v30, v14
	v_mov_b32_e32 v31, v25
	v_mov_b32_e32 v32, v22
	v_mov_b32_e32 v33, v9
	v_mov_b32_e32 v25, v13
	v_pk_add_f32 v[30:31], v[16:17], v[30:31] neg_lo:[0,1] neg_hi:[0,1]
	v_pk_add_f32 v[24:25], v[32:33], v[24:25] neg_lo:[0,1] neg_hi:[0,1]
	v_mov_b32_e32 v17, v21
	v_pk_add_f32 v[8:9], v[8:9], v[12:13] neg_lo:[0,1] neg_hi:[0,1]
	v_pk_add_f32 v[10:11], v[10:11], v[24:25] neg_lo:[0,1] neg_hi:[0,1]
	v_pk_add_f32 v[12:13], v[16:17], v[14:15] neg_lo:[0,1] neg_hi:[0,1]
	v_pk_add_f32 v[2:3], v[2:3], v[28:29] neg_lo:[0,1] neg_hi:[0,1]
	v_pk_add_f32 v[16:17], v[26:27], v[10:11]
	v_pk_add_f32 v[14:15], v[2:3], v[12:13]
	v_mov_b32_e32 v13, v27
	v_mov_b32_e32 v3, v11
	v_pk_add_f32 v[2:3], v[12:13], v[2:3]
	v_mov_b32_e32 v10, v14
	v_pk_add_f32 v[2:3], v[2:3], v[30:31] neg_lo:[0,1] neg_hi:[0,1]
	v_mov_b32_e32 v11, v17
	v_pk_add_f32 v[8:9], v[18:19], v[8:9] neg_lo:[0,1] neg_hi:[0,1]
	v_pk_add_f32 v[10:11], v[10:11], v[2:3] neg_lo:[0,1] neg_hi:[0,1]
	v_pk_add_f32 v[2:3], v[8:9], v[2:3] neg_lo:[0,1] neg_hi:[0,1]
	v_pk_add_f32 v[10:11], v[12:13], v[10:11] neg_lo:[0,1] neg_hi:[0,1]
	v_pk_add_f32 v[8:9], v[16:17], v[14:15]
	v_pk_add_f32 v[2:3], v[2:3], v[10:11]
	v_pk_add_f32 v[10:11], v[22:23], v[8:9]
	s_nop 0
	v_pk_add_f32 v[12:13], v[10:11], v[22:23] neg_lo:[0,1] neg_hi:[0,1]
	s_nop 0
	v_pk_add_f32 v[8:9], v[8:9], v[12:13] neg_lo:[0,1] neg_hi:[0,1]
	s_nop 0
	v_pk_add_f32 v[2:3], v[2:3], v[8:9]
	s_nop 0
	v_pk_add_f32 v[2:3], v[10:11], v[2:3]
	s_nop 0
	v_cndmask_b32_e32 v2, v205, v2, vcc
	v_cmp_neq_f32_e32 vcc, s90, v35
	s_nop 1
	v_cndmask_b32_e32 v3, v205, v3, vcc
	v_cmp_ngt_f32_e32 vcc, -1.0, v35
	s_nop 1
	v_cndmask_b32_e32 v3, v206, v3, vcc
	v_cmp_ngt_f32_e32 vcc, -1.0, v34
	s_nop 1
	v_cndmask_b32_e32 v2, v206, v2, vcc
	v_cmp_neq_f32_e32 vcc, -1.0, v34
	s_nop 1
	v_cndmask_b32_e32 v2, v207, v2, vcc
	v_cmp_neq_f32_e32 vcc, -1.0, v35
	s_nop 1
	v_cndmask_b32_e32 v3, v207, v3, vcc
	v_cmp_lt_f32_e64 vcc, |v35|, s91
	s_nop 1
	v_cndmask_b32_e32 v3, v3, v35, vcc
	v_cmp_lt_f32_e64 vcc, |v34|, s91
	s_nop 1
	v_cndmask_b32_e32 v2, v2, v34, vcc
	v_pk_add_f32 v[2:3], v[6:7], v[2:3] neg_lo:[0,1] neg_hi:[0,1]
	v_lshlrev_b64 v[6:7], s53, v[4:5]
	v_lshl_add_u64 v[6:7], v[6:7], 2, s[78:79]
	v_lshl_add_u64 v[6:7], v[6:7], 0, v[152:153]
	s_and_b64 vcc, exec, s[6:7]
	global_store_dwordx4 v[6:7], v[0:3], off nt
	s_cbranch_vccnz .LBB0_256
	v_readlane_b32 s4, v250, 0
	v_readlane_b32 s5, v250, 1
	s_nop 1
	v_mov_b64_e32 v[6:7], s[4:5]
	v_mad_i64_i32 v[4:5], s[4:5], v4, s92, v[6:7]
	v_lshl_add_u64 v[4:5], v[4:5], 0, v[152:153]
	v_add_co_u32_e32 v4, vcc, 0x10c06000, v4
	s_nop 1
	v_addc_co_u32_e32 v5, vcc, 0, v5, vcc
	global_store_dwordx4 v[4:5], v[0:3], off offset:256 nt

.LBB0_277:
	s_or_b64 exec, exec, s[84:85]
	s_and_b64 s[52:53], s[4:5], exec
	v_readlane_b32 s84, v250, 10
	s_mov_b32 s52, 0x18201000
	v_readlane_b32 s86, v250, 12
	v_readlane_b32 s87, v250, 13
	s_cselect_b32 s52, s52, 0x10180000
	s_mov_b64 s[54:55], s[86:87]
	v_readlane_b32 s85, v250, 11
	s_add_u32 s84, s54, s52
	s_addc_u32 s85, s55, 0
	s_and_b64 s[52:53], s[4:5], exec
	s_cselect_b32 s52, 4, 13
	s_lshl_b32 s53, s76, 7
	s_and_b32 s53, s53, 0x1f80
	v_ashrrev_i32_e32 v138, 7, v138
	v_or_b32_e32 v128, s53, v133
	v_cndmask_b32_e64 v152, v128, v134, s[4:5]
	v_lshl_add_u32 v128, v139, 2, v138
	v_mul_f32_e32 v139, v49, v49
	v_fmac_f32_e32 v139, v48, v48
	v_fmac_f32_e32 v139, v50, v50
	v_fmac_f32_e32 v139, v51, v51
	v_fmac_f32_e32 v139, v52, v52
	v_fmac_f32_e32 v139, v53, v53
	v_fmac_f32_e32 v139, v54, v54
	v_fmac_f32_e32 v139, v55, v55
	v_fmac_f32_e32 v139, v56, v56
	v_fmac_f32_e32 v139, v57, v57
	v_fmac_f32_e32 v139, v58, v58
	v_fmac_f32_e32 v139, v59, v59
	v_fmac_f32_e32 v139, v60, v60
	v_fmac_f32_e32 v139, v61, v61
	v_fmac_f32_e32 v139, v62, v62
	v_fmac_f32_e32 v139, v63, v63
	v_fmac_f32_e32 v139, v32, v32
	v_fmac_f32_e32 v139, v33, v33
	v_fmac_f32_e32 v139, v34, v34
	v_fmac_f32_e32 v139, v35, v35
	v_fmac_f32_e32 v139, v36, v36
	v_fmac_f32_e32 v139, v37, v37
	v_fmac_f32_e32 v139, v38, v38
	v_ashrrev_i32_e32 v129, 31, v128
	v_fmac_f32_e32 v139, v39, v39
	s_waitcnt lgkmcnt(0)
	v_lshlrev_b64 v[140:141], s52, v[128:129]
	v_fmac_f32_e32 v139, v40, v40
	v_lshl_add_u64 v[140:141], v[140:141], 0, v[152:153]
	s_waitcnt vmcnt(1)
	v_lshlrev_b32_e32 v144, 8, v152
	v_add_u32_e32 v152, 0x800, v152
	v_fmac_f32_e32 v139, v41, v41
	v_lshlrev_b64 v[142:143], 21, v[128:129]
	v_mad_i64_i32 v[128:129], s[54:55], v128, s95, v[152:153]
	v_fmac_f32_e32 v139, v42, v42
	v_lshlrev_b64 v[140:141], 9, v[140:141]
	v_lshl_add_u64 v[142:143], s[22:23], 0, v[142:143]
	v_mov_b32_e32 v145, v153
	v_lshlrev_b64 v[128:129], 8, v[128:129]
	v_fmac_f32_e32 v139, v43, v43
	v_lshl_add_u64 v[140:141], s[84:85], 0, v[140:141]
	v_lshl_add_u64 v[144:145], v[142:143], 0, v[144:145]
	v_lshl_add_u64 v[128:129], s[24:25], 0, v[128:129]
	v_lshlrev_b32_e32 v152, 4, v211
	v_fmac_f32_e32 v139, v44, v44
	v_lshl_add_u64 v[146:147], v[140:141], 0, v[152:153]
	v_cvt_pk_bf16_f32 v140, v112, v113
	v_cvt_pk_bf16_f32 v141, v114, v115
	v_cvt_pk_bf16_f32 v142, v116, v117
	v_cvt_pk_bf16_f32 v143, v118, v119
	v_cndmask_b32_e64 v129, v145, v129, s[4:5]
	v_cndmask_b32_e64 v128, v144, v128, s[4:5]
	v_fmac_f32_e32 v139, v45, v45
	v_permlane32_swap_b32_e32 v140, v142
	v_permlane32_swap_b32_e32 v141, v143
	v_lshl_add_u64 v[128:129], v[128:129], 0, v[152:153]
	v_fmac_f32_e32 v139, v46, v46
	global_store_dwordx4 v[146:147], v[112:115], off nt
	global_store_dwordx4 v[146:147], v[116:119], off offset:32 nt
	global_store_dwordx4 v[146:147], v[120:123], off offset:64 nt
	global_store_dwordx4 v[146:147], v[124:127], off offset:96 nt
	global_store_dwordx4 v[128:129], v[140:143], off
	v_fmac_f32_e32 v139, v47, v47
	ds_bpermute_b32 v144, v130, v139
	v_cvt_pk_bf16_f32 v140, v120, v121
	v_cvt_pk_bf16_f32 v141, v122, v123
	v_cvt_pk_bf16_f32 v142, v124, v125
	v_cvt_pk_bf16_f32 v143, v126, v127
	s_nop 0
	v_permlane32_swap_b32_e32 v140, v142
	v_permlane32_swap_b32_e32 v141, v143
	global_store_dwordx4 v[128:129], v[140:143], off offset:32
	global_store_dwordx4 v[146:147], v[96:99], off offset:128 nt
	global_store_dwordx4 v[146:147], v[100:103], off offset:160 nt
	global_store_dwordx4 v[146:147], v[104:107], off offset:192 nt
	global_store_dwordx4 v[146:147], v[108:111], off offset:224 nt
	v_cvt_pk_bf16_f32 v140, v96, v97
	v_cvt_pk_bf16_f32 v141, v98, v99
	v_cvt_pk_bf16_f32 v142, v100, v101
	v_cvt_pk_bf16_f32 v143, v102, v103
	s_nop 0
	v_permlane32_swap_b32_e32 v140, v142
	v_permlane32_swap_b32_e32 v141, v143
	global_store_dwordx4 v[128:129], v[140:143], off offset:64
	s_waitcnt lgkmcnt(0)
	v_add_f32_e32 v139, v139, v144
	ds_bpermute_b32 v144, v131, v139
	v_cvt_pk_bf16_f32 v140, v104, v105
	v_cvt_pk_bf16_f32 v141, v106, v107
	v_cvt_pk_bf16_f32 v142, v108, v109
	v_cvt_pk_bf16_f32 v143, v110, v111
	s_nop 0
	v_permlane32_swap_b32_e32 v140, v142
	v_permlane32_swap_b32_e32 v141, v143
	global_store_dwordx4 v[128:129], v[140:143], off offset:96
	global_store_dwordx4 v[146:147], v[80:83], off offset:256 nt
	global_store_dwordx4 v[146:147], v[84:87], off offset:288 nt
	global_store_dwordx4 v[146:147], v[88:91], off offset:320 nt
	global_store_dwordx4 v[146:147], v[92:95], off offset:352 nt
	v_cvt_pk_bf16_f32 v140, v80, v81
	v_cvt_pk_bf16_f32 v141, v82, v83
	v_cvt_pk_bf16_f32 v142, v84, v85
	v_cvt_pk_bf16_f32 v143, v86, v87
	s_nop 0
	v_permlane32_swap_b32_e32 v140, v142
	v_permlane32_swap_b32_e32 v141, v143
	global_store_dwordx4 v[128:129], v[140:143], off offset:128
	v_or_b32_e32 v133, 32, v133
	s_nop 0
	v_cvt_pk_bf16_f32 v140, v88, v89
	v_cvt_pk_bf16_f32 v141, v90, v91
	v_cvt_pk_bf16_f32 v142, v92, v93
	v_cvt_pk_bf16_f32 v143, v94, v95
	s_nop 0
	v_permlane32_swap_b32_e32 v140, v142
	v_permlane32_swap_b32_e32 v141, v143
	global_store_dwordx4 v[128:129], v[140:143], off offset:160
	global_store_dwordx4 v[146:147], v[64:67], off offset:384 nt
	global_store_dwordx4 v[146:147], v[68:71], off offset:416 nt
	global_store_dwordx4 v[146:147], v[72:75], off offset:448 nt
	global_store_dwordx4 v[146:147], v[76:79], off offset:480 nt
	v_cvt_pk_bf16_f32 v140, v64, v65
	v_cvt_pk_bf16_f32 v141, v66, v67
	v_cvt_pk_bf16_f32 v142, v68, v69
	v_cvt_pk_bf16_f32 v143, v70, v71
	s_nop 0
	v_permlane32_swap_b32_e32 v140, v142
	v_permlane32_swap_b32_e32 v141, v143
	global_store_dwordx4 v[128:129], v[140:143], off offset:192
	s_waitcnt lgkmcnt(0)
	s_nop 0
	v_max_f32_e32 v142, v144, v144
	v_max_f32_e32 v139, v139, v142
	ds_bpermute_b32 v144, v132, v139
	v_cvt_pk_bf16_f32 v140, v72, v73
	v_cvt_pk_bf16_f32 v141, v74, v75
	v_cvt_pk_bf16_f32 v142, v76, v77
	v_cvt_pk_bf16_f32 v143, v78, v79
	s_waitcnt lgkmcnt(0)
	v_max_f32_e32 v144, v144, v144
	v_max_f32_e32 v139, v139, v144
	ds_bpermute_b32 v144, v135, v139
	v_permlane32_swap_b32_e32 v140, v142
	v_permlane32_swap_b32_e32 v141, v143
	global_store_dwordx4 v[128:129], v[140:143], off offset:224
	s_waitcnt lgkmcnt(0)
	v_max_f32_e32 v129, v144, v144
	v_lshrrev_b32_e32 v128, 4, v133
	v_max_f32_e32 v140, v139, v129
	ds_bpermute_b32 v141, v136, v140
	v_mov_b32_e32 v129, s34
	v_cndmask_b32_e64 v139, v129, v128, s[4:5]
	v_lshl_add_u32 v128, v139, 3, v137
	v_ashrrev_i32_e32 v129, 31, v128
	s_and_saveexec_b64 s[86:87], s[6:7]
	s_cbranch_execz .LBB0_279
	s_waitcnt lgkmcnt(0)
	v_max_f32_e32 v137, v141, v141
	v_max_f32_e32 v140, v140, v140
	v_lshl_add_u64 v[142:143], v[128:129], 2, s[36:37]
	v_max_f32_e32 v137, v140, v137
	global_atomic_umax v[142:143], v137, off

.LBB0_281:
	s_or_b64 exec, exec, s[86:87]
	v_or_b32_e32 v128, s53, v133
	v_cndmask_b32_e64 v152, v128, v134, s[4:5]
	v_lshl_add_u32 v128, v139, 2, v138
	v_ashrrev_i32_e32 v129, 31, v128
	s_waitcnt lgkmcnt(0)
	v_lshlrev_b64 v[130:131], s52, v[128:129]
	v_lshl_add_u64 v[130:131], v[130:131], 0, v[152:153]
	v_lshlrev_b32_e32 v134, 8, v152
	v_add_u32_e32 v152, 0x800, v152
	v_lshlrev_b64 v[132:133], 21, v[128:129]
	v_mad_i64_i32 v[128:129], s[6:7], v128, s95, v[152:153]
	v_lshlrev_b32_e32 v136, 2, v211
	v_lshlrev_b64 v[130:131], 9, v[130:131]
	v_lshl_add_u64 v[132:133], s[22:23], 0, v[132:133]
	v_mov_b32_e32 v135, v153
	v_lshlrev_b64 v[128:129], 8, v[128:129]
	v_lshlrev_b32_e32 v140, 3, v211
	v_lshl_add_u64 v[130:131], s[84:85], 0, v[130:131]
	v_lshl_add_u64 v[132:133], v[132:133], 0, v[134:135]
	v_lshl_add_u64 v[134:135], s[24:25], 0, v[128:129]
	v_lshlrev_b32_e32 v152, 2, v136
	v_lshl_add_u64 v[136:137], v[130:131], 0, v[152:153]
	v_cvt_pk_bf16_f32 v128, v48, v49
	v_cvt_pk_bf16_f32 v129, v50, v51
	v_cvt_pk_bf16_f32 v130, v52, v53
	v_cvt_pk_bf16_f32 v131, v54, v55
	v_cndmask_b32_e64 v133, v133, v135, s[4:5]
	v_cndmask_b32_e64 v132, v132, v134, s[4:5]
	v_lshlrev_b32_e32 v152, 1, v140
	v_permlane32_swap_b32_e32 v128, v130
	v_permlane32_swap_b32_e32 v129, v131
	v_lshl_add_u64 v[132:133], v[132:133], 0, v[152:153]
	global_store_dwordx4 v[136:137], v[48:51], off nt
	global_store_dwordx4 v[136:137], v[52:55], off offset:32 nt
	global_store_dwordx4 v[136:137], v[56:59], off offset:64 nt
	global_store_dwordx4 v[136:137], v[60:63], off offset:96 nt
	global_store_dwordx4 v[132:133], v[128:131], off
	s_mov_b64 s[4:5], 0
	s_nop 0
	v_cvt_pk_bf16_f32 v128, v56, v57
	v_cvt_pk_bf16_f32 v129, v58, v59
	v_cvt_pk_bf16_f32 v130, v60, v61
	v_cvt_pk_bf16_f32 v131, v62, v63
	s_nop 0
	v_permlane32_swap_b32_e32 v128, v130
	v_permlane32_swap_b32_e32 v129, v131
	global_store_dwordx4 v[132:133], v[128:131], off offset:32
	global_store_dwordx4 v[136:137], v[32:35], off offset:128 nt
	global_store_dwordx4 v[136:137], v[36:39], off offset:160 nt
	global_store_dwordx4 v[136:137], v[40:43], off offset:192 nt
	global_store_dwordx4 v[136:137], v[44:47], off offset:224 nt
	v_cvt_pk_bf16_f32 v128, v32, v33
	v_cvt_pk_bf16_f32 v129, v34, v35
	v_cvt_pk_bf16_f32 v130, v36, v37
	v_cvt_pk_bf16_f32 v131, v38, v39
	s_nop 0
	v_permlane32_swap_b32_e32 v128, v130
	v_permlane32_swap_b32_e32 v129, v131
	global_store_dwordx4 v[132:133], v[128:131], off offset:64
	s_nop 1
	v_cvt_pk_bf16_f32 v128, v40, v41
	v_cvt_pk_bf16_f32 v129, v42, v43
	v_cvt_pk_bf16_f32 v130, v44, v45
	v_cvt_pk_bf16_f32 v131, v46, v47
	s_nop 0
	v_permlane32_swap_b32_e32 v128, v130
	v_permlane32_swap_b32_e32 v129, v131
	global_store_dwordx4 v[132:133], v[128:131], off offset:96
	global_store_dwordx4 v[136:137], v[16:19], off offset:256 nt
	global_store_dwordx4 v[136:137], v[20:23], off offset:288 nt
	global_store_dwordx4 v[136:137], v[24:27], off offset:320 nt
	global_store_dwordx4 v[136:137], v[28:31], off offset:352 nt
	v_cvt_pk_bf16_f32 v128, v16, v17
	v_cvt_pk_bf16_f32 v129, v18, v19
	v_cvt_pk_bf16_f32 v130, v20, v21
	v_cvt_pk_bf16_f32 v131, v22, v23
	s_nop 0
	v_permlane32_swap_b32_e32 v128, v130
	v_permlane32_swap_b32_e32 v129, v131
	global_store_dwordx4 v[132:133], v[128:131], off offset:128
	s_nop 1
	v_cvt_pk_bf16_f32 v128, v24, v25
	v_cvt_pk_bf16_f32 v129, v26, v27
	v_cvt_pk_bf16_f32 v130, v28, v29
	v_cvt_pk_bf16_f32 v131, v30, v31
	s_nop 0
	v_permlane32_swap_b32_e32 v128, v130
	v_permlane32_swap_b32_e32 v129, v131
	global_store_dwordx4 v[132:133], v[128:131], off offset:160
	global_store_dwordx4 v[136:137], v[0:3], off offset:384 nt
	global_store_dwordx4 v[136:137], v[4:7], off offset:416 nt
	global_store_dwordx4 v[136:137], v[8:11], off offset:448 nt
	global_store_dwordx4 v[136:137], v[12:15], off offset:480 nt
	v_cvt_pk_bf16_f32 v128, v0, v1
	v_cvt_pk_bf16_f32 v129, v2, v3
	v_cvt_pk_bf16_f32 v130, v4, v5
	v_cvt_pk_bf16_f32 v131, v6, v7
	s_nop 0
	v_permlane32_swap_b32_e32 v128, v130
	v_permlane32_swap_b32_e32 v129, v131
	global_store_dwordx4 v[132:133], v[128:131], off offset:192
	s_nop 1
	v_cvt_pk_bf16_f32 v128, v8, v9
	v_cvt_pk_bf16_f32 v129, v10, v11
	v_cvt_pk_bf16_f32 v130, v12, v13
	v_cvt_pk_bf16_f32 v131, v14, v15
	s_nop 0
	v_permlane32_swap_b32_e32 v128, v130
	v_permlane32_swap_b32_e32 v129, v131
	global_store_dwordx4 v[132:133], v[128:131], off offset:224

.LBB0_298:
	s_or_b64 exec, exec, s[0:1]
	v_readlane_b32 s84, v250, 10
	s_and_b64 s[0:1], vcc, exec
	v_readlane_b32 s86, v250, 12
	v_readlane_b32 s87, v250, 13
	s_cselect_b32 s0, s97, 0x8080000
	s_mov_b64 s[6:7], s[86:87]
	s_add_u32 s0, s6, s0
	s_addc_u32 s1, s7, 0
	s_and_b64 s[6:7], vcc, exec
	s_cselect_b32 s34, 4, 13
	s_lshl_b32 s6, s76, 7
	s_and_b32 s54, s6, 0x1f80
	v_or_b32_e32 v129, s54, v138
	v_cndmask_b32_e32 v152, v129, v139, vcc
	v_lshlrev_b32_e32 v130, 7, v152
	v_mov_b32_e32 v131, v153
	s_waitcnt vmcnt(0)
	v_lshl_add_u64 v[150:151], s[38:39], 0, v[130:131]
	v_add_u32_e32 v130, v145, v140
	v_ashrrev_i32_e32 v131, 31, v130
	s_waitcnt lgkmcnt(0)
	v_lshlrev_b64 v[132:133], s34, v[130:131]
	v_lshl_add_u64 v[132:133], v[132:133], 0, v[152:153]
	v_lshlrev_b64 v[132:133], 8, v[132:133]
	v_add_u32_e32 v214, 0x800, v152
	v_mov_b32_e32 v215, v153
	v_lshl_add_u64 v[146:147], s[0:1], 0, v[132:133]
	v_lshlrev_b32_e32 v132, 4, v211
	v_mov_b32_e32 v133, v153
	v_lshl_add_u64 v[216:217], v[146:147], 0, v[132:133]
	v_lshlrev_b64 v[146:147], 20, v[130:131]
	v_mad_i64_i32 v[130:131], s[6:7], v130, s95, v[214:215]
	v_lshlrev_b64 v[130:131], 7, v[130:131]
	v_lshl_add_u64 v[218:219], v[150:151], 0, v[146:147]
	v_lshl_add_u64 v[130:131], s[40:41], 0, v[130:131]
	v_cvt_pk_bf16_f32 v146, v112, v113
	v_cvt_pk_bf16_f32 v147, v114, v115
	v_cvt_pk_bf16_f32 v148, v116, v117
	v_cvt_pk_bf16_f32 v149, v118, v119
	v_cndmask_b32_e32 v131, v219, v131, vcc
	v_cndmask_b32_e32 v130, v218, v130, vcc
	v_permlane32_swap_b32_e32 v146, v148
	v_permlane32_swap_b32_e32 v147, v149
	v_lshl_add_u64 v[130:131], v[130:131], 0, v[132:133]
	global_store_dwordx4 v[216:217], v[112:115], off nt
	global_store_dwordx4 v[216:217], v[116:119], off offset:32 nt
	global_store_dwordx4 v[216:217], v[120:123], off offset:64 nt
	global_store_dwordx4 v[216:217], v[124:127], off offset:96 nt
	global_store_dwordx4 v[130:131], v[146:149], off
	v_lshlrev_b32_e32 v143, 3, v211
	v_add_u32_e32 v144, v128, v143
	v_cvt_pk_bf16_f32 v146, v120, v121
	v_cvt_pk_bf16_f32 v147, v122, v123
	v_cvt_pk_bf16_f32 v148, v124, v125
	v_cvt_pk_bf16_f32 v149, v126, v127
	s_nop 0
	v_permlane32_swap_b32_e32 v146, v148
	v_permlane32_swap_b32_e32 v147, v149
	global_store_dwordx4 v[130:131], v[146:149], off offset:32
	global_store_dwordx4 v[216:217], v[96:99], off offset:128 nt
	global_store_dwordx4 v[216:217], v[100:103], off offset:160 nt
	global_store_dwordx4 v[216:217], v[104:107], off offset:192 nt
	global_store_dwordx4 v[216:217], v[108:111], off offset:224 nt
	v_cvt_pk_bf16_f32 v146, v96, v97
	v_cvt_pk_bf16_f32 v147, v98, v99
	v_cvt_pk_bf16_f32 v148, v100, v101
	v_cvt_pk_bf16_f32 v149, v102, v103
	s_nop 0
	v_permlane32_swap_b32_e32 v146, v148
	v_permlane32_swap_b32_e32 v147, v149
	global_store_dwordx4 v[130:131], v[146:149], off offset:64
	v_and_b32_e32 v128, 56, v144
	v_lshlrev_b32_e32 v128, 1, v128
	v_cvt_pk_bf16_f32 v146, v104, v105
	v_cvt_pk_bf16_f32 v147, v106, v107
	v_cvt_pk_bf16_f32 v148, v108, v109
	v_cvt_pk_bf16_f32 v149, v110, v111
	s_nop 0
	v_permlane32_swap_b32_e32 v146, v148
	v_permlane32_swap_b32_e32 v147, v149
	global_store_dwordx4 v[130:131], v[146:149], off offset:96
	v_add_u32_e32 v130, v137, v145
	v_ashrrev_i32_e32 v131, 31, v130
	v_lshlrev_b64 v[146:147], s34, v[130:131]
	v_lshl_add_u64 v[146:147], v[146:147], 0, v[152:153]
	v_lshlrev_b64 v[146:147], 8, v[146:147]
	v_lshl_add_u64 v[146:147], s[0:1], 0, v[146:147]
	v_lshl_add_u64 v[146:147], v[146:147], 0, v[132:133]
	global_store_dwordx4 v[146:147], v[80:83], off nt
	global_store_dwordx4 v[146:147], v[84:87], off offset:32 nt
	global_store_dwordx4 v[146:147], v[88:91], off offset:64 nt
	global_store_dwordx4 v[146:147], v[92:95], off offset:96 nt
	v_lshlrev_b64 v[146:147], 20, v[130:131]
	v_mad_i64_i32 v[130:131], s[6:7], v130, s95, v[214:215]
	v_lshlrev_b64 v[130:131], 7, v[130:131]
	v_lshl_add_u64 v[216:217], v[150:151], 0, v[146:147]
	v_lshl_add_u64 v[130:131], s[40:41], 0, v[130:131]
	v_cndmask_b32_e32 v217, v217, v131, vcc
	v_cndmask_b32_e32 v216, v216, v130, vcc
	v_mov_b32_e32 v129, v153
	v_cvt_pk_bf16_f32 v146, v80, v81
	v_cvt_pk_bf16_f32 v147, v82, v83
	v_cvt_pk_bf16_f32 v148, v84, v85
	v_cvt_pk_bf16_f32 v149, v86, v87
	v_lshl_add_u64 v[130:131], v[216:217], 0, v[128:129]
	v_add_u32_e32 v129, 16, v144
	v_permlane32_swap_b32_e32 v146, v148
	v_permlane32_swap_b32_e32 v147, v149
	v_and_b32_e32 v129, 56, v129
	global_store_dwordx4 v[130:131], v[146:149], off
	v_lshlrev_b32_e32 v130, 1, v129
	v_mul_f32_e32 v129, v49, v49
	v_fmac_f32_e32 v129, v48, v48
	v_fmac_f32_e32 v129, v50, v50
	v_fmac_f32_e32 v129, v51, v51
	v_fmac_f32_e32 v129, v52, v52
	v_fmac_f32_e32 v129, v53, v53
	v_fmac_f32_e32 v129, v54, v54
	v_fmac_f32_e32 v129, v55, v55
	v_fmac_f32_e32 v129, v56, v56
	v_fmac_f32_e32 v129, v57, v57
	v_fmac_f32_e32 v129, v58, v58
	v_fmac_f32_e32 v129, v59, v59
	v_fmac_f32_e32 v129, v60, v60
	v_fmac_f32_e32 v129, v61, v61
	v_fmac_f32_e32 v129, v62, v62
	v_fmac_f32_e32 v129, v63, v63
	v_fmac_f32_e32 v129, v32, v32
	v_fmac_f32_e32 v129, v33, v33
	v_fmac_f32_e32 v129, v34, v34
	v_fmac_f32_e32 v129, v35, v35
	v_fmac_f32_e32 v129, v36, v36
	v_fmac_f32_e32 v129, v37, v37
	v_fmac_f32_e32 v129, v38, v38
	v_fmac_f32_e32 v129, v39, v39
	v_fmac_f32_e32 v129, v40, v40
	v_fmac_f32_e32 v129, v41, v41
	v_fmac_f32_e32 v129, v42, v42
	v_fmac_f32_e32 v129, v43, v43
	v_fmac_f32_e32 v129, v44, v44
	v_fmac_f32_e32 v129, v45, v45
	v_fmac_f32_e32 v129, v46, v46
	v_mov_b32_e32 v131, v153
	v_fmac_f32_e32 v129, v47, v47
	v_lshl_add_u64 v[216:217], v[216:217], 0, v[130:131]
	ds_bpermute_b32 v131, v134, v129
	v_cvt_pk_bf16_f32 v146, v88, v89
	v_cvt_pk_bf16_f32 v147, v90, v91
	v_cvt_pk_bf16_f32 v148, v92, v93
	v_cvt_pk_bf16_f32 v149, v94, v95
	s_waitcnt lgkmcnt(0)
	v_add_f32_e32 v129, v129, v131
	ds_bpermute_b32 v131, v135, v129
	v_permlane32_swap_b32_e32 v146, v148
	v_permlane32_swap_b32_e32 v147, v149
	v_or_b32_e32 v144, 1, v140
	global_store_dwordx4 v[216:217], v[146:149], off
	s_waitcnt lgkmcnt(0)
	v_max_f32_e32 v131, v131, v131
	v_max_f32_e32 v129, v129, v131
	v_add_u32_e32 v146, v145, v144
	v_ashrrev_i32_e32 v147, 31, v146
	v_lshlrev_b64 v[148:149], s34, v[146:147]
	ds_bpermute_b32 v131, v136, v129
	v_lshl_add_u64 v[148:149], v[148:149], 0, v[152:153]
	v_lshlrev_b64 v[148:149], 8, v[148:149]
	v_lshl_add_u64 v[148:149], s[0:1], 0, v[148:149]
	v_lshl_add_u64 v[148:149], v[148:149], 0, v[132:133]
	global_store_dwordx4 v[148:149], v[64:67], off offset:128 nt
	global_store_dwordx4 v[148:149], v[68:71], off offset:160 nt
	global_store_dwordx4 v[148:149], v[72:75], off offset:192 nt
	global_store_dwordx4 v[148:149], v[76:79], off offset:224 nt
	v_lshlrev_b64 v[148:149], 20, v[146:147]
	v_mad_i64_i32 v[146:147], s[6:7], v146, s95, v[214:215]
	s_waitcnt lgkmcnt(0)
	v_max_f32_e32 v131, v131, v131
	v_lshlrev_b64 v[146:147], 7, v[146:147]
	v_max_f32_e32 v131, v129, v131
	v_lshl_add_u64 v[150:151], v[150:151], 0, v[148:149]
	v_lshl_add_u64 v[214:215], s[40:41], 0, v[146:147]
	ds_bpermute_b32 v145, v141, v131
	v_cvt_pk_bf16_f32 v146, v64, v65
	v_cvt_pk_bf16_f32 v147, v66, v67
	v_cvt_pk_bf16_f32 v148, v68, v69
	v_cvt_pk_bf16_f32 v149, v70, v71
	v_cndmask_b32_e32 v151, v151, v215, vcc
	v_cndmask_b32_e32 v150, v150, v214, vcc
	v_permlane32_swap_b32_e32 v146, v148
	v_permlane32_swap_b32_e32 v147, v149
	v_lshl_add_u64 v[132:133], v[150:151], 0, v[132:133]
	global_store_dwordx4 v[132:133], v[146:149], off offset:64
	v_or_b32_e32 v129, 32, v138
	v_readlane_b32 s85, v250, 11
	v_cvt_pk_bf16_f32 v146, v72, v73
	v_cvt_pk_bf16_f32 v147, v74, v75
	v_cvt_pk_bf16_f32 v148, v76, v77
	v_cvt_pk_bf16_f32 v149, v78, v79
	s_nop 0
	v_permlane32_swap_b32_e32 v146, v148
	v_permlane32_swap_b32_e32 v147, v149
	global_store_dwordx4 v[132:133], v[146:149], off offset:96
	s_waitcnt lgkmcnt(0)
	v_max_f32_e32 v133, v145, v145
	v_max_f32_e32 v133, v131, v133
	ds_bpermute_b32 v138, v142, v133
	v_lshrrev_b32_e32 v132, 4, v129
	v_mov_b32_e32 v131, s53
	v_cndmask_b32_e32 v131, v131, v132, vcc
	v_lshlrev_b32_e32 v132, 3, v131
	v_add_u32_e32 v131, s52, v132
	s_and_saveexec_b64 s[6:7], s[4:5]
	s_cbranch_execz .LBB0_300
	v_add_u32_e32 v146, v131, v140
	s_waitcnt lgkmcnt(0)
	v_max_f32_e32 v138, v138, v138
	v_max_f32_e32 v133, v133, v133
	v_ashrrev_i32_e32 v147, 31, v146
	v_max_f32_e32 v133, v133, v138
	v_lshl_add_u64 v[146:147], v[146:147], 2, s[36:37]
	global_atomic_umax v[146:147], v133, off

.LBB0_302:
	s_or_b64 exec, exec, s[6:7]
	v_or_b32_e32 v129, s54, v129
	v_cndmask_b32_e32 v152, v129, v139, vcc
	s_waitcnt lgkmcnt(0)
	v_lshlrev_b32_e32 v134, 7, v152
	v_mov_b32_e32 v135, v153
	v_lshl_add_u64 v[146:147], s[38:39], 0, v[134:135]
	v_add_u32_e32 v134, v132, v140
	v_ashrrev_i32_e32 v135, 31, v134
	v_lshlrev_b64 v[138:139], s34, v[134:135]
	v_lshl_add_u64 v[138:139], v[138:139], 0, v[152:153]
	v_lshlrev_b32_e32 v131, 2, v211
	v_lshlrev_b64 v[138:139], 8, v[138:139]
	v_add_u32_e32 v148, 0x800, v152
	v_mov_b32_e32 v149, v153
	v_lshl_add_u64 v[138:139], s[0:1], 0, v[138:139]
	v_lshlrev_b32_e32 v150, 2, v131
	v_mov_b32_e32 v151, v153
	v_lshl_add_u64 v[214:215], v[138:139], 0, v[150:151]
	v_lshlrev_b64 v[138:139], 20, v[134:135]
	v_mad_i64_i32 v[134:135], s[4:5], v134, s95, v[148:149]
	v_lshlrev_b64 v[134:135], 7, v[134:135]
	v_lshl_add_u64 v[216:217], v[146:147], 0, v[138:139]
	v_lshl_add_u64 v[134:135], s[40:41], 0, v[134:135]
	v_cvt_pk_bf16_f32 v138, v48, v49
	v_cvt_pk_bf16_f32 v139, v50, v51
	v_cvt_pk_bf16_f32 v140, v52, v53
	v_cvt_pk_bf16_f32 v141, v54, v55
	v_cndmask_b32_e32 v135, v217, v135, vcc
	v_cndmask_b32_e32 v134, v216, v134, vcc
	v_lshlrev_b32_e32 v142, 1, v143
	v_mov_b32_e32 v143, v153
	v_permlane32_swap_b32_e32 v138, v140
	v_permlane32_swap_b32_e32 v139, v141
	v_lshl_add_u64 v[134:135], v[134:135], 0, v[142:143]
	global_store_dwordx4 v[214:215], v[48:51], off nt
	global_store_dwordx4 v[214:215], v[52:55], off offset:32 nt
	global_store_dwordx4 v[214:215], v[56:59], off offset:64 nt
	global_store_dwordx4 v[214:215], v[60:63], off offset:96 nt
	global_store_dwordx4 v[134:135], v[138:141], off
	v_mov_b32_e32 v129, v153
	v_mov_b32_e32 v131, v153
	v_cvt_pk_bf16_f32 v138, v56, v57
	v_cvt_pk_bf16_f32 v139, v58, v59
	v_cvt_pk_bf16_f32 v140, v60, v61
	v_cvt_pk_bf16_f32 v141, v62, v63
	s_nop 0
	v_permlane32_swap_b32_e32 v138, v140
	v_permlane32_swap_b32_e32 v139, v141
	global_store_dwordx4 v[134:135], v[138:141], off offset:32
	global_store_dwordx4 v[214:215], v[32:35], off offset:128 nt
	global_store_dwordx4 v[214:215], v[36:39], off offset:160 nt
	global_store_dwordx4 v[214:215], v[40:43], off offset:192 nt
	global_store_dwordx4 v[214:215], v[44:47], off offset:224 nt
	v_cvt_pk_bf16_f32 v138, v32, v33
	v_cvt_pk_bf16_f32 v139, v34, v35
	v_cvt_pk_bf16_f32 v140, v36, v37
	v_cvt_pk_bf16_f32 v141, v38, v39
	s_nop 0
	v_permlane32_swap_b32_e32 v138, v140
	v_permlane32_swap_b32_e32 v139, v141
	global_store_dwordx4 v[134:135], v[138:141], off offset:64
	s_nop 1
	v_cvt_pk_bf16_f32 v138, v40, v41
	v_cvt_pk_bf16_f32 v139, v42, v43
	v_cvt_pk_bf16_f32 v140, v44, v45
	v_cvt_pk_bf16_f32 v141, v46, v47
	s_nop 0
	v_permlane32_swap_b32_e32 v138, v140
	v_permlane32_swap_b32_e32 v139, v141
	global_store_dwordx4 v[134:135], v[138:141], off offset:96
	v_add_u32_e32 v134, v137, v132
	v_ashrrev_i32_e32 v135, 31, v134
	v_lshlrev_b64 v[136:137], s34, v[134:135]
	v_lshl_add_u64 v[136:137], v[136:137], 0, v[152:153]
	v_lshlrev_b64 v[136:137], 8, v[136:137]
	v_lshl_add_u64 v[136:137], s[0:1], 0, v[136:137]
	v_lshl_add_u64 v[136:137], v[136:137], 0, v[150:151]
	global_store_dwordx4 v[136:137], v[16:19], off nt
	global_store_dwordx4 v[136:137], v[20:23], off offset:32 nt
	global_store_dwordx4 v[136:137], v[24:27], off offset:64 nt
	global_store_dwordx4 v[136:137], v[28:31], off offset:96 nt
	v_lshlrev_b64 v[136:137], 20, v[134:135]
	v_mad_i64_i32 v[134:135], s[4:5], v134, s95, v[148:149]
	v_lshlrev_b64 v[134:135], 7, v[134:135]
	v_lshl_add_u64 v[138:139], v[146:147], 0, v[136:137]
	v_lshl_add_u64 v[140:141], s[40:41], 0, v[134:135]
	v_cvt_pk_bf16_f32 v134, v16, v17
	v_cvt_pk_bf16_f32 v135, v18, v19
	v_cvt_pk_bf16_f32 v136, v20, v21
	v_cvt_pk_bf16_f32 v137, v22, v23
	v_cndmask_b32_e32 v139, v139, v141, vcc
	v_cndmask_b32_e32 v138, v138, v140, vcc
	v_permlane32_swap_b32_e32 v134, v136
	v_permlane32_swap_b32_e32 v135, v137
	v_lshl_add_u64 v[128:129], v[138:139], 0, v[128:129]
	global_store_dwordx4 v[128:129], v[134:137], off
	v_lshl_add_u64 v[128:129], v[138:139], 0, v[130:131]
	s_mov_b64 s[4:5], 0
	v_cvt_pk_bf16_f32 v134, v24, v25
	v_cvt_pk_bf16_f32 v135, v26, v27
	v_cvt_pk_bf16_f32 v136, v28, v29
	v_cvt_pk_bf16_f32 v137, v30, v31
	s_nop 0
	v_permlane32_swap_b32_e32 v134, v136
	v_permlane32_swap_b32_e32 v135, v137
	global_store_dwordx4 v[128:129], v[134:137], off
	v_add_u32_e32 v128, v132, v144
	v_ashrrev_i32_e32 v129, 31, v128
	v_lshlrev_b64 v[130:131], s34, v[128:129]
	v_lshl_add_u64 v[130:131], v[130:131], 0, v[152:153]
	v_lshlrev_b64 v[130:131], 8, v[130:131]
	v_lshl_add_u64 v[130:131], s[0:1], 0, v[130:131]
	v_lshl_add_u64 v[130:131], v[130:131], 0, v[150:151]
	global_store_dwordx4 v[130:131], v[0:3], off offset:128 nt
	global_store_dwordx4 v[130:131], v[4:7], off offset:160 nt
	global_store_dwordx4 v[130:131], v[8:11], off offset:192 nt
	global_store_dwordx4 v[130:131], v[12:15], off offset:224 nt
	v_lshlrev_b64 v[130:131], 20, v[128:129]
	v_mad_i64_i32 v[128:129], s[0:1], v128, s95, v[148:149]
	v_lshlrev_b64 v[128:129], 7, v[128:129]
	v_lshl_add_u64 v[132:133], v[146:147], 0, v[130:131]
	v_lshl_add_u64 v[134:135], s[40:41], 0, v[128:129]
	v_cvt_pk_bf16_f32 v128, v0, v1
	v_cvt_pk_bf16_f32 v129, v2, v3
	v_cvt_pk_bf16_f32 v130, v4, v5
	v_cvt_pk_bf16_f32 v131, v6, v7
	v_cndmask_b32_e32 v133, v133, v135, vcc
	v_cndmask_b32_e32 v132, v132, v134, vcc
	v_permlane32_swap_b32_e32 v128, v130
	v_permlane32_swap_b32_e32 v129, v131
	v_lshl_add_u64 v[132:133], v[132:133], 0, v[142:143]
	global_store_dwordx4 v[132:133], v[128:131], off offset:64
	s_nop 1
	v_cvt_pk_bf16_f32 v128, v8, v9
	v_cvt_pk_bf16_f32 v129, v10, v11
	v_cvt_pk_bf16_f32 v130, v12, v13
	v_cvt_pk_bf16_f32 v131, v14, v15
	s_nop 0
	v_permlane32_swap_b32_e32 v128, v130
	v_permlane32_swap_b32_e32 v129, v131
	global_store_dwordx4 v[132:133], v[128:131], off offset:96

.LBB0_308:
	s_andn2_b64 vcc, exec, s[0:1]
	s_cbranch_vccnz .LBB0_310
	s_and_b32 s0, s74, 3
	s_cmpk_eq_i32 s76, 0x100
	s_cselect_b64 vcc, -1, 0
	s_waitcnt vmcnt(5)
	v_add_lshl_u32 v128, v212, s0, 7
	s_and_b64 s[0:1], vcc, exec
	s_cselect_b32 s0, s93, 0x8ae4100
	v_readlane_b32 s6, v250, 0
	s_cselect_b32 s4, 4, 13
	v_readlane_b32 s7, v250, 1
	s_add_u32 s0, s6, s0
	s_waitcnt vmcnt(3)
	v_lshl_or_b32 v133, v210, 6, v209
	s_addc_u32 s1, s7, 0
	s_ashr_i32 s6, s76, 6
	v_lshrrev_b32_e32 v129, 4, v133
	v_mov_b32_e32 v134, s6
	v_cndmask_b32_e32 v129, v134, v129, vcc
	s_lshl_b32 s5, s76, 7
	v_lshlrev_b32_e32 v135, 3, v129
	v_ashrrev_i32_e32 v136, 6, v128
	s_and_b32 s5, s5, 0x1f80
	v_add_u32_e32 v128, v135, v136
	v_and_b32_e32 v132, 15, v213
	v_or_b32_e32 v130, s5, v133
	v_ashrrev_i32_e32 v129, 31, v128
	v_cndmask_b32_e32 v152, v130, v132, vcc
	v_lshlrev_b64 v[128:129], s4, v[128:129]
	v_lshl_add_u64 v[128:129], v[128:129], 0, v[152:153]
	v_lshlrev_b64 v[128:129], 7, v[128:129]
	v_pk_mul_f32 v[112:113], v[112:113], s[56:57] op_sel_hi:[1,0]
	v_pk_mul_f32 v[96:97], v[96:97], s[56:57] op_sel_hi:[1,0]
	v_pk_mul_f32 v[98:99], v[98:99], s[56:57] op_sel_hi:[1,0]
	v_pk_mul_f32 v[100:101], v[100:101], s[56:57] op_sel_hi:[1,0]
	v_pk_mul_f32 v[102:103], v[102:103], s[56:57] op_sel_hi:[1,0]
	v_lshl_add_u64 v[128:129], s[0:1], 0, v[128:129]
	v_pk_mul_f32 v[130:131], v[114:115], s[56:57] op_sel_hi:[1,0]
	v_pk_mul_f32 v[116:117], v[116:117], s[56:57] op_sel_hi:[1,0]
	v_pk_mul_f32 v[118:119], v[118:119], s[56:57] op_sel_hi:[1,0]
	v_cvt_pk_bf16_f32 v114, v112, v113
	v_lshlrev_b32_e32 v112, 4, v211
	v_mov_b32_e32 v113, v153
	v_cvt_pk_bf16_f32 v96, v96, v97
	v_cvt_pk_bf16_f32 v97, v98, v99
	v_cvt_pk_bf16_f32 v98, v100, v101
	v_cvt_pk_bf16_f32 v99, v102, v103
	v_cvt_pk_bf16_f32 v116, v116, v117
	v_cvt_pk_bf16_f32 v117, v118, v119
	v_lshl_add_u64 v[118:119], v[128:129], 0, v[112:113]
	v_permlane32_swap_b32_e32 v96, v98
	v_permlane32_swap_b32_e32 v97, v99
	global_store_dwordx4 v[118:119], v[96:99], off offset:64 nt
	v_pk_mul_f32 v[100:101], v[108:109], s[56:57] op_sel_hi:[1,0]
	v_pk_mul_f32 v[102:103], v[110:111], s[56:57] op_sel_hi:[1,0]
	v_pk_mul_f32 v[96:97], v[104:105], s[56:57] op_sel_hi:[1,0]
	v_pk_mul_f32 v[98:99], v[106:107], s[56:57] op_sel_hi:[1,0]
	v_cvt_pk_bf16_f32 v96, v96, v97
	v_cvt_pk_bf16_f32 v97, v98, v99
	v_cvt_pk_bf16_f32 v98, v100, v101
	v_cvt_pk_bf16_f32 v99, v102, v103
	s_nop 0
	v_permlane32_swap_b32_e32 v96, v98
	v_permlane32_swap_b32_e32 v97, v99
	global_store_dwordx4 v[118:119], v[96:99], off offset:96 nt
	v_pk_mul_f32 v[64:65], v[64:65], s[56:57] op_sel_hi:[1,0]
	v_pk_mul_f32 v[66:67], v[66:67], s[56:57] op_sel_hi:[1,0]
	v_or_b32_e32 v98, 1, v136
	v_add_u32_e32 v96, v135, v98
	v_ashrrev_i32_e32 v97, 31, v96
	v_lshlrev_b64 v[96:97], s4, v[96:97]
	v_lshl_add_u64 v[96:97], v[96:97], 0, v[152:153]
	v_lshlrev_b64 v[96:97], 7, v[96:97]
	v_pk_mul_f32 v[68:69], v[68:69], s[56:57] op_sel_hi:[1,0]
	v_pk_mul_f32 v[70:71], v[70:71], s[56:57] op_sel_hi:[1,0]
	v_lshl_add_u64 v[96:97], s[0:1], 0, v[96:97]
	v_pk_mul_f32 v[80:81], v[80:81], s[56:57] op_sel_hi:[1,0]
	v_pk_mul_f32 v[82:83], v[82:83], s[56:57] op_sel_hi:[1,0]
	v_pk_mul_f32 v[84:85], v[84:85], s[56:57] op_sel_hi:[1,0]
	v_cvt_pk_bf16_f32 v64, v64, v65
	v_cvt_pk_bf16_f32 v65, v66, v67
	v_cvt_pk_bf16_f32 v66, v68, v69
	v_cvt_pk_bf16_f32 v67, v70, v71
	v_cvt_pk_bf16_f32 v80, v80, v81
	v_cvt_pk_bf16_f32 v81, v82, v83
	v_cvt_pk_bf16_f32 v82, v84, v85
	v_lshl_add_u64 v[84:85], v[96:97], 0, v[112:113]
	v_permlane32_swap_b32_e32 v64, v66
	v_permlane32_swap_b32_e32 v65, v67
	global_store_dwordx4 v[84:85], v[64:67], off offset:64 nt
	v_pk_mul_f32 v[68:69], v[76:77], s[56:57] op_sel_hi:[1,0]
	v_pk_mul_f32 v[70:71], v[78:79], s[56:57] op_sel_hi:[1,0]
	v_pk_mul_f32 v[64:65], v[72:73], s[56:57] op_sel_hi:[1,0]
	v_pk_mul_f32 v[66:67], v[74:75], s[56:57] op_sel_hi:[1,0]
	v_cvt_pk_bf16_f32 v64, v64, v65
	v_cvt_pk_bf16_f32 v65, v66, v67
	v_cvt_pk_bf16_f32 v66, v68, v69
	v_cvt_pk_bf16_f32 v67, v70, v71
	s_nop 0
	v_permlane32_swap_b32_e32 v64, v66
	v_permlane32_swap_b32_e32 v65, v67
	global_store_dwordx4 v[84:85], v[64:67], off offset:96 nt
	v_pk_mul_f32 v[32:33], v[32:33], s[56:57] op_sel_hi:[1,0]
	v_pk_mul_f32 v[34:35], v[34:35], s[56:57] op_sel_hi:[1,0]
	v_or_b32_e32 v64, 32, v133
	v_lshrrev_b32_e32 v65, 4, v64
	v_or_b32_e32 v64, s5, v64
	v_cndmask_b32_e32 v152, v64, v132, vcc
	v_cndmask_b32_e32 v64, v134, v65, vcc
	v_lshlrev_b32_e32 v66, 3, v64
	v_add_u32_e32 v64, v66, v136
	v_ashrrev_i32_e32 v65, 31, v64
	v_lshlrev_b64 v[64:65], s4, v[64:65]
	v_lshl_add_u64 v[64:65], v[64:65], 0, v[152:153]
	v_lshlrev_b64 v[64:65], 7, v[64:65]
	v_pk_mul_f32 v[36:37], v[36:37], s[56:57] op_sel_hi:[1,0]
	v_pk_mul_f32 v[38:39], v[38:39], s[56:57] op_sel_hi:[1,0]
	v_lshl_add_u64 v[64:65], s[0:1], 0, v[64:65]
	v_pk_mul_f32 v[48:49], v[48:49], s[56:57] op_sel_hi:[1,0]
	v_pk_mul_f32 v[50:51], v[50:51], s[56:57] op_sel_hi:[1,0]
	v_pk_mul_f32 v[52:53], v[52:53], s[56:57] op_sel_hi:[1,0]
	v_cvt_pk_bf16_f32 v32, v32, v33
	v_cvt_pk_bf16_f32 v33, v34, v35
	v_cvt_pk_bf16_f32 v34, v36, v37
	v_cvt_pk_bf16_f32 v35, v38, v39
	v_cvt_pk_bf16_f32 v48, v48, v49
	v_cvt_pk_bf16_f32 v49, v50, v51
	v_cvt_pk_bf16_f32 v50, v52, v53
	v_lshl_add_u64 v[52:53], v[64:65], 0, v[112:113]
	v_permlane32_swap_b32_e32 v32, v34
	v_permlane32_swap_b32_e32 v33, v35
	global_store_dwordx4 v[52:53], v[32:35], off offset:64 nt
	v_pk_mul_f32 v[36:37], v[44:45], s[56:57] op_sel_hi:[1,0]
	v_pk_mul_f32 v[38:39], v[46:47], s[56:57] op_sel_hi:[1,0]
	v_pk_mul_f32 v[32:33], v[40:41], s[56:57] op_sel_hi:[1,0]
	v_pk_mul_f32 v[34:35], v[42:43], s[56:57] op_sel_hi:[1,0]
	v_cvt_pk_bf16_f32 v32, v32, v33
	v_cvt_pk_bf16_f32 v33, v34, v35
	v_cvt_pk_bf16_f32 v34, v36, v37
	v_cvt_pk_bf16_f32 v35, v38, v39
	s_nop 0
	v_permlane32_swap_b32_e32 v32, v34
	v_permlane32_swap_b32_e32 v33, v35
	global_store_dwordx4 v[52:53], v[32:35], off offset:96 nt
	v_pk_mul_f32 v[86:87], v[86:87], s[56:57] op_sel_hi:[1,0]
	v_pk_mul_f32 v[54:55], v[54:55], s[56:57] op_sel_hi:[1,0]
	v_add_u32_e32 v32, v66, v98
	v_ashrrev_i32_e32 v33, 31, v32
	v_lshlrev_b64 v[32:33], s4, v[32:33]
	v_lshl_add_u64 v[32:33], v[32:33], 0, v[152:153]
	v_lshlrev_b64 v[32:33], 7, v[32:33]
	v_pk_mul_f32 v[16:17], v[16:17], s[56:57] op_sel_hi:[1,0]
	v_pk_mul_f32 v[18:19], v[18:19], s[56:57] op_sel_hi:[1,0]
	v_pk_mul_f32 v[20:21], v[20:21], s[56:57] op_sel_hi:[1,0]
	v_pk_mul_f32 v[22:23], v[22:23], s[56:57] op_sel_hi:[1,0]
	v_pk_mul_f32 v[0:1], v[0:1], s[56:57] op_sel_hi:[1,0]
	v_pk_mul_f32 v[2:3], v[2:3], s[56:57] op_sel_hi:[1,0]
	v_pk_mul_f32 v[4:5], v[4:5], s[56:57] op_sel_hi:[1,0]
	v_pk_mul_f32 v[6:7], v[6:7], s[56:57] op_sel_hi:[1,0]
	v_cvt_pk_bf16_f32 v115, v130, v131
	v_cvt_pk_bf16_f32 v83, v86, v87
	v_cvt_pk_bf16_f32 v51, v54, v55
	v_lshl_add_u64 v[32:33], s[0:1], 0, v[32:33]
	v_cvt_pk_bf16_f32 v16, v16, v17
	v_cvt_pk_bf16_f32 v17, v18, v19
	v_cvt_pk_bf16_f32 v18, v20, v21
	v_cvt_pk_bf16_f32 v19, v22, v23
	v_cvt_pk_bf16_f32 v0, v0, v1
	v_cvt_pk_bf16_f32 v1, v2, v3
	v_cvt_pk_bf16_f32 v2, v4, v5
	v_cvt_pk_bf16_f32 v3, v6, v7
	v_permlane32_swap_b32_e32 v114, v116
	v_permlane32_swap_b32_e32 v115, v117
	v_permlane32_swap_b32_e32 v80, v82
	v_permlane32_swap_b32_e32 v81, v83
	v_permlane32_swap_b32_e32 v48, v50
	v_permlane32_swap_b32_e32 v49, v51
	v_permlane32_swap_b32_e32 v16, v18
	v_permlane32_swap_b32_e32 v17, v19
	v_lshl_add_u64 v[20:21], v[32:33], 0, v[112:113]
	v_permlane32_swap_b32_e32 v0, v2
	v_permlane32_swap_b32_e32 v1, v3
	global_store_dwordx4 v[118:119], v[114:117], off nt
	global_store_dwordx4 v[84:85], v[80:83], off nt
	v_pk_mul_f32 v[86:87], v[92:93], s[56:57] op_sel_hi:[1,0]
	v_pk_mul_f32 v[114:115], v[120:121], s[56:57] op_sel_hi:[1,0]
	v_pk_mul_f32 v[116:117], v[122:123], s[56:57] op_sel_hi:[1,0]
	v_pk_mul_f32 v[120:121], v[124:125], s[56:57] op_sel_hi:[1,0]
	v_pk_mul_f32 v[122:123], v[126:127], s[56:57] op_sel_hi:[1,0]
	v_pk_mul_f32 v[80:81], v[88:89], s[56:57] op_sel_hi:[1,0]
	v_pk_mul_f32 v[82:83], v[90:91], s[56:57] op_sel_hi:[1,0]
	v_pk_mul_f32 v[88:89], v[94:95], s[56:57] op_sel_hi:[1,0]
	global_store_dwordx4 v[52:53], v[48:51], off nt
	v_pk_mul_f32 v[54:55], v[60:61], s[56:57] op_sel_hi:[1,0]
	global_store_dwordx4 v[20:21], v[16:19], off nt
	v_pk_mul_f32 v[48:49], v[56:57], s[56:57] op_sel_hi:[1,0]
	v_pk_mul_f32 v[50:51], v[58:59], s[56:57] op_sel_hi:[1,0]
	v_pk_mul_f32 v[56:57], v[62:63], s[56:57] op_sel_hi:[1,0]
	v_pk_mul_f32 v[16:17], v[24:25], s[56:57] op_sel_hi:[1,0]
	v_pk_mul_f32 v[18:19], v[26:27], s[56:57] op_sel_hi:[1,0]
	v_pk_mul_f32 v[22:23], v[28:29], s[56:57] op_sel_hi:[1,0]
	v_pk_mul_f32 v[24:25], v[30:31], s[56:57] op_sel_hi:[1,0]
	global_store_dwordx4 v[20:21], v[0:3], off offset:64 nt
	v_pk_mul_f32 v[4:5], v[12:13], s[56:57] op_sel_hi:[1,0]
	v_pk_mul_f32 v[6:7], v[14:15], s[56:57] op_sel_hi:[1,0]
	v_pk_mul_f32 v[0:1], v[8:9], s[56:57] op_sel_hi:[1,0]
	v_pk_mul_f32 v[2:3], v[10:11], s[56:57] op_sel_hi:[1,0]
	v_cvt_pk_bf16_f32 v114, v114, v115
	v_cvt_pk_bf16_f32 v115, v116, v117
	v_cvt_pk_bf16_f32 v116, v120, v121
	v_cvt_pk_bf16_f32 v117, v122, v123
	v_cvt_pk_bf16_f32 v80, v80, v81
	v_cvt_pk_bf16_f32 v81, v82, v83
	v_cvt_pk_bf16_f32 v82, v86, v87
	v_cvt_pk_bf16_f32 v83, v88, v89
	v_cvt_pk_bf16_f32 v48, v48, v49
	v_cvt_pk_bf16_f32 v49, v50, v51
	v_cvt_pk_bf16_f32 v50, v54, v55
	v_cvt_pk_bf16_f32 v51, v56, v57
	v_cvt_pk_bf16_f32 v16, v16, v17
	v_cvt_pk_bf16_f32 v17, v18, v19
	v_cvt_pk_bf16_f32 v18, v22, v23
	v_cvt_pk_bf16_f32 v19, v24, v25
	v_cvt_pk_bf16_f32 v0, v0, v1
	v_cvt_pk_bf16_f32 v1, v2, v3
	v_cvt_pk_bf16_f32 v2, v4, v5
	v_cvt_pk_bf16_f32 v3, v6, v7
	v_permlane32_swap_b32_e32 v114, v116
	v_permlane32_swap_b32_e32 v115, v117
	v_permlane32_swap_b32_e32 v80, v82
	v_permlane32_swap_b32_e32 v81, v83
	v_permlane32_swap_b32_e32 v48, v50
	v_permlane32_swap_b32_e32 v49, v51
	v_permlane32_swap_b32_e32 v16, v18
	v_permlane32_swap_b32_e32 v17, v19
	v_permlane32_swap_b32_e32 v0, v2
	v_permlane32_swap_b32_e32 v1, v3
	global_store_dwordx4 v[118:119], v[114:117], off offset:32 nt
	global_store_dwordx4 v[84:85], v[80:83], off offset:32 nt
	global_store_dwordx4 v[52:53], v[48:51], off offset:32 nt
	global_store_dwordx4 v[20:21], v[16:19], off offset:32 nt
	global_store_dwordx4 v[20:21], v[0:3], off offset:96 nt

.LBB0_323:
	v_ashrrev_i32_e32 v174, 7, v173
	v_lshl_add_u32 v128, v128, 2, v174
	v_ashrrev_i32_e32 v129, 31, v128
	s_lshl_b32 s7, s78, 2
	v_lshlrev_b64 v[128:129], s6, v[128:129]
	s_add_u32 s54, s62, s7
	v_lshl_add_u64 v[128:129], v[128:129], 0, v[152:153]
	s_addc_u32 s55, s63, 0
	v_lshlrev_b64 v[128:129], 9, v[128:129]
	v_lshl_add_u64 v[128:129], s[54:55], 0, v[128:129]
	v_lshlrev_b32_e32 v152, 2, v209
	v_or_b32_e32 v141, 8, v172
	v_lshl_add_u64 v[128:129], v[128:129], 0, v[152:153]
	s_mov_b64 s[6:7], -1
	s_and_b64 vcc, exec, s[4:5]
	v_or_b32_e32 v142, s52, v141
	global_store_dword v[128:129], v112, off nt
	global_store_dword v[128:129], v113, off offset:512 nt
	global_store_dword v[128:129], v114, off offset:1024 nt
	global_store_dword v[128:129], v115, off offset:1536 nt
	s_cbranch_vccnz .LBB0_325
	v_or_b32_e32 v128, s52, v141
	s_mov_b64 s[6:7], 0

.LBB0_328:
	v_lshl_add_u32 v130, v129, 2, v174
	v_ashrrev_i32_e32 v131, 31, v130
	s_lshl_b32 s7, s78, 2
	v_lshlrev_b64 v[130:131], s6, v[130:131]
	v_mov_b32_e32 v129, v153
	s_add_u32 s54, s62, s7
	v_lshl_add_u64 v[128:129], v[130:131], 0, v[128:129]
	s_addc_u32 s55, s63, 0
	v_lshlrev_b64 v[128:129], 9, v[128:129]
	s_waitcnt vmcnt(4)
	v_or_b32_e32 v148, 16, v171
	v_lshl_add_u64 v[128:129], s[54:55], 0, v[128:129]
	v_or_b32_e32 v212, v148, v170
	v_lshl_add_u64 v[128:129], v[128:129], 0, v[152:153]
	s_mov_b64 s[6:7], -1
	s_and_b64 vcc, exec, s[4:5]
	v_or_b32_e32 v144, s52, v212
	global_store_dword v[128:129], v116, off nt
	global_store_dword v[128:129], v117, off offset:512 nt
	global_store_dword v[128:129], v118, off offset:1024 nt
	global_store_dword v[128:129], v119, off offset:1536 nt
	s_cbranch_vccnz .LBB0_330
	v_or_b32_e32 v128, s52, v212
	s_mov_b64 s[6:7], 0

.LBB0_333:
	v_lshl_add_u32 v130, v129, 2, v174
	v_ashrrev_i32_e32 v131, 31, v130
	s_lshl_b32 s7, s78, 2
	v_lshlrev_b64 v[130:131], s6, v[130:131]
	v_mov_b32_e32 v129, v153
	s_add_u32 s54, s62, s7
	v_lshl_add_u64 v[128:129], v[130:131], 0, v[128:129]
	s_addc_u32 s55, s63, 0
	v_lshlrev_b64 v[128:129], 9, v[128:129]
	v_or_b32_e32 v149, 24, v171
	v_lshl_add_u64 v[128:129], s[54:55], 0, v[128:129]
	v_or_b32_e32 v177, v149, v170
	v_lshl_add_u64 v[128:129], v[128:129], 0, v[152:153]
	s_mov_b64 s[6:7], -1
	s_and_b64 vcc, exec, s[4:5]
	v_or_b32_e32 v146, s52, v177
	global_store_dword v[128:129], v120, off nt
	global_store_dword v[128:129], v121, off offset:512 nt
	global_store_dword v[128:129], v122, off offset:1024 nt
	global_store_dword v[128:129], v123, off offset:1536 nt
	s_cbranch_vccnz .LBB0_335
	v_or_b32_e32 v128, s52, v177
	s_mov_b64 s[6:7], 0

.LBB0_338:
	v_lshl_add_u32 v130, v129, 2, v174
	v_ashrrev_i32_e32 v131, 31, v130
	s_lshl_b32 s7, s78, 2
	v_lshlrev_b64 v[130:131], s6, v[130:131]
	v_mov_b32_e32 v129, v153
	s_add_u32 s54, s62, s7
	v_lshl_add_u64 v[128:129], v[130:131], 0, v[128:129]
	s_addc_u32 s55, s63, 0
	v_lshlrev_b64 v[128:129], 9, v[128:129]
	v_lshl_add_u64 v[128:129], s[54:55], 0, v[128:129]
	v_lshl_add_u64 v[128:129], v[128:129], 0, v[152:153]
	global_store_dword v[128:129], v124, off nt
	global_store_dword v[128:129], v125, off offset:512 nt
	global_store_dword v[128:129], v126, off offset:1024 nt
	global_store_dword v[128:129], v127, off offset:1536 nt
	v_lshlrev_b32_e32 v128, 14, v209
	v_mov_b32_e32 v129, v153
	v_lshl_add_u64 v[134:135], s[18:19], 0, v[128:129]
	v_cvt_pk_bf16_f32 v128, v112, v113
	v_cvt_pk_bf16_f32 v129, v114, v115
	v_cvt_pk_bf16_f32 v130, v116, v117
	v_cvt_pk_bf16_f32 v131, v118, v119
	s_nop 0
	v_permlane32_swap_b32_e32 v128, v130
	v_permlane32_swap_b32_e32 v129, v131
	s_mov_b64 s[6:7], -1
	s_and_b64 vcc, exec, s[0:1]
	v_lshl_add_u32 v132, s34, 2, v174
	s_cbranch_vccz .LBB0_340
	v_ashrrev_i32_e32 v133, 31, v132
	v_lshlrev_b64 v[136:137], 21, v[132:133]
	v_lshl_add_u64 v[136:137], v[134:135], 0, v[136:137]
	s_mov_b64 s[6:7], 0

.LBB0_351:
	v_lshl_add_u32 v130, v129, 2, v174
	v_ashrrev_i32_e32 v131, 31, v130
	s_lshl_b32 s7, s78, 2
	v_lshlrev_b64 v[130:131], s6, v[130:131]
	v_mov_b32_e32 v129, v153
	s_add_u32 s54, s62, s7
	v_lshl_add_u64 v[128:129], v[130:131], 0, v[128:129]
	s_addc_u32 s55, s63, 0
	v_lshlrev_b64 v[128:129], 9, v[128:129]
	v_lshl_add_u64 v[128:129], s[54:55], 0, v[128:129]
	v_lshl_add_u64 v[128:129], v[128:129], 0, v[152:153]
	s_and_b64 vcc, exec, s[4:5]
	s_mov_b64 s[6:7], -1
	global_store_dword v[128:129], v96, off offset:128 nt
	global_store_dword v[128:129], v97, off offset:640 nt
	global_store_dword v[128:129], v98, off offset:1152 nt
	global_store_dword v[128:129], v99, off offset:1664 nt
	s_cbranch_vccnz .LBB0_353
	v_or_b32_e32 v128, s52, v141
	s_mov_b64 s[6:7], 0

.LBB0_356:
	v_lshl_add_u32 v130, v129, 2, v174
	v_ashrrev_i32_e32 v131, 31, v130
	s_lshl_b32 s7, s78, 2
	v_lshlrev_b64 v[130:131], s6, v[130:131]
	v_mov_b32_e32 v129, v153
	s_add_u32 s54, s62, s7
	v_lshl_add_u64 v[128:129], v[130:131], 0, v[128:129]
	s_addc_u32 s55, s63, 0
	v_lshlrev_b64 v[128:129], 9, v[128:129]
	v_lshl_add_u64 v[128:129], s[54:55], 0, v[128:129]
	v_lshl_add_u64 v[128:129], v[128:129], 0, v[152:153]
	s_and_b64 vcc, exec, s[4:5]
	s_mov_b64 s[6:7], -1
	global_store_dword v[128:129], v100, off offset:128 nt
	global_store_dword v[128:129], v101, off offset:640 nt
	global_store_dword v[128:129], v102, off offset:1152 nt
	global_store_dword v[128:129], v103, off offset:1664 nt
	s_cbranch_vccnz .LBB0_358
	v_or_b32_e32 v128, s52, v212
	s_mov_b64 s[6:7], 0

.LBB0_361:
	v_lshl_add_u32 v130, v129, 2, v174
	v_ashrrev_i32_e32 v131, 31, v130
	s_lshl_b32 s7, s78, 2
	v_lshlrev_b64 v[130:131], s6, v[130:131]
	v_mov_b32_e32 v129, v153
	s_add_u32 s54, s62, s7
	v_lshl_add_u64 v[128:129], v[130:131], 0, v[128:129]
	s_addc_u32 s55, s63, 0
	v_lshlrev_b64 v[128:129], 9, v[128:129]
	v_lshl_add_u64 v[128:129], s[54:55], 0, v[128:129]
	v_lshl_add_u64 v[128:129], v[128:129], 0, v[152:153]
	s_and_b64 vcc, exec, s[4:5]
	s_mov_b64 s[6:7], -1
	global_store_dword v[128:129], v104, off offset:128 nt
	global_store_dword v[128:129], v105, off offset:640 nt
	global_store_dword v[128:129], v106, off offset:1152 nt
	global_store_dword v[128:129], v107, off offset:1664 nt
	s_cbranch_vccnz .LBB0_363
	v_or_b32_e32 v128, s52, v177
	s_mov_b64 s[6:7], 0

.LBB0_366:
	v_lshl_add_u32 v130, v129, 2, v174
	v_ashrrev_i32_e32 v131, 31, v130
	s_lshl_b32 s7, s78, 2
	v_lshlrev_b64 v[130:131], s6, v[130:131]
	v_mov_b32_e32 v129, v153
	s_add_u32 s54, s62, s7
	v_lshl_add_u64 v[128:129], v[130:131], 0, v[128:129]
	s_addc_u32 s55, s63, 0
	v_lshlrev_b64 v[128:129], 9, v[128:129]
	v_lshl_add_u64 v[128:129], s[54:55], 0, v[128:129]
	v_or_b32_e32 v176, 32, v209
	v_lshl_add_u64 v[128:129], v[128:129], 0, v[152:153]
	global_store_dword v[128:129], v108, off offset:128 nt
	global_store_dword v[128:129], v109, off offset:640 nt
	global_store_dword v[128:129], v110, off offset:1152 nt
	global_store_dword v[128:129], v111, off offset:1664 nt
	v_lshlrev_b32_e32 v128, 14, v176
	v_mov_b32_e32 v129, v153
	v_lshl_add_u64 v[136:137], s[18:19], 0, v[128:129]
	v_cvt_pk_bf16_f32 v128, v96, v97
	v_cvt_pk_bf16_f32 v129, v98, v99
	v_cvt_pk_bf16_f32 v130, v100, v101
	v_cvt_pk_bf16_f32 v131, v102, v103
	s_nop 0
	v_permlane32_swap_b32_e32 v128, v130
	v_permlane32_swap_b32_e32 v129, v131
	s_and_b64 vcc, exec, s[4:5]
	s_mov_b64 s[6:7], -1
	s_cbranch_vccnz .LBB0_368
	v_ashrrev_i32_e32 v133, 31, v132
	v_lshlrev_b64 v[138:139], 21, v[132:133]
	v_lshl_add_u64 v[138:139], v[136:137], 0, v[138:139]
	s_mov_b64 s[6:7], 0

.LBB0_379:
	v_lshl_add_u32 v130, v129, 2, v174
	v_ashrrev_i32_e32 v131, 31, v130
	s_lshl_b32 s7, s78, 2
	v_lshlrev_b64 v[130:131], s6, v[130:131]
	v_mov_b32_e32 v129, v153
	s_add_u32 s54, s62, s7
	v_lshl_add_u64 v[128:129], v[130:131], 0, v[128:129]
	s_addc_u32 s55, s63, 0
	v_lshlrev_b64 v[128:129], 9, v[128:129]
	v_lshl_add_u64 v[128:129], s[54:55], 0, v[128:129]
	v_lshl_add_u64 v[128:129], v[128:129], 0, v[152:153]
	s_and_b64 vcc, exec, s[4:5]
	s_mov_b64 s[6:7], -1
	global_store_dword v[128:129], v80, off offset:256 nt
	global_store_dword v[128:129], v81, off offset:768 nt
	global_store_dword v[128:129], v82, off offset:1280 nt
	global_store_dword v[128:129], v83, off offset:1792 nt
	s_cbranch_vccnz .LBB0_381
	v_or_b32_e32 v128, s52, v141
	s_mov_b64 s[6:7], 0

.LBB0_384:
	v_lshl_add_u32 v130, v129, 2, v174
	v_ashrrev_i32_e32 v131, 31, v130
	s_lshl_b32 s7, s78, 2
	v_lshlrev_b64 v[130:131], s6, v[130:131]
	v_mov_b32_e32 v129, v153
	s_add_u32 s54, s62, s7
	v_lshl_add_u64 v[128:129], v[130:131], 0, v[128:129]
	s_addc_u32 s55, s63, 0
	v_lshlrev_b64 v[128:129], 9, v[128:129]
	v_lshl_add_u64 v[128:129], s[54:55], 0, v[128:129]
	v_lshl_add_u64 v[128:129], v[128:129], 0, v[152:153]
	s_and_b64 vcc, exec, s[4:5]
	s_mov_b64 s[6:7], -1
	global_store_dword v[128:129], v84, off offset:256 nt
	global_store_dword v[128:129], v85, off offset:768 nt
	global_store_dword v[128:129], v86, off offset:1280 nt
	global_store_dword v[128:129], v87, off offset:1792 nt
	s_cbranch_vccnz .LBB0_386
	v_or_b32_e32 v128, s52, v212
	s_mov_b64 s[6:7], 0

.LBB0_389:
	v_lshl_add_u32 v130, v129, 2, v174
	v_ashrrev_i32_e32 v131, 31, v130
	s_lshl_b32 s7, s78, 2
	v_lshlrev_b64 v[130:131], s6, v[130:131]
	v_mov_b32_e32 v129, v153
	s_add_u32 s54, s62, s7
	v_lshl_add_u64 v[128:129], v[130:131], 0, v[128:129]
	s_addc_u32 s55, s63, 0
	v_lshlrev_b64 v[128:129], 9, v[128:129]
	v_lshl_add_u64 v[128:129], s[54:55], 0, v[128:129]
	v_lshl_add_u64 v[128:129], v[128:129], 0, v[152:153]
	s_and_b64 vcc, exec, s[4:5]
	s_mov_b64 s[6:7], -1
	global_store_dword v[128:129], v88, off offset:256 nt
	global_store_dword v[128:129], v89, off offset:768 nt
	global_store_dword v[128:129], v90, off offset:1280 nt
	global_store_dword v[128:129], v91, off offset:1792 nt
	s_cbranch_vccnz .LBB0_391
	v_or_b32_e32 v128, s52, v177
	s_mov_b64 s[6:7], 0

.LBB0_394:
	v_lshl_add_u32 v130, v129, 2, v174
	v_ashrrev_i32_e32 v131, 31, v130
	s_lshl_b32 s7, s78, 2
	v_lshlrev_b64 v[130:131], s6, v[130:131]
	v_mov_b32_e32 v129, v153
	s_add_u32 s54, s62, s7
	v_lshl_add_u64 v[128:129], v[130:131], 0, v[128:129]
	s_addc_u32 s55, s63, 0
	v_lshlrev_b64 v[128:129], 9, v[128:129]
	v_lshl_add_u64 v[128:129], s[54:55], 0, v[128:129]
	v_or_b32_e32 v177, 64, v209
	v_lshl_add_u64 v[128:129], v[128:129], 0, v[152:153]
	global_store_dword v[128:129], v92, off offset:256 nt
	global_store_dword v[128:129], v93, off offset:768 nt
	global_store_dword v[128:129], v94, off offset:1280 nt
	global_store_dword v[128:129], v95, off offset:1792 nt
	v_lshlrev_b32_e32 v128, 14, v177
	v_mov_b32_e32 v129, v153
	v_lshl_add_u64 v[138:139], s[18:19], 0, v[128:129]
	v_cvt_pk_bf16_f32 v128, v80, v81
	v_cvt_pk_bf16_f32 v129, v82, v83
	v_cvt_pk_bf16_f32 v130, v84, v85
	v_cvt_pk_bf16_f32 v131, v86, v87
	s_nop 0
	v_permlane32_swap_b32_e32 v128, v130
	v_permlane32_swap_b32_e32 v129, v131
	s_and_b64 vcc, exec, s[4:5]
	s_mov_b64 s[6:7], -1
	s_cbranch_vccnz .LBB0_396
	v_ashrrev_i32_e32 v133, 31, v132
	v_lshlrev_b64 v[148:149], 21, v[132:133]
	v_lshl_add_u64 v[148:149], v[138:139], 0, v[148:149]
	s_mov_b64 s[6:7], 0

.LBB0_407:
	v_lshl_add_u32 v128, v128, 2, v174
	v_ashrrev_i32_e32 v129, 31, v128
	s_lshl_b32 s7, s78, 2
	v_lshlrev_b64 v[128:129], s6, v[128:129]
	v_mov_b32_e32 v141, v153
	s_add_u32 s54, s62, s7
	v_lshl_add_u64 v[128:129], v[128:129], 0, v[140:141]
	s_addc_u32 s55, s63, 0
	v_lshlrev_b64 v[128:129], 9, v[128:129]
	v_lshl_add_u64 v[128:129], s[54:55], 0, v[128:129]
	v_lshl_add_u64 v[128:129], v[128:129], 0, v[152:153]
	s_and_b64 vcc, exec, s[4:5]
	s_mov_b64 s[6:7], -1
	global_store_dword v[128:129], v64, off offset:384 nt
	global_store_dword v[128:129], v65, off offset:896 nt
	global_store_dword v[128:129], v66, off offset:1408 nt
	global_store_dword v[128:129], v67, off offset:1920 nt
	s_cbranch_vccnz .LBB0_409
	s_mov_b64 s[6:7], 0

.LBB0_412:
	v_lshl_add_u32 v128, v128, 2, v174
	v_ashrrev_i32_e32 v129, 31, v128
	s_lshl_b32 s7, s78, 2
	v_lshlrev_b64 v[128:129], s6, v[128:129]
	v_mov_b32_e32 v143, v153
	s_add_u32 s54, s62, s7
	v_lshl_add_u64 v[128:129], v[128:129], 0, v[142:143]
	s_addc_u32 s55, s63, 0
	v_lshlrev_b64 v[128:129], 9, v[128:129]
	v_lshl_add_u64 v[128:129], s[54:55], 0, v[128:129]
	v_lshl_add_u64 v[128:129], v[128:129], 0, v[152:153]
	s_and_b64 vcc, exec, s[4:5]
	s_mov_b64 s[6:7], -1
	global_store_dword v[128:129], v68, off offset:384 nt
	global_store_dword v[128:129], v69, off offset:896 nt
	global_store_dword v[128:129], v70, off offset:1408 nt
	global_store_dword v[128:129], v71, off offset:1920 nt
	s_cbranch_vccnz .LBB0_414
	s_mov_b64 s[6:7], 0

.LBB0_417:
	v_lshl_add_u32 v128, v128, 2, v174
	v_ashrrev_i32_e32 v129, 31, v128
	s_lshl_b32 s7, s78, 2
	v_lshlrev_b64 v[128:129], s6, v[128:129]
	v_mov_b32_e32 v145, v153
	s_add_u32 s54, s62, s7
	v_lshl_add_u64 v[128:129], v[128:129], 0, v[144:145]
	s_addc_u32 s55, s63, 0
	v_lshlrev_b64 v[128:129], 9, v[128:129]
	v_lshl_add_u64 v[128:129], s[54:55], 0, v[128:129]
	v_lshl_add_u64 v[128:129], v[128:129], 0, v[152:153]
	s_and_b64 vcc, exec, s[4:5]
	s_mov_b64 s[6:7], -1
	global_store_dword v[128:129], v72, off offset:384 nt
	global_store_dword v[128:129], v73, off offset:896 nt
	global_store_dword v[128:129], v74, off offset:1408 nt
	global_store_dword v[128:129], v75, off offset:1920 nt
	s_cbranch_vccnz .LBB0_419
	s_mov_b64 s[6:7], 0

.LBB0_422:
	v_lshl_add_u32 v128, v128, 2, v174
	v_ashrrev_i32_e32 v129, 31, v128
	s_lshl_b32 s7, s78, 2
	v_lshlrev_b64 v[128:129], s6, v[128:129]
	v_mov_b32_e32 v147, v153
	s_add_u32 s54, s62, s7
	v_lshl_add_u64 v[128:129], v[128:129], 0, v[146:147]
	s_addc_u32 s55, s63, 0
	v_lshlrev_b64 v[128:129], 9, v[128:129]
	v_lshl_add_u64 v[128:129], s[54:55], 0, v[128:129]
	v_or_b32_e32 v212, 0x60, v209
	v_lshl_add_u64 v[128:129], v[128:129], 0, v[152:153]
	global_store_dword v[128:129], v76, off offset:384 nt
	global_store_dword v[128:129], v77, off offset:896 nt
	global_store_dword v[128:129], v78, off offset:1408 nt
	global_store_dword v[128:129], v79, off offset:1920 nt
	v_lshlrev_b32_e32 v128, 14, v212
	v_mov_b32_e32 v129, v153
	v_lshl_add_u64 v[140:141], s[18:19], 0, v[128:129]
	v_cvt_pk_bf16_f32 v128, v64, v65
	v_cvt_pk_bf16_f32 v129, v66, v67
	v_cvt_pk_bf16_f32 v130, v68, v69
	v_cvt_pk_bf16_f32 v131, v70, v71
	s_nop 0
	v_permlane32_swap_b32_e32 v128, v130
	v_permlane32_swap_b32_e32 v129, v131
	s_and_b64 vcc, exec, s[4:5]
	s_mov_b64 s[6:7], -1
	s_cbranch_vccnz .LBB0_424
	v_ashrrev_i32_e32 v133, 31, v132
	v_lshlrev_b64 v[142:143], 21, v[132:133]
	v_lshl_add_u64 v[142:143], v[140:141], 0, v[142:143]
	s_mov_b64 s[6:7], 0

.LBB0_435:
	v_lshl_add_u32 v130, v129, 2, v174
	v_ashrrev_i32_e32 v131, 31, v130
	s_lshl_b32 s7, s78, 2
	v_lshlrev_b64 v[130:131], s6, v[130:131]
	v_mov_b32_e32 v129, v153
	s_add_u32 s54, s62, s7
	v_lshl_add_u64 v[128:129], v[130:131], 0, v[128:129]
	s_addc_u32 s55, s63, 0
	v_lshlrev_b64 v[128:129], 9, v[128:129]
	v_or_b32_e32 v222, 40, v171
	v_lshl_add_u64 v[128:129], s[54:55], 0, v[128:129]
	v_or_b32_e32 v223, v222, v170
	v_lshl_add_u64 v[128:129], v[128:129], 0, v[152:153]
	s_mov_b64 s[6:7], -1
	s_and_b64 vcc, exec, s[4:5]
	v_or_b32_e32 v144, s52, v223
	global_store_dword v[128:129], v48, off nt
	global_store_dword v[128:129], v49, off offset:512 nt
	global_store_dword v[128:129], v50, off offset:1024 nt
	global_store_dword v[128:129], v51, off offset:1536 nt
	s_cbranch_vccnz .LBB0_437
	v_or_b32_e32 v128, s52, v223
	s_mov_b64 s[6:7], 0

.LBB0_440:
	v_lshl_add_u32 v130, v129, 2, v174
	v_ashrrev_i32_e32 v131, 31, v130
	s_lshl_b32 s7, s78, 2
	v_lshlrev_b64 v[130:131], s6, v[130:131]
	v_mov_b32_e32 v129, v153
	s_add_u32 s54, s62, s7
	v_lshl_add_u64 v[128:129], v[130:131], 0, v[128:129]
	s_addc_u32 s55, s63, 0
	v_lshlrev_b64 v[128:129], 9, v[128:129]
	v_or_b32_e32 v224, 48, v171
	v_lshl_add_u64 v[128:129], s[54:55], 0, v[128:129]
	v_or_b32_e32 v228, v224, v170
	v_lshl_add_u64 v[128:129], v[128:129], 0, v[152:153]
	s_mov_b64 s[6:7], -1
	s_and_b64 vcc, exec, s[4:5]
	v_or_b32_e32 v146, s52, v228
	global_store_dword v[128:129], v52, off nt
	global_store_dword v[128:129], v53, off offset:512 nt
	global_store_dword v[128:129], v54, off offset:1024 nt
	global_store_dword v[128:129], v55, off offset:1536 nt
	s_cbranch_vccnz .LBB0_442
	v_or_b32_e32 v128, s52, v228
	s_mov_b64 s[6:7], 0

.LBB0_445:
	v_lshl_add_u32 v130, v129, 2, v174
	v_ashrrev_i32_e32 v131, 31, v130
	s_lshl_b32 s7, s78, 2
	v_lshlrev_b64 v[130:131], s6, v[130:131]
	v_mov_b32_e32 v129, v153
	s_add_u32 s54, s62, s7
	v_lshl_add_u64 v[128:129], v[130:131], 0, v[128:129]
	s_addc_u32 s55, s63, 0
	v_lshlrev_b64 v[128:129], 9, v[128:129]
	v_or_b32_e32 v225, 56, v171
	v_lshl_add_u64 v[128:129], s[54:55], 0, v[128:129]
	v_or_b32_e32 v226, v225, v170
	v_lshl_add_u64 v[128:129], v[128:129], 0, v[152:153]
	s_mov_b64 s[6:7], -1
	s_and_b64 vcc, exec, s[4:5]
	v_or_b32_e32 v148, s52, v226
	global_store_dword v[128:129], v56, off nt
	global_store_dword v[128:129], v57, off offset:512 nt
	global_store_dword v[128:129], v58, off offset:1024 nt
	global_store_dword v[128:129], v59, off offset:1536 nt
	s_cbranch_vccnz .LBB0_447
	v_or_b32_e32 v128, s52, v226
	s_mov_b64 s[6:7], 0

.LBB0_450:
	v_lshl_add_u32 v130, v129, 2, v174
	v_ashrrev_i32_e32 v131, 31, v130
	s_lshl_b32 s7, s78, 2
	v_lshlrev_b64 v[130:131], s6, v[130:131]
	v_mov_b32_e32 v129, v153
	s_add_u32 s54, s62, s7
	v_lshl_add_u64 v[128:129], v[130:131], 0, v[128:129]
	s_addc_u32 s55, s63, 0
	v_lshlrev_b64 v[128:129], 9, v[128:129]
	v_lshl_add_u64 v[128:129], s[54:55], 0, v[128:129]
	v_lshl_add_u64 v[128:129], v[128:129], 0, v[152:153]
	global_store_dword v[128:129], v60, off nt
	global_store_dword v[128:129], v61, off offset:512 nt
	global_store_dword v[128:129], v62, off offset:1024 nt
	global_store_dword v[128:129], v63, off offset:1536 nt
	v_cvt_pk_bf16_f32 v128, v48, v49
	v_cvt_pk_bf16_f32 v129, v50, v51
	v_cvt_pk_bf16_f32 v130, v52, v53
	v_cvt_pk_bf16_f32 v131, v54, v55
	s_nop 0
	v_permlane32_swap_b32_e32 v128, v130
	v_permlane32_swap_b32_e32 v129, v131
	s_and_b64 vcc, exec, s[4:5]
	s_mov_b64 s[6:7], -1
	s_cbranch_vccnz .LBB0_452
	v_ashrrev_i32_e32 v133, 31, v132
	v_lshlrev_b64 v[150:151], 21, v[132:133]
	v_lshl_add_u64 v[150:151], v[134:135], 0, v[150:151]
	s_mov_b64 s[6:7], 0

.LBB0_463:
	v_lshl_add_u32 v130, v129, 2, v174
	v_ashrrev_i32_e32 v131, 31, v130
	s_lshl_b32 s7, s78, 2
	v_lshlrev_b64 v[130:131], s6, v[130:131]
	v_mov_b32_e32 v129, v153
	s_add_u32 s54, s62, s7
	v_lshl_add_u64 v[128:129], v[130:131], 0, v[128:129]
	s_addc_u32 s55, s63, 0
	v_lshlrev_b64 v[128:129], 9, v[128:129]
	v_lshl_add_u64 v[128:129], s[54:55], 0, v[128:129]
	v_lshl_add_u64 v[128:129], v[128:129], 0, v[152:153]
	s_and_b64 vcc, exec, s[4:5]
	s_mov_b64 s[6:7], -1
	global_store_dword v[128:129], v32, off offset:128 nt
	global_store_dword v[128:129], v33, off offset:640 nt
	global_store_dword v[128:129], v34, off offset:1152 nt
	global_store_dword v[128:129], v35, off offset:1664 nt
	s_cbranch_vccnz .LBB0_465
	v_or_b32_e32 v128, s52, v223
	s_mov_b64 s[6:7], 0

.LBB0_468:
	v_lshl_add_u32 v130, v129, 2, v174
	v_ashrrev_i32_e32 v131, 31, v130
	s_lshl_b32 s7, s78, 2
	v_lshlrev_b64 v[130:131], s6, v[130:131]
	v_mov_b32_e32 v129, v153
	s_add_u32 s54, s62, s7
	v_lshl_add_u64 v[128:129], v[130:131], 0, v[128:129]
	s_addc_u32 s55, s63, 0
	v_lshlrev_b64 v[128:129], 9, v[128:129]
	v_lshl_add_u64 v[128:129], s[54:55], 0, v[128:129]
	v_lshl_add_u64 v[128:129], v[128:129], 0, v[152:153]
	s_and_b64 vcc, exec, s[4:5]
	s_mov_b64 s[6:7], -1
	global_store_dword v[128:129], v36, off offset:128 nt
	global_store_dword v[128:129], v37, off offset:640 nt
	global_store_dword v[128:129], v38, off offset:1152 nt
	global_store_dword v[128:129], v39, off offset:1664 nt
	s_cbranch_vccnz .LBB0_470
	v_or_b32_e32 v128, s52, v228
	s_mov_b64 s[6:7], 0

.LBB0_473:
	v_lshl_add_u32 v130, v129, 2, v174
	v_ashrrev_i32_e32 v131, 31, v130
	s_lshl_b32 s7, s78, 2
	v_lshlrev_b64 v[130:131], s6, v[130:131]
	v_mov_b32_e32 v129, v153
	s_add_u32 s54, s62, s7
	v_lshl_add_u64 v[128:129], v[130:131], 0, v[128:129]
	s_addc_u32 s55, s63, 0
	v_lshlrev_b64 v[128:129], 9, v[128:129]
	v_lshl_add_u64 v[128:129], s[54:55], 0, v[128:129]
	v_lshl_add_u64 v[128:129], v[128:129], 0, v[152:153]
	s_and_b64 vcc, exec, s[4:5]
	s_mov_b64 s[6:7], -1
	global_store_dword v[128:129], v40, off offset:128 nt
	global_store_dword v[128:129], v41, off offset:640 nt
	global_store_dword v[128:129], v42, off offset:1152 nt
	global_store_dword v[128:129], v43, off offset:1664 nt
	s_cbranch_vccnz .LBB0_475
	v_or_b32_e32 v128, s52, v226
	s_mov_b64 s[6:7], 0

.LBB0_478:
	v_lshl_add_u32 v130, v129, 2, v174
	v_ashrrev_i32_e32 v131, 31, v130
	s_lshl_b32 s7, s78, 2
	v_lshlrev_b64 v[130:131], s6, v[130:131]
	v_mov_b32_e32 v129, v153
	s_add_u32 s54, s62, s7
	v_lshl_add_u64 v[128:129], v[130:131], 0, v[128:129]
	s_addc_u32 s55, s63, 0
	v_lshlrev_b64 v[128:129], 9, v[128:129]
	v_lshl_add_u64 v[128:129], s[54:55], 0, v[128:129]
	v_lshl_add_u64 v[128:129], v[128:129], 0, v[152:153]
	global_store_dword v[128:129], v44, off offset:128 nt
	global_store_dword v[128:129], v45, off offset:640 nt
	global_store_dword v[128:129], v46, off offset:1152 nt
	global_store_dword v[128:129], v47, off offset:1664 nt
	v_cvt_pk_bf16_f32 v128, v32, v33
	v_cvt_pk_bf16_f32 v129, v34, v35
	v_cvt_pk_bf16_f32 v130, v36, v37
	v_cvt_pk_bf16_f32 v131, v38, v39
	s_nop 0
	v_permlane32_swap_b32_e32 v128, v130
	v_permlane32_swap_b32_e32 v129, v131
	s_and_b64 vcc, exec, s[4:5]
	s_mov_b64 s[6:7], -1
	s_cbranch_vccnz .LBB0_480
	v_ashrrev_i32_e32 v133, 31, v132
	v_lshlrev_b64 v[134:135], 21, v[132:133]
	v_lshl_add_u64 v[134:135], v[136:137], 0, v[134:135]
	s_mov_b64 s[6:7], 0

.LBB0_491:
	v_lshl_add_u32 v130, v129, 2, v174
	v_ashrrev_i32_e32 v131, 31, v130
	s_lshl_b32 s7, s78, 2
	v_lshlrev_b64 v[130:131], s6, v[130:131]
	v_mov_b32_e32 v129, v153
	s_add_u32 s54, s62, s7
	v_lshl_add_u64 v[128:129], v[130:131], 0, v[128:129]
	s_addc_u32 s55, s63, 0
	v_lshlrev_b64 v[128:129], 9, v[128:129]
	v_lshl_add_u64 v[128:129], s[54:55], 0, v[128:129]
	v_lshl_add_u64 v[128:129], v[128:129], 0, v[152:153]
	s_and_b64 vcc, exec, s[4:5]
	s_mov_b64 s[6:7], -1
	global_store_dword v[128:129], v16, off offset:256 nt
	global_store_dword v[128:129], v17, off offset:768 nt
	global_store_dword v[128:129], v18, off offset:1280 nt
	global_store_dword v[128:129], v19, off offset:1792 nt
	s_cbranch_vccnz .LBB0_493
	v_or_b32_e32 v128, s52, v223
	s_mov_b64 s[6:7], 0

.LBB0_496:
	v_lshl_add_u32 v130, v129, 2, v174
	v_ashrrev_i32_e32 v131, 31, v130
	s_lshl_b32 s7, s78, 2
	v_lshlrev_b64 v[130:131], s6, v[130:131]
	v_mov_b32_e32 v129, v153
	s_add_u32 s54, s62, s7
	v_lshl_add_u64 v[128:129], v[130:131], 0, v[128:129]
	s_addc_u32 s55, s63, 0
	v_lshlrev_b64 v[128:129], 9, v[128:129]
	v_lshl_add_u64 v[128:129], s[54:55], 0, v[128:129]
	v_lshl_add_u64 v[128:129], v[128:129], 0, v[152:153]
	s_and_b64 vcc, exec, s[4:5]
	s_mov_b64 s[6:7], -1
	global_store_dword v[128:129], v20, off offset:256 nt
	global_store_dword v[128:129], v21, off offset:768 nt
	global_store_dword v[128:129], v22, off offset:1280 nt
	global_store_dword v[128:129], v23, off offset:1792 nt
	s_cbranch_vccnz .LBB0_498
	v_or_b32_e32 v128, s52, v228
	s_mov_b64 s[6:7], 0

.LBB0_501:
	v_lshl_add_u32 v130, v129, 2, v174
	v_ashrrev_i32_e32 v131, 31, v130
	s_lshl_b32 s7, s78, 2
	v_lshlrev_b64 v[130:131], s6, v[130:131]
	v_mov_b32_e32 v129, v153
	s_add_u32 s54, s62, s7
	v_lshl_add_u64 v[128:129], v[130:131], 0, v[128:129]
	s_addc_u32 s55, s63, 0
	v_lshlrev_b64 v[128:129], 9, v[128:129]
	v_lshl_add_u64 v[128:129], s[54:55], 0, v[128:129]
	v_lshl_add_u64 v[128:129], v[128:129], 0, v[152:153]
	s_and_b64 vcc, exec, s[4:5]
	s_mov_b64 s[6:7], -1
	global_store_dword v[128:129], v24, off offset:256 nt
	global_store_dword v[128:129], v25, off offset:768 nt
	global_store_dword v[128:129], v26, off offset:1280 nt
	global_store_dword v[128:129], v27, off offset:1792 nt
	s_cbranch_vccnz .LBB0_503
	v_or_b32_e32 v128, s52, v226
	s_mov_b64 s[6:7], 0

.LBB0_506:
	v_lshl_add_u32 v130, v129, 2, v174
	v_ashrrev_i32_e32 v131, 31, v130
	s_lshl_b32 s7, s78, 2
	v_lshlrev_b64 v[130:131], s6, v[130:131]
	v_mov_b32_e32 v129, v153
	s_add_u32 s52, s62, s7
	v_lshl_add_u64 v[128:129], v[130:131], 0, v[128:129]
	s_addc_u32 s53, s63, 0
	v_lshlrev_b64 v[128:129], 9, v[128:129]
	v_lshl_add_u64 v[128:129], s[52:53], 0, v[128:129]
	v_lshl_add_u64 v[128:129], v[128:129], 0, v[152:153]
	global_store_dword v[128:129], v28, off offset:256 nt
	global_store_dword v[128:129], v29, off offset:768 nt
	global_store_dword v[128:129], v30, off offset:1280 nt
	global_store_dword v[128:129], v31, off offset:1792 nt
	v_cvt_pk_bf16_f32 v128, v16, v17
	v_cvt_pk_bf16_f32 v129, v18, v19
	v_cvt_pk_bf16_f32 v130, v20, v21
	v_cvt_pk_bf16_f32 v131, v22, v23
	s_nop 0
	v_permlane32_swap_b32_e32 v128, v130
	v_permlane32_swap_b32_e32 v129, v131
	s_and_b64 vcc, exec, s[4:5]
	s_mov_b64 s[6:7], -1
	s_cbranch_vccnz .LBB0_508
	v_ashrrev_i32_e32 v133, 31, v132
	v_lshlrev_b64 v[134:135], 21, v[132:133]
	v_lshl_add_u64 v[134:135], v[138:139], 0, v[134:135]
	s_mov_b64 s[6:7], 0

.LBB0_519:
	v_lshl_add_u32 v128, v128, 2, v174
	v_ashrrev_i32_e32 v129, 31, v128
	s_lshl_b32 s7, s78, 2
	v_lshlrev_b64 v[128:129], s6, v[128:129]
	v_mov_b32_e32 v143, v153
	s_add_u32 s52, s62, s7
	v_lshl_add_u64 v[128:129], v[128:129], 0, v[142:143]
	s_addc_u32 s53, s63, 0
	v_lshlrev_b64 v[128:129], 9, v[128:129]
	v_lshl_add_u64 v[128:129], s[52:53], 0, v[128:129]
	v_lshl_add_u64 v[128:129], v[128:129], 0, v[152:153]
	s_and_b64 vcc, exec, s[4:5]
	s_mov_b64 s[6:7], -1
	global_store_dword v[128:129], v0, off offset:384 nt
	global_store_dword v[128:129], v1, off offset:896 nt
	global_store_dword v[128:129], v2, off offset:1408 nt
	global_store_dword v[128:129], v3, off offset:1920 nt
	s_cbranch_vccnz .LBB0_521
	s_mov_b64 s[6:7], 0

.LBB0_524:
	v_lshl_add_u32 v128, v128, 2, v174
	v_ashrrev_i32_e32 v129, 31, v128
	s_lshl_b32 s7, s78, 2
	v_lshlrev_b64 v[128:129], s6, v[128:129]
	v_mov_b32_e32 v145, v153
	s_add_u32 s52, s62, s7
	v_lshl_add_u64 v[128:129], v[128:129], 0, v[144:145]
	s_addc_u32 s53, s63, 0
	v_lshlrev_b64 v[128:129], 9, v[128:129]
	v_lshl_add_u64 v[128:129], s[52:53], 0, v[128:129]
	v_lshl_add_u64 v[128:129], v[128:129], 0, v[152:153]
	s_and_b64 vcc, exec, s[4:5]
	s_mov_b64 s[6:7], -1
	global_store_dword v[128:129], v4, off offset:384 nt
	global_store_dword v[128:129], v5, off offset:896 nt
	global_store_dword v[128:129], v6, off offset:1408 nt
	global_store_dword v[128:129], v7, off offset:1920 nt
	s_cbranch_vccnz .LBB0_526
	s_mov_b64 s[6:7], 0

.LBB0_529:
	v_lshl_add_u32 v128, v128, 2, v174
	v_ashrrev_i32_e32 v129, 31, v128
	s_lshl_b32 s7, s78, 2
	v_lshlrev_b64 v[128:129], s6, v[128:129]
	v_mov_b32_e32 v147, v153
	s_add_u32 s52, s62, s7
	v_lshl_add_u64 v[128:129], v[128:129], 0, v[146:147]
	s_addc_u32 s53, s63, 0
	v_lshlrev_b64 v[128:129], 9, v[128:129]
	v_lshl_add_u64 v[128:129], s[52:53], 0, v[128:129]
	v_lshl_add_u64 v[128:129], v[128:129], 0, v[152:153]
	s_and_b64 vcc, exec, s[4:5]
	s_mov_b64 s[6:7], -1
	global_store_dword v[128:129], v8, off offset:384 nt
	global_store_dword v[128:129], v9, off offset:896 nt
	global_store_dword v[128:129], v10, off offset:1408 nt
	global_store_dword v[128:129], v11, off offset:1920 nt
	s_cbranch_vccnz .LBB0_531
	s_mov_b64 s[6:7], 0

.LBB0_534:
	v_lshl_add_u32 v128, v128, 2, v174
	v_ashrrev_i32_e32 v129, 31, v128
	s_lshl_b32 s7, s78, 2
	v_lshlrev_b64 v[128:129], s6, v[128:129]
	v_mov_b32_e32 v149, v153
	s_add_u32 s52, s62, s7
	v_lshl_add_u64 v[128:129], v[128:129], 0, v[148:149]
	s_addc_u32 s53, s63, 0
	v_lshlrev_b64 v[128:129], 9, v[128:129]
	v_lshl_add_u64 v[128:129], s[52:53], 0, v[128:129]
	v_lshl_add_u64 v[128:129], v[128:129], 0, v[152:153]
	global_store_dword v[128:129], v12, off offset:384 nt
	global_store_dword v[128:129], v13, off offset:896 nt
	global_store_dword v[128:129], v14, off offset:1408 nt
	global_store_dword v[128:129], v15, off offset:1920 nt
	v_cvt_pk_bf16_f32 v128, v0, v1
	v_cvt_pk_bf16_f32 v129, v2, v3
	v_cvt_pk_bf16_f32 v130, v4, v5
	v_cvt_pk_bf16_f32 v131, v6, v7
	s_nop 0
	v_permlane32_swap_b32_e32 v128, v130
	v_permlane32_swap_b32_e32 v129, v131
	s_and_b64 vcc, exec, s[4:5]
	s_mov_b64 s[6:7], -1
	s_cbranch_vccnz .LBB0_536
	v_ashrrev_i32_e32 v133, 31, v132
	v_lshlrev_b64 v[134:135], 21, v[132:133]
	v_lshl_add_u64 v[134:135], v[140:141], 0, v[134:135]
	s_mov_b64 s[6:7], 0

.LBB0_549:
	v_ashrrev_i32_e32 v139, 6, v173
	v_lshl_add_u32 v128, v128, 3, v139
	v_ashrrev_i32_e32 v129, 31, v128
	s_lshl_b32 s7, s76, 2
	v_lshlrev_b64 v[128:129], s6, v[128:129]
	s_add_u32 s54, s62, s7
	v_lshl_add_u64 v[128:129], v[128:129], 0, v[152:153]
	s_addc_u32 s55, s63, 0
	v_lshlrev_b64 v[128:129], 8, v[128:129]
	v_lshl_add_u64 v[128:129], s[54:55], 0, v[128:129]
	v_lshlrev_b32_e32 v152, 2, v209
	v_or_b32_e32 v131, 8, v172
	v_lshl_add_u64 v[128:129], v[128:129], 0, v[152:153]
	s_mov_b64 s[6:7], -1
	s_and_b64 vcc, exec, s[4:5]
	v_or_b32_e32 v132, s52, v131
	global_store_dword v[128:129], v112, off nt
	global_store_dword v[128:129], v113, off offset:256 nt
	global_store_dword v[128:129], v114, off offset:512 nt
	global_store_dword v[128:129], v115, off offset:768 nt
	s_cbranch_vccnz .LBB0_551
	v_or_b32_e32 v128, s52, v131
	s_mov_b64 s[6:7], 0

.LBB0_554:
	v_lshl_add_u32 v136, v129, 3, v139
	v_ashrrev_i32_e32 v137, 31, v136
	s_lshl_b32 s7, s76, 2
	v_lshlrev_b64 v[136:137], s6, v[136:137]
	v_mov_b32_e32 v129, v153
	s_add_u32 s54, s62, s7
	v_lshl_add_u64 v[128:129], v[136:137], 0, v[128:129]
	s_addc_u32 s55, s63, 0
	v_lshlrev_b64 v[128:129], 8, v[128:129]
	s_waitcnt vmcnt(5)
	v_or_b32_e32 v144, 16, v171
	v_lshl_add_u64 v[128:129], s[54:55], 0, v[128:129]
	v_or_b32_e32 v147, v144, v170
	v_lshl_add_u64 v[128:129], v[128:129], 0, v[152:153]
	s_mov_b64 s[6:7], -1
	s_and_b64 vcc, exec, s[4:5]
	v_or_b32_e32 v134, s52, v147
	global_store_dword v[128:129], v116, off nt
	global_store_dword v[128:129], v117, off offset:256 nt
	global_store_dword v[128:129], v118, off offset:512 nt
	global_store_dword v[128:129], v119, off offset:768 nt
	s_cbranch_vccnz .LBB0_556
	v_or_b32_e32 v128, s52, v147
	s_mov_b64 s[6:7], 0

.LBB0_559:
	v_lshl_add_u32 v140, v129, 3, v139
	v_ashrrev_i32_e32 v141, 31, v140
	s_lshl_b32 s7, s76, 2
	v_lshlrev_b64 v[140:141], s6, v[140:141]
	v_mov_b32_e32 v129, v153
	s_add_u32 s54, s62, s7
	v_lshl_add_u64 v[128:129], v[140:141], 0, v[128:129]
	s_addc_u32 s55, s63, 0
	v_lshlrev_b64 v[128:129], 8, v[128:129]
	v_or_b32_e32 v145, 24, v171
	v_lshl_add_u64 v[128:129], s[54:55], 0, v[128:129]
	v_or_b32_e32 v146, v145, v170
	v_lshl_add_u64 v[128:129], v[128:129], 0, v[152:153]
	s_mov_b64 s[6:7], -1
	s_and_b64 vcc, exec, s[4:5]
	v_or_b32_e32 v136, s52, v146
	global_store_dword v[128:129], v120, off nt
	global_store_dword v[128:129], v121, off offset:256 nt
	global_store_dword v[128:129], v122, off offset:512 nt
	global_store_dword v[128:129], v123, off offset:768 nt
	s_cbranch_vccnz .LBB0_561
	v_or_b32_e32 v128, s52, v146
	s_mov_b64 s[6:7], 0

.LBB0_564:
	s_waitcnt vmcnt(12)
	v_lshl_add_u32 v148, v129, 3, v139
	v_ashrrev_i32_e32 v149, 31, v148
	s_lshl_b32 s7, s76, 2
	v_lshlrev_b64 v[148:149], s6, v[148:149]
	v_mov_b32_e32 v129, v153
	s_add_u32 s54, s62, s7
	v_lshl_add_u64 v[128:129], v[148:149], 0, v[128:129]
	s_addc_u32 s55, s63, 0
	v_lshlrev_b64 v[128:129], 8, v[128:129]
	v_lshl_add_u64 v[128:129], s[54:55], 0, v[128:129]
	v_lshl_add_u64 v[128:129], v[128:129], 0, v[152:153]
	global_store_dword v[128:129], v124, off nt
	global_store_dword v[128:129], v125, off offset:256 nt
	global_store_dword v[128:129], v126, off offset:512 nt
	global_store_dword v[128:129], v127, off offset:768 nt
	v_lshlrev_b32_e32 v128, 14, v209
	v_mov_b32_e32 v129, v153
	v_cvt_pk_bf16_f32 v112, v112, v113
	v_cvt_pk_bf16_f32 v113, v114, v115
	v_cvt_pk_bf16_f32 v114, v116, v117
	v_cvt_pk_bf16_f32 v115, v118, v119
	v_lshl_add_u64 v[128:129], s[20:21], 0, v[128:129]
	v_permlane32_swap_b32_e32 v112, v114
	v_permlane32_swap_b32_e32 v113, v115
	s_mov_b64 s[6:7], -1
	s_and_b64 vcc, exec, s[0:1]
	v_lshl_add_u32 v116, s34, 3, v139
	s_cbranch_vccz .LBB0_566
	v_ashrrev_i32_e32 v117, 31, v116
	v_lshlrev_b64 v[118:119], 20, v[116:117]
	v_lshl_add_u64 v[118:119], v[128:129], 0, v[118:119]
	s_mov_b64 s[6:7], 0

.LBB0_568:
	v_lshlrev_b32_e32 v174, 1, v117
	v_mov_b32_e32 v175, v153
	v_lshl_add_u64 v[118:119], v[118:119], 0, v[174:175]
	global_store_dwordx4 v[118:119], v[112:115], off nt
	s_and_b64 vcc, exec, s[4:5]
	s_mov_b64 s[0:1], -1
	v_cvt_pk_bf16_f32 v112, v120, v121
	v_cvt_pk_bf16_f32 v113, v122, v123
	v_cvt_pk_bf16_f32 v114, v124, v125
	v_cvt_pk_bf16_f32 v115, v126, v127
	s_nop 0
	v_permlane32_swap_b32_e32 v112, v114
	v_permlane32_swap_b32_e32 v113, v115
	s_cbranch_vccnz .LBB0_570
	v_ashrrev_i32_e32 v117, 31, v116
	v_lshlrev_b64 v[118:119], 20, v[116:117]
	v_lshl_add_u64 v[118:119], v[128:129], 0, v[118:119]
	s_mov_b64 s[0:1], 0

.LBB0_572:
	v_lshlrev_b32_e32 v126, 1, v117
	v_mov_b32_e32 v127, v153
	v_lshl_add_u64 v[118:119], v[118:119], 0, v[126:127]
	s_and_b64 vcc, exec, s[4:5]
	s_mov_b64 s[0:1], -1
	global_store_dwordx4 v[118:119], v[112:115], off nt
	s_cbranch_vccnz .LBB0_574
	s_nop 0
	v_or_b32_e32 v112, s52, v172
	s_mov_b64 s[0:1], 0

.LBB0_577:
	v_lshl_add_u32 v114, v113, 3, v139
	v_ashrrev_i32_e32 v115, 31, v114
	s_lshl_b32 s1, s6, 2
	v_lshlrev_b64 v[114:115], s0, v[114:115]
	v_mov_b32_e32 v113, v153
	s_add_u32 s6, s62, s1
	v_lshl_add_u64 v[112:113], v[114:115], 0, v[112:113]
	s_addc_u32 s7, s63, 0
	v_lshlrev_b64 v[112:113], 8, v[112:113]
	v_lshl_add_u64 v[112:113], s[6:7], 0, v[112:113]
	v_lshl_add_u64 v[112:113], v[112:113], 0, v[152:153]
	s_and_b64 vcc, exec, s[4:5]
	s_mov_b64 s[0:1], -1
	global_store_dword v[112:113], v96, off offset:128 nt
	global_store_dword v[112:113], v97, off offset:384 nt
	global_store_dword v[112:113], v98, off offset:640 nt
	global_store_dword v[112:113], v99, off offset:896 nt
	s_cbranch_vccnz .LBB0_579
	v_or_b32_e32 v112, s52, v131
	s_mov_b64 s[0:1], 0

.LBB0_582:
	v_lshl_add_u32 v114, v113, 3, v139
	v_ashrrev_i32_e32 v115, 31, v114
	s_lshl_b32 s1, s6, 2
	v_lshlrev_b64 v[114:115], s0, v[114:115]
	v_mov_b32_e32 v113, v153
	s_add_u32 s6, s62, s1
	v_lshl_add_u64 v[112:113], v[114:115], 0, v[112:113]
	s_addc_u32 s7, s63, 0
	v_lshlrev_b64 v[112:113], 8, v[112:113]
	v_lshl_add_u64 v[112:113], s[6:7], 0, v[112:113]
	v_lshl_add_u64 v[112:113], v[112:113], 0, v[152:153]
	s_and_b64 vcc, exec, s[4:5]
	s_mov_b64 s[0:1], -1
	global_store_dword v[112:113], v100, off offset:128 nt
	global_store_dword v[112:113], v101, off offset:384 nt
	global_store_dword v[112:113], v102, off offset:640 nt
	global_store_dword v[112:113], v103, off offset:896 nt
	s_cbranch_vccnz .LBB0_584
	v_or_b32_e32 v112, s52, v147
	s_mov_b64 s[0:1], 0

.LBB0_587:
	v_lshl_add_u32 v114, v113, 3, v139
	v_ashrrev_i32_e32 v115, 31, v114
	s_lshl_b32 s1, s6, 2
	v_lshlrev_b64 v[114:115], s0, v[114:115]
	v_mov_b32_e32 v113, v153
	s_add_u32 s6, s62, s1
	v_lshl_add_u64 v[112:113], v[114:115], 0, v[112:113]
	s_addc_u32 s7, s63, 0
	v_lshlrev_b64 v[112:113], 8, v[112:113]
	v_lshl_add_u64 v[112:113], s[6:7], 0, v[112:113]
	v_lshl_add_u64 v[112:113], v[112:113], 0, v[152:153]
	s_and_b64 vcc, exec, s[4:5]
	s_mov_b64 s[0:1], -1
	global_store_dword v[112:113], v104, off offset:128 nt
	global_store_dword v[112:113], v105, off offset:384 nt
	global_store_dword v[112:113], v106, off offset:640 nt
	global_store_dword v[112:113], v107, off offset:896 nt
	s_cbranch_vccnz .LBB0_589
	v_or_b32_e32 v112, s52, v146
	s_mov_b64 s[0:1], 0

.LBB0_592:
	v_lshl_add_u32 v118, v113, 3, v139
	v_ashrrev_i32_e32 v119, 31, v118
	s_lshl_b32 s1, s6, 2
	v_lshlrev_b64 v[118:119], s0, v[118:119]
	v_mov_b32_e32 v113, v153
	s_add_u32 s6, s62, s1
	v_lshl_add_u64 v[112:113], v[118:119], 0, v[112:113]
	s_addc_u32 s7, s63, 0
	v_lshlrev_b64 v[112:113], 8, v[112:113]
	v_lshl_add_u64 v[112:113], s[6:7], 0, v[112:113]
	v_or_b32_e32 v114, 32, v209
	v_lshl_add_u64 v[112:113], v[112:113], 0, v[152:153]
	global_store_dword v[112:113], v108, off offset:128 nt
	global_store_dword v[112:113], v109, off offset:384 nt
	global_store_dword v[112:113], v110, off offset:640 nt
	global_store_dword v[112:113], v111, off offset:896 nt
	v_lshlrev_b32_e32 v112, 14, v114
	v_mov_b32_e32 v113, v153
	v_cvt_pk_bf16_f32 v96, v96, v97
	v_cvt_pk_bf16_f32 v97, v98, v99
	v_cvt_pk_bf16_f32 v98, v100, v101
	v_cvt_pk_bf16_f32 v99, v102, v103
	v_lshl_add_u64 v[112:113], s[20:21], 0, v[112:113]
	v_permlane32_swap_b32_e32 v96, v98
	v_permlane32_swap_b32_e32 v97, v99
	s_and_b64 vcc, exec, s[4:5]
	s_mov_b64 s[0:1], -1
	s_cbranch_vccnz .LBB0_594
	v_ashrrev_i32_e32 v117, 31, v116
	v_lshlrev_b64 v[100:101], 20, v[116:117]
	v_lshl_add_u64 v[100:101], v[112:113], 0, v[100:101]
	s_mov_b64 s[0:1], 0

.LBB0_596:
	v_lshlrev_b32_e32 v102, 1, v102
	v_mov_b32_e32 v103, v153
	v_lshl_add_u64 v[100:101], v[100:101], 0, v[102:103]
	global_store_dwordx4 v[100:101], v[96:99], off nt
	s_and_b64 vcc, exec, s[4:5]
	s_mov_b64 s[0:1], -1
	v_cvt_pk_bf16_f32 v96, v104, v105
	v_cvt_pk_bf16_f32 v97, v106, v107
	v_cvt_pk_bf16_f32 v98, v108, v109
	v_cvt_pk_bf16_f32 v99, v110, v111
	s_nop 0
	v_permlane32_swap_b32_e32 v96, v98
	v_permlane32_swap_b32_e32 v97, v99
	s_cbranch_vccnz .LBB0_598
	v_ashrrev_i32_e32 v117, 31, v116
	v_lshlrev_b64 v[100:101], 20, v[116:117]
	v_lshl_add_u64 v[100:101], v[112:113], 0, v[100:101]
	s_mov_b64 s[0:1], 0

.LBB0_600:
	v_lshlrev_b32_e32 v102, 1, v102
	v_mov_b32_e32 v103, v153
	v_lshl_add_u64 v[100:101], v[100:101], 0, v[102:103]
	s_and_b64 vcc, exec, s[4:5]
	s_mov_b64 s[0:1], -1
	global_store_dwordx4 v[100:101], v[96:99], off nt
	s_cbranch_vccnz .LBB0_602
	s_nop 0
	v_or_b32_e32 v96, s52, v172
	s_mov_b64 s[0:1], 0

.LBB0_605:
	v_or_b32_e32 v98, 1, v139
	v_lshl_add_u32 v100, v97, 3, v98
	v_ashrrev_i32_e32 v101, 31, v100
	s_lshl_b32 s1, s6, 2
	v_lshlrev_b64 v[100:101], s0, v[100:101]
	v_mov_b32_e32 v97, v153
	s_add_u32 s6, s62, s1
	v_lshl_add_u64 v[96:97], v[100:101], 0, v[96:97]
	s_addc_u32 s7, s63, 0
	v_lshlrev_b64 v[96:97], 8, v[96:97]
	v_lshl_add_u64 v[96:97], s[6:7], 0, v[96:97]
	v_lshl_add_u64 v[96:97], v[96:97], 0, v[152:153]
	s_and_b64 vcc, exec, s[4:5]
	s_mov_b64 s[0:1], -1
	global_store_dword v[96:97], v80, off nt
	global_store_dword v[96:97], v81, off offset:256 nt
	global_store_dword v[96:97], v82, off offset:512 nt
	global_store_dword v[96:97], v83, off offset:768 nt
	s_cbranch_vccnz .LBB0_607
	v_or_b32_e32 v96, s52, v131
	s_mov_b64 s[0:1], 0

.LBB0_610:
	v_lshl_add_u32 v100, v97, 3, v98
	v_ashrrev_i32_e32 v101, 31, v100
	s_lshl_b32 s1, s6, 2
	v_lshlrev_b64 v[100:101], s0, v[100:101]
	v_mov_b32_e32 v97, v153
	s_add_u32 s6, s62, s1
	v_lshl_add_u64 v[96:97], v[100:101], 0, v[96:97]
	s_addc_u32 s7, s63, 0
	v_lshlrev_b64 v[96:97], 8, v[96:97]
	v_lshl_add_u64 v[96:97], s[6:7], 0, v[96:97]
	v_lshl_add_u64 v[96:97], v[96:97], 0, v[152:153]
	s_and_b64 vcc, exec, s[4:5]
	s_mov_b64 s[0:1], -1
	global_store_dword v[96:97], v84, off nt
	global_store_dword v[96:97], v85, off offset:256 nt
	global_store_dword v[96:97], v86, off offset:512 nt
	global_store_dword v[96:97], v87, off offset:768 nt
	s_cbranch_vccnz .LBB0_612
	v_or_b32_e32 v96, s52, v147
	s_mov_b64 s[0:1], 0

.LBB0_615:
	v_lshl_add_u32 v100, v97, 3, v98
	v_ashrrev_i32_e32 v101, 31, v100
	s_lshl_b32 s1, s6, 2
	v_lshlrev_b64 v[100:101], s0, v[100:101]
	v_mov_b32_e32 v97, v153
	s_add_u32 s6, s62, s1
	v_lshl_add_u64 v[96:97], v[100:101], 0, v[96:97]
	s_addc_u32 s7, s63, 0
	v_lshlrev_b64 v[96:97], 8, v[96:97]
	v_lshl_add_u64 v[96:97], s[6:7], 0, v[96:97]
	v_lshl_add_u64 v[96:97], v[96:97], 0, v[152:153]
	s_and_b64 vcc, exec, s[4:5]
	s_mov_b64 s[0:1], -1
	global_store_dword v[96:97], v88, off nt
	global_store_dword v[96:97], v89, off offset:256 nt
	global_store_dword v[96:97], v90, off offset:512 nt
	global_store_dword v[96:97], v91, off offset:768 nt
	s_cbranch_vccnz .LBB0_617
	v_or_b32_e32 v96, s52, v146
	s_mov_b64 s[0:1], 0

.LBB0_620:
	v_lshl_add_u32 v100, v97, 3, v98
	v_ashrrev_i32_e32 v101, 31, v100
	s_lshl_b32 s1, s6, 2
	v_lshlrev_b64 v[100:101], s0, v[100:101]
	v_mov_b32_e32 v97, v153
	s_add_u32 s6, s62, s1
	v_lshl_add_u64 v[96:97], v[100:101], 0, v[96:97]
	s_addc_u32 s7, s63, 0
	v_lshlrev_b64 v[96:97], 8, v[96:97]
	v_lshl_add_u64 v[96:97], s[6:7], 0, v[96:97]
	v_cvt_pk_bf16_f32 v80, v80, v81
	v_cvt_pk_bf16_f32 v81, v82, v83
	v_cvt_pk_bf16_f32 v82, v84, v85
	v_cvt_pk_bf16_f32 v83, v86, v87
	v_lshl_add_u64 v[96:97], v[96:97], 0, v[152:153]
	v_permlane32_swap_b32_e32 v80, v82
	v_permlane32_swap_b32_e32 v81, v83
	s_mov_b64 s[0:1], -1
	s_and_b64 vcc, exec, s[4:5]
	v_lshl_add_u32 v84, s34, 3, v98
	global_store_dword v[96:97], v92, off nt
	global_store_dword v[96:97], v93, off offset:256 nt
	global_store_dword v[96:97], v94, off offset:512 nt
	global_store_dword v[96:97], v95, off offset:768 nt
	s_cbranch_vccnz .LBB0_622
	v_ashrrev_i32_e32 v85, 31, v84
	v_lshlrev_b64 v[86:87], 20, v[84:85]
	v_lshl_add_u64 v[86:87], v[128:129], 0, v[86:87]
	s_mov_b64 s[0:1], 0

.LBB0_624:
	v_lshlrev_b32_e32 v100, 1, v85
	v_mov_b32_e32 v101, v153
	v_lshl_add_u64 v[86:87], v[86:87], 0, v[100:101]
	global_store_dwordx4 v[86:87], v[80:83], off nt
	s_and_b64 vcc, exec, s[4:5]
	s_mov_b64 s[0:1], -1
	v_cvt_pk_bf16_f32 v80, v88, v89
	v_cvt_pk_bf16_f32 v81, v90, v91
	v_cvt_pk_bf16_f32 v82, v92, v93
	v_cvt_pk_bf16_f32 v83, v94, v95
	s_nop 0
	v_permlane32_swap_b32_e32 v80, v82
	v_permlane32_swap_b32_e32 v81, v83
	s_cbranch_vccnz .LBB0_626
	v_ashrrev_i32_e32 v85, 31, v84
	v_lshlrev_b64 v[86:87], 20, v[84:85]
	v_lshl_add_u64 v[86:87], v[128:129], 0, v[86:87]
	s_mov_b64 s[0:1], 0

.LBB0_628:
	v_lshlrev_b32_e32 v90, 1, v85
	v_mov_b32_e32 v91, v153
	v_lshl_add_u64 v[86:87], v[86:87], 0, v[90:91]
	s_and_b64 vcc, exec, s[4:5]
	s_mov_b64 s[0:1], -1
	global_store_dwordx4 v[86:87], v[80:83], off nt
	s_cbranch_vccnz .LBB0_630
	s_mov_b64 s[0:1], 0

.LBB0_633:
	v_lshl_add_u32 v80, v80, 3, v98
	v_ashrrev_i32_e32 v81, 31, v80
	s_lshl_b32 s1, s6, 2
	v_lshlrev_b64 v[80:81], s0, v[80:81]
	v_mov_b32_e32 v131, v153
	s_add_u32 s6, s62, s1
	v_lshl_add_u64 v[80:81], v[80:81], 0, v[130:131]
	s_addc_u32 s7, s63, 0
	v_lshlrev_b64 v[80:81], 8, v[80:81]
	v_lshl_add_u64 v[80:81], s[6:7], 0, v[80:81]
	v_lshl_add_u64 v[80:81], v[80:81], 0, v[152:153]
	s_and_b64 vcc, exec, s[4:5]
	s_mov_b64 s[0:1], -1
	global_store_dword v[80:81], v64, off offset:128 nt
	global_store_dword v[80:81], v65, off offset:384 nt
	global_store_dword v[80:81], v66, off offset:640 nt
	global_store_dword v[80:81], v67, off offset:896 nt
	s_cbranch_vccnz .LBB0_635
	s_mov_b64 s[0:1], 0

.LBB0_638:
	v_lshl_add_u32 v80, v80, 3, v98
	v_ashrrev_i32_e32 v81, 31, v80
	s_lshl_b32 s1, s6, 2
	v_lshlrev_b64 v[80:81], s0, v[80:81]
	v_mov_b32_e32 v133, v153
	s_add_u32 s6, s62, s1
	v_lshl_add_u64 v[80:81], v[80:81], 0, v[132:133]
	s_addc_u32 s7, s63, 0
	v_lshlrev_b64 v[80:81], 8, v[80:81]
	v_lshl_add_u64 v[80:81], s[6:7], 0, v[80:81]
	v_lshl_add_u64 v[80:81], v[80:81], 0, v[152:153]
	s_and_b64 vcc, exec, s[4:5]
	s_mov_b64 s[0:1], -1
	global_store_dword v[80:81], v68, off offset:128 nt
	global_store_dword v[80:81], v69, off offset:384 nt
	global_store_dword v[80:81], v70, off offset:640 nt
	global_store_dword v[80:81], v71, off offset:896 nt
	s_cbranch_vccnz .LBB0_640
	s_mov_b64 s[0:1], 0

.LBB0_643:
	v_lshl_add_u32 v80, v80, 3, v98
	v_ashrrev_i32_e32 v81, 31, v80
	s_lshl_b32 s1, s6, 2
	v_lshlrev_b64 v[80:81], s0, v[80:81]
	v_mov_b32_e32 v135, v153
	s_add_u32 s6, s62, s1
	v_lshl_add_u64 v[80:81], v[80:81], 0, v[134:135]
	s_addc_u32 s7, s63, 0
	v_lshlrev_b64 v[80:81], 8, v[80:81]
	v_lshl_add_u64 v[80:81], s[6:7], 0, v[80:81]
	v_lshl_add_u64 v[80:81], v[80:81], 0, v[152:153]
	s_and_b64 vcc, exec, s[4:5]
	s_mov_b64 s[0:1], -1
	global_store_dword v[80:81], v72, off offset:128 nt
	global_store_dword v[80:81], v73, off offset:384 nt
	global_store_dword v[80:81], v74, off offset:640 nt
	global_store_dword v[80:81], v75, off offset:896 nt
	s_cbranch_vccnz .LBB0_645
	s_mov_b64 s[0:1], 0

.LBB0_648:
	v_lshl_add_u32 v80, v80, 3, v98
	v_ashrrev_i32_e32 v81, 31, v80
	s_lshl_b32 s1, s6, 2
	v_lshlrev_b64 v[80:81], s0, v[80:81]
	v_mov_b32_e32 v137, v153
	s_add_u32 s6, s62, s1
	v_lshl_add_u64 v[80:81], v[80:81], 0, v[136:137]
	s_addc_u32 s7, s63, 0
	v_lshlrev_b64 v[80:81], 8, v[80:81]
	v_lshl_add_u64 v[80:81], s[6:7], 0, v[80:81]
	v_cvt_pk_bf16_f32 v64, v64, v65
	v_cvt_pk_bf16_f32 v65, v66, v67
	v_cvt_pk_bf16_f32 v66, v68, v69
	v_cvt_pk_bf16_f32 v67, v70, v71
	v_lshl_add_u64 v[80:81], v[80:81], 0, v[152:153]
	v_permlane32_swap_b32_e32 v64, v66
	v_permlane32_swap_b32_e32 v65, v67
	s_and_b64 vcc, exec, s[4:5]
	s_mov_b64 s[0:1], -1
	global_store_dword v[80:81], v76, off offset:128 nt
	global_store_dword v[80:81], v77, off offset:384 nt
	global_store_dword v[80:81], v78, off offset:640 nt
	global_store_dword v[80:81], v79, off offset:896 nt
	s_cbranch_vccnz .LBB0_650
	v_ashrrev_i32_e32 v85, 31, v84
	v_lshlrev_b64 v[68:69], 20, v[84:85]
	v_lshl_add_u64 v[68:69], v[112:113], 0, v[68:69]
	s_mov_b64 s[0:1], 0

.LBB0_652:
	v_lshlrev_b32_e32 v70, 1, v143
	v_mov_b32_e32 v71, v153
	v_lshl_add_u64 v[68:69], v[68:69], 0, v[70:71]
	global_store_dwordx4 v[68:69], v[64:67], off nt
	s_and_b64 vcc, exec, s[4:5]
	s_mov_b64 s[0:1], -1
	v_cvt_pk_bf16_f32 v64, v72, v73
	v_cvt_pk_bf16_f32 v65, v74, v75
	v_cvt_pk_bf16_f32 v66, v76, v77
	v_cvt_pk_bf16_f32 v67, v78, v79
	s_nop 0
	v_permlane32_swap_b32_e32 v64, v66
	v_permlane32_swap_b32_e32 v65, v67
	s_cbranch_vccnz .LBB0_654
	v_ashrrev_i32_e32 v85, 31, v84
	v_lshlrev_b64 v[68:69], 20, v[84:85]
	v_lshl_add_u64 v[68:69], v[112:113], 0, v[68:69]
	s_mov_b64 s[0:1], 0

.LBB0_656:
	v_lshlrev_b32_e32 v70, 1, v121
	v_mov_b32_e32 v71, v153
	v_or_b32_e32 v76, 32, v171
	v_lshl_add_u64 v[68:69], v[68:69], 0, v[70:71]
	v_or_b32_e32 v82, v76, v170
	global_store_dwordx4 v[68:69], v[64:67], off nt
	s_mov_b64 s[0:1], -1
	s_and_b64 vcc, exec, s[4:5]
	v_or_b32_e32 v64, s52, v82
	s_cbranch_vccnz .LBB0_658
	v_or_b32_e32 v66, s52, v82
	s_mov_b64 s[0:1], 0

.LBB0_661:
	v_lshl_add_u32 v68, v67, 3, v139
	v_ashrrev_i32_e32 v69, 31, v68
	s_lshl_b32 s1, s6, 2
	v_lshlrev_b64 v[68:69], s0, v[68:69]
	v_mov_b32_e32 v67, v153
	s_add_u32 s6, s62, s1
	v_lshl_add_u64 v[66:67], v[68:69], 0, v[66:67]
	s_addc_u32 s7, s63, 0
	v_lshlrev_b64 v[66:67], 8, v[66:67]
	v_lshl_add_u64 v[66:67], s[6:7], 0, v[66:67]
	v_or_b32_e32 v77, 40, v171
	v_lshl_add_u64 v[66:67], v[66:67], 0, v[152:153]
	v_or_b32_e32 v78, v77, v170
	global_store_dword v[66:67], v48, off nt
	global_store_dword v[66:67], v49, off offset:256 nt
	global_store_dword v[66:67], v50, off offset:512 nt
	global_store_dword v[66:67], v51, off offset:768 nt
	s_mov_b64 s[0:1], -1
	s_and_b64 vcc, exec, s[4:5]
	v_or_b32_e32 v66, s52, v78
	s_cbranch_vccnz .LBB0_663
	v_or_b32_e32 v68, s52, v78
	s_mov_b64 s[0:1], 0

.LBB0_666:
	v_lshl_add_u32 v70, v69, 3, v139
	v_ashrrev_i32_e32 v71, 31, v70
	s_lshl_b32 s1, s6, 2
	v_lshlrev_b64 v[70:71], s0, v[70:71]
	v_mov_b32_e32 v69, v153
	s_add_u32 s6, s62, s1
	v_lshl_add_u64 v[68:69], v[70:71], 0, v[68:69]
	s_addc_u32 s7, s63, 0
	v_lshlrev_b64 v[68:69], 8, v[68:69]
	v_lshl_add_u64 v[68:69], s[6:7], 0, v[68:69]
	v_or_b32_e32 v79, 48, v171
	v_lshl_add_u64 v[68:69], v[68:69], 0, v[152:153]
	v_or_b32_e32 v83, v79, v170
	global_store_dword v[68:69], v52, off nt
	global_store_dword v[68:69], v53, off offset:256 nt
	global_store_dword v[68:69], v54, off offset:512 nt
	global_store_dword v[68:69], v55, off offset:768 nt
	s_mov_b64 s[0:1], -1
	s_and_b64 vcc, exec, s[4:5]
	v_or_b32_e32 v68, s52, v83
	s_cbranch_vccnz .LBB0_668
	v_or_b32_e32 v70, s52, v83
	s_mov_b64 s[0:1], 0

.LBB0_671:
	v_lshl_add_u32 v72, v71, 3, v139
	v_ashrrev_i32_e32 v73, 31, v72
	s_lshl_b32 s1, s6, 2
	v_lshlrev_b64 v[72:73], s0, v[72:73]
	v_mov_b32_e32 v71, v153
	s_add_u32 s6, s62, s1
	v_lshl_add_u64 v[70:71], v[72:73], 0, v[70:71]
	s_addc_u32 s7, s63, 0
	v_lshlrev_b64 v[70:71], 8, v[70:71]
	v_lshl_add_u64 v[70:71], s[6:7], 0, v[70:71]
	v_or_b32_e32 v80, 56, v171
	v_lshl_add_u64 v[70:71], v[70:71], 0, v[152:153]
	v_or_b32_e32 v81, v80, v170
	global_store_dword v[70:71], v56, off nt
	global_store_dword v[70:71], v57, off offset:256 nt
	global_store_dword v[70:71], v58, off offset:512 nt
	global_store_dword v[70:71], v59, off offset:768 nt
	s_mov_b64 s[0:1], -1
	s_and_b64 vcc, exec, s[4:5]
	v_or_b32_e32 v70, s52, v81
	s_cbranch_vccnz .LBB0_673
	v_or_b32_e32 v72, s52, v81
	s_mov_b64 s[0:1], 0

.LBB0_676:
	v_lshl_add_u32 v86, v73, 3, v139
	v_ashrrev_i32_e32 v87, 31, v86
	s_lshl_b32 s1, s6, 2
	v_lshlrev_b64 v[86:87], s0, v[86:87]
	v_mov_b32_e32 v73, v153
	s_add_u32 s6, s62, s1
	v_lshl_add_u64 v[72:73], v[86:87], 0, v[72:73]
	s_addc_u32 s7, s63, 0
	v_lshlrev_b64 v[72:73], 8, v[72:73]
	v_lshl_add_u64 v[72:73], s[6:7], 0, v[72:73]
	v_cvt_pk_bf16_f32 v48, v48, v49
	v_cvt_pk_bf16_f32 v49, v50, v51
	v_cvt_pk_bf16_f32 v50, v52, v53
	v_cvt_pk_bf16_f32 v51, v54, v55
	v_lshl_add_u64 v[72:73], v[72:73], 0, v[152:153]
	v_permlane32_swap_b32_e32 v48, v50
	v_permlane32_swap_b32_e32 v49, v51
	s_and_b64 vcc, exec, s[4:5]
	s_mov_b64 s[0:1], -1
	global_store_dword v[72:73], v60, off nt
	global_store_dword v[72:73], v61, off offset:256 nt
	global_store_dword v[72:73], v62, off offset:512 nt
	global_store_dword v[72:73], v63, off offset:768 nt
	s_cbranch_vccnz .LBB0_678
	v_ashrrev_i32_e32 v117, 31, v116
	v_lshlrev_b64 v[52:53], 20, v[116:117]
	v_lshl_add_u64 v[52:53], v[128:129], 0, v[52:53]
	s_mov_b64 s[0:1], 0

.LBB0_680:
	v_lshlrev_b32_e32 v86, 1, v55
	v_mov_b32_e32 v87, v153
	v_lshl_add_u64 v[52:53], v[52:53], 0, v[86:87]
	global_store_dwordx4 v[52:53], v[48:51], off nt
	s_and_b64 vcc, exec, s[4:5]
	s_mov_b64 s[0:1], -1
	v_cvt_pk_bf16_f32 v48, v56, v57
	v_cvt_pk_bf16_f32 v49, v58, v59
	v_cvt_pk_bf16_f32 v50, v60, v61
	v_cvt_pk_bf16_f32 v51, v62, v63
	s_nop 0
	v_permlane32_swap_b32_e32 v48, v50
	v_permlane32_swap_b32_e32 v49, v51
	s_cbranch_vccnz .LBB0_682
	v_ashrrev_i32_e32 v117, 31, v116
	v_lshlrev_b64 v[52:53], 20, v[116:117]
	v_lshl_add_u64 v[52:53], v[128:129], 0, v[52:53]
	s_mov_b64 s[0:1], 0

.LBB0_684:
	v_lshlrev_b32_e32 v60, 1, v59
	v_mov_b32_e32 v61, v153
	v_lshl_add_u64 v[52:53], v[52:53], 0, v[60:61]
	s_and_b64 vcc, exec, s[4:5]
	s_mov_b64 s[0:1], -1
	global_store_dwordx4 v[52:53], v[48:51], off nt
	s_cbranch_vccnz .LBB0_686
	s_nop 0
	v_or_b32_e32 v48, s52, v82
	s_mov_b64 s[0:1], 0

.LBB0_689:
	v_lshl_add_u32 v50, v49, 3, v139
	v_ashrrev_i32_e32 v51, 31, v50
	s_lshl_b32 s1, s6, 2
	v_lshlrev_b64 v[50:51], s0, v[50:51]
	v_mov_b32_e32 v49, v153
	s_add_u32 s6, s62, s1
	v_lshl_add_u64 v[48:49], v[50:51], 0, v[48:49]
	s_addc_u32 s7, s63, 0
	v_lshlrev_b64 v[48:49], 8, v[48:49]
	v_lshl_add_u64 v[48:49], s[6:7], 0, v[48:49]
	v_lshl_add_u64 v[48:49], v[48:49], 0, v[152:153]
	s_and_b64 vcc, exec, s[4:5]
	s_mov_b64 s[0:1], -1
	global_store_dword v[48:49], v32, off offset:128 nt
	global_store_dword v[48:49], v33, off offset:384 nt
	global_store_dword v[48:49], v34, off offset:640 nt
	global_store_dword v[48:49], v35, off offset:896 nt
	s_cbranch_vccnz .LBB0_691
	v_or_b32_e32 v48, s52, v78
	s_mov_b64 s[0:1], 0

.LBB0_694:
	v_lshl_add_u32 v50, v49, 3, v139
	v_ashrrev_i32_e32 v51, 31, v50
	s_lshl_b32 s1, s6, 2
	v_lshlrev_b64 v[50:51], s0, v[50:51]
	v_mov_b32_e32 v49, v153
	s_add_u32 s6, s62, s1
	v_lshl_add_u64 v[48:49], v[50:51], 0, v[48:49]
	s_addc_u32 s7, s63, 0
	v_lshlrev_b64 v[48:49], 8, v[48:49]
	v_lshl_add_u64 v[48:49], s[6:7], 0, v[48:49]
	v_lshl_add_u64 v[48:49], v[48:49], 0, v[152:153]
	s_and_b64 vcc, exec, s[4:5]
	s_mov_b64 s[0:1], -1
	global_store_dword v[48:49], v36, off offset:128 nt
	global_store_dword v[48:49], v37, off offset:384 nt
	global_store_dword v[48:49], v38, off offset:640 nt
	global_store_dword v[48:49], v39, off offset:896 nt
	s_cbranch_vccnz .LBB0_696
	v_or_b32_e32 v48, s52, v83
	s_mov_b64 s[0:1], 0

.LBB0_699:
	v_lshl_add_u32 v50, v49, 3, v139
	v_ashrrev_i32_e32 v51, 31, v50
	s_lshl_b32 s1, s6, 2
	v_lshlrev_b64 v[50:51], s0, v[50:51]
	v_mov_b32_e32 v49, v153
	s_add_u32 s6, s62, s1
	v_lshl_add_u64 v[48:49], v[50:51], 0, v[48:49]
	s_addc_u32 s7, s63, 0
	v_lshlrev_b64 v[48:49], 8, v[48:49]
	v_lshl_add_u64 v[48:49], s[6:7], 0, v[48:49]
	v_lshl_add_u64 v[48:49], v[48:49], 0, v[152:153]
	s_and_b64 vcc, exec, s[4:5]
	s_mov_b64 s[0:1], -1
	global_store_dword v[48:49], v40, off offset:128 nt
	global_store_dword v[48:49], v41, off offset:384 nt
	global_store_dword v[48:49], v42, off offset:640 nt
	global_store_dword v[48:49], v43, off offset:896 nt
	s_cbranch_vccnz .LBB0_701
	v_or_b32_e32 v48, s52, v81
	s_mov_b64 s[0:1], 0

.LBB0_704:
	v_lshl_add_u32 v50, v49, 3, v139
	v_ashrrev_i32_e32 v51, 31, v50
	s_lshl_b32 s1, s6, 2
	v_lshlrev_b64 v[50:51], s0, v[50:51]
	v_mov_b32_e32 v49, v153
	s_add_u32 s6, s62, s1
	v_lshl_add_u64 v[48:49], v[50:51], 0, v[48:49]
	s_addc_u32 s7, s63, 0
	v_lshlrev_b64 v[48:49], 8, v[48:49]
	v_lshl_add_u64 v[48:49], s[6:7], 0, v[48:49]
	v_cvt_pk_bf16_f32 v32, v32, v33
	v_cvt_pk_bf16_f32 v33, v34, v35
	v_cvt_pk_bf16_f32 v34, v36, v37
	v_cvt_pk_bf16_f32 v35, v38, v39
	v_lshl_add_u64 v[48:49], v[48:49], 0, v[152:153]
	v_permlane32_swap_b32_e32 v32, v34
	v_permlane32_swap_b32_e32 v33, v35
	s_and_b64 vcc, exec, s[4:5]
	s_mov_b64 s[0:1], -1
	global_store_dword v[48:49], v44, off offset:128 nt
	global_store_dword v[48:49], v45, off offset:384 nt
	global_store_dword v[48:49], v46, off offset:640 nt
	global_store_dword v[48:49], v47, off offset:896 nt
	s_cbranch_vccnz .LBB0_706
	v_ashrrev_i32_e32 v117, 31, v116
	v_lshlrev_b64 v[36:37], 20, v[116:117]
	v_lshl_add_u64 v[36:37], v[112:113], 0, v[36:37]
	s_mov_b64 s[0:1], 0

.LBB0_708:
	v_lshlrev_b32_e32 v38, 1, v38
	v_mov_b32_e32 v39, v153
	v_lshl_add_u64 v[36:37], v[36:37], 0, v[38:39]
	global_store_dwordx4 v[36:37], v[32:35], off nt
	s_and_b64 vcc, exec, s[4:5]
	s_mov_b64 s[0:1], -1
	v_cvt_pk_bf16_f32 v32, v40, v41
	v_cvt_pk_bf16_f32 v33, v42, v43
	v_cvt_pk_bf16_f32 v34, v44, v45
	v_cvt_pk_bf16_f32 v35, v46, v47
	s_nop 0
	v_permlane32_swap_b32_e32 v32, v34
	v_permlane32_swap_b32_e32 v33, v35
	s_cbranch_vccnz .LBB0_710
	v_ashrrev_i32_e32 v117, 31, v116
	v_lshlrev_b64 v[36:37], 20, v[116:117]
	v_lshl_add_u64 v[36:37], v[112:113], 0, v[36:37]
	s_mov_b64 s[0:1], 0

.LBB0_712:
	v_lshlrev_b32_e32 v38, 1, v38
	v_mov_b32_e32 v39, v153
	v_lshl_add_u64 v[36:37], v[36:37], 0, v[38:39]
	s_and_b64 vcc, exec, s[4:5]
	s_mov_b64 s[0:1], -1
	global_store_dwordx4 v[36:37], v[32:35], off nt
	s_cbranch_vccnz .LBB0_714
	s_nop 0
	v_or_b32_e32 v32, s52, v82
	s_mov_b64 s[0:1], 0

.LBB0_717:
	v_lshl_add_u32 v34, v33, 3, v98
	v_ashrrev_i32_e32 v35, 31, v34
	s_lshl_b32 s1, s6, 2
	v_lshlrev_b64 v[34:35], s0, v[34:35]
	v_mov_b32_e32 v33, v153
	s_add_u32 s6, s62, s1
	v_lshl_add_u64 v[32:33], v[34:35], 0, v[32:33]
	s_addc_u32 s7, s63, 0
	v_lshlrev_b64 v[32:33], 8, v[32:33]
	v_lshl_add_u64 v[32:33], s[6:7], 0, v[32:33]
	v_lshl_add_u64 v[32:33], v[32:33], 0, v[152:153]
	s_and_b64 vcc, exec, s[4:5]
	s_mov_b64 s[0:1], -1
	global_store_dword v[32:33], v16, off nt
	global_store_dword v[32:33], v17, off offset:256 nt
	global_store_dword v[32:33], v18, off offset:512 nt
	global_store_dword v[32:33], v19, off offset:768 nt
	s_cbranch_vccnz .LBB0_719
	v_or_b32_e32 v32, s52, v78
	s_mov_b64 s[0:1], 0

.LBB0_722:
	v_lshl_add_u32 v34, v33, 3, v98
	v_ashrrev_i32_e32 v35, 31, v34
	s_lshl_b32 s1, s6, 2
	v_lshlrev_b64 v[34:35], s0, v[34:35]
	v_mov_b32_e32 v33, v153
	s_add_u32 s6, s62, s1
	v_lshl_add_u64 v[32:33], v[34:35], 0, v[32:33]
	s_addc_u32 s7, s63, 0
	v_lshlrev_b64 v[32:33], 8, v[32:33]
	v_lshl_add_u64 v[32:33], s[6:7], 0, v[32:33]
	v_lshl_add_u64 v[32:33], v[32:33], 0, v[152:153]
	s_and_b64 vcc, exec, s[4:5]
	s_mov_b64 s[0:1], -1
	global_store_dword v[32:33], v20, off nt
	global_store_dword v[32:33], v21, off offset:256 nt
	global_store_dword v[32:33], v22, off offset:512 nt
	global_store_dword v[32:33], v23, off offset:768 nt
	s_cbranch_vccnz .LBB0_724
	v_or_b32_e32 v32, s52, v83
	s_mov_b64 s[0:1], 0

.LBB0_727:
	v_lshl_add_u32 v34, v33, 3, v98
	v_ashrrev_i32_e32 v35, 31, v34
	s_lshl_b32 s1, s6, 2
	v_lshlrev_b64 v[34:35], s0, v[34:35]
	v_mov_b32_e32 v33, v153
	s_add_u32 s6, s62, s1
	v_lshl_add_u64 v[32:33], v[34:35], 0, v[32:33]
	s_addc_u32 s7, s63, 0
	v_lshlrev_b64 v[32:33], 8, v[32:33]
	v_lshl_add_u64 v[32:33], s[6:7], 0, v[32:33]
	v_lshl_add_u64 v[32:33], v[32:33], 0, v[152:153]
	s_and_b64 vcc, exec, s[4:5]
	s_mov_b64 s[0:1], -1
	global_store_dword v[32:33], v24, off nt
	global_store_dword v[32:33], v25, off offset:256 nt
	global_store_dword v[32:33], v26, off offset:512 nt
	global_store_dword v[32:33], v27, off offset:768 nt
	s_cbranch_vccnz .LBB0_729
	v_or_b32_e32 v32, s52, v81
	s_mov_b64 s[0:1], 0

.LBB0_732:
	v_lshl_add_u32 v34, v33, 3, v98
	v_ashrrev_i32_e32 v35, 31, v34
	s_lshl_b32 s1, s6, 2
	v_lshlrev_b64 v[34:35], s0, v[34:35]
	v_mov_b32_e32 v33, v153
	s_add_u32 s6, s62, s1
	v_lshl_add_u64 v[32:33], v[34:35], 0, v[32:33]
	s_addc_u32 s7, s63, 0
	v_lshlrev_b64 v[32:33], 8, v[32:33]
	v_lshl_add_u64 v[32:33], s[6:7], 0, v[32:33]
	v_cvt_pk_bf16_f32 v16, v16, v17
	v_cvt_pk_bf16_f32 v17, v18, v19
	v_cvt_pk_bf16_f32 v18, v20, v21
	v_cvt_pk_bf16_f32 v19, v22, v23
	v_lshl_add_u64 v[32:33], v[32:33], 0, v[152:153]
	v_permlane32_swap_b32_e32 v16, v18
	v_permlane32_swap_b32_e32 v17, v19
	s_and_b64 vcc, exec, s[4:5]
	s_mov_b64 s[0:1], -1
	global_store_dword v[32:33], v28, off nt
	global_store_dword v[32:33], v29, off offset:256 nt
	global_store_dword v[32:33], v30, off offset:512 nt
	global_store_dword v[32:33], v31, off offset:768 nt
	s_cbranch_vccnz .LBB0_734
	v_ashrrev_i32_e32 v85, 31, v84
	v_lshlrev_b64 v[20:21], 20, v[84:85]
	v_lshl_add_u64 v[20:21], v[128:129], 0, v[20:21]
	s_mov_b64 s[0:1], 0

.LBB0_736:
	v_lshlrev_b32_e32 v34, 1, v23
	v_mov_b32_e32 v35, v153
	v_lshl_add_u64 v[20:21], v[20:21], 0, v[34:35]
	global_store_dwordx4 v[20:21], v[16:19], off nt
	s_and_b64 vcc, exec, s[4:5]
	s_mov_b64 s[0:1], -1
	v_cvt_pk_bf16_f32 v16, v24, v25
	v_cvt_pk_bf16_f32 v17, v26, v27
	v_cvt_pk_bf16_f32 v18, v28, v29
	v_cvt_pk_bf16_f32 v19, v30, v31
	s_nop 0
	v_permlane32_swap_b32_e32 v16, v18
	v_permlane32_swap_b32_e32 v17, v19
	s_cbranch_vccnz .LBB0_738
	v_ashrrev_i32_e32 v85, 31, v84
	v_lshlrev_b64 v[20:21], 20, v[84:85]
	v_lshl_add_u64 v[20:21], v[128:129], 0, v[20:21]
	s_mov_b64 s[0:1], 0

.LBB0_740:
	v_lshlrev_b32_e32 v26, 1, v25
	v_mov_b32_e32 v27, v153
	v_lshl_add_u64 v[20:21], v[20:21], 0, v[26:27]
	s_and_b64 vcc, exec, s[4:5]
	s_mov_b64 s[0:1], -1
	global_store_dwordx4 v[20:21], v[16:19], off nt
	s_cbranch_vccnz .LBB0_742
	s_mov_b64 s[0:1], 0

.LBB0_745:
	v_lshl_add_u32 v16, v16, 3, v98
	v_ashrrev_i32_e32 v17, 31, v16
	s_lshl_b32 s1, s6, 2
	v_lshlrev_b64 v[16:17], s0, v[16:17]
	v_mov_b32_e32 v65, v153
	s_add_u32 s6, s62, s1
	v_lshl_add_u64 v[16:17], v[16:17], 0, v[64:65]
	s_addc_u32 s7, s63, 0
	v_lshlrev_b64 v[16:17], 8, v[16:17]
	v_lshl_add_u64 v[16:17], s[6:7], 0, v[16:17]
	v_lshl_add_u64 v[16:17], v[16:17], 0, v[152:153]
	s_and_b64 vcc, exec, s[4:5]
	s_mov_b64 s[0:1], -1
	global_store_dword v[16:17], v0, off offset:128 nt
	global_store_dword v[16:17], v1, off offset:384 nt
	global_store_dword v[16:17], v2, off offset:640 nt
	global_store_dword v[16:17], v3, off offset:896 nt
	s_cbranch_vccnz .LBB0_747
	s_mov_b64 s[0:1], 0

.LBB0_750:
	v_lshl_add_u32 v16, v16, 3, v98
	v_ashrrev_i32_e32 v17, 31, v16
	s_lshl_b32 s1, s6, 2
	v_lshlrev_b64 v[16:17], s0, v[16:17]
	v_mov_b32_e32 v67, v153
	s_add_u32 s6, s62, s1
	v_lshl_add_u64 v[16:17], v[16:17], 0, v[66:67]
	s_addc_u32 s7, s63, 0
	v_lshlrev_b64 v[16:17], 8, v[16:17]
	v_lshl_add_u64 v[16:17], s[6:7], 0, v[16:17]
	v_lshl_add_u64 v[16:17], v[16:17], 0, v[152:153]
	s_and_b64 vcc, exec, s[4:5]
	s_mov_b64 s[0:1], -1
	global_store_dword v[16:17], v4, off offset:128 nt
	global_store_dword v[16:17], v5, off offset:384 nt
	global_store_dword v[16:17], v6, off offset:640 nt
	global_store_dword v[16:17], v7, off offset:896 nt
	s_cbranch_vccnz .LBB0_752
	s_mov_b64 s[0:1], 0

.LBB0_755:
	v_lshl_add_u32 v16, v16, 3, v98
	v_ashrrev_i32_e32 v17, 31, v16
	s_lshl_b32 s1, s6, 2
	v_lshlrev_b64 v[16:17], s0, v[16:17]
	v_mov_b32_e32 v69, v153
	s_add_u32 s6, s62, s1
	v_lshl_add_u64 v[16:17], v[16:17], 0, v[68:69]
	s_addc_u32 s7, s63, 0
	v_lshlrev_b64 v[16:17], 8, v[16:17]
	v_lshl_add_u64 v[16:17], s[6:7], 0, v[16:17]
	v_lshl_add_u64 v[16:17], v[16:17], 0, v[152:153]
	s_and_b64 vcc, exec, s[4:5]
	s_mov_b64 s[0:1], -1
	global_store_dword v[16:17], v8, off offset:128 nt
	global_store_dword v[16:17], v9, off offset:384 nt
	global_store_dword v[16:17], v10, off offset:640 nt
	global_store_dword v[16:17], v11, off offset:896 nt
	s_cbranch_vccnz .LBB0_757
	s_mov_b64 s[0:1], 0

.LBB0_760:
	v_lshl_add_u32 v16, v16, 3, v98
	v_ashrrev_i32_e32 v17, 31, v16
	s_lshl_b32 s1, s6, 2
	v_lshlrev_b64 v[16:17], s0, v[16:17]
	v_mov_b32_e32 v71, v153
	s_add_u32 s6, s62, s1
	v_lshl_add_u64 v[16:17], v[16:17], 0, v[70:71]
	s_addc_u32 s7, s63, 0
	v_lshlrev_b64 v[16:17], 8, v[16:17]
	v_lshl_add_u64 v[16:17], s[6:7], 0, v[16:17]
	v_cvt_pk_bf16_f32 v0, v0, v1
	v_cvt_pk_bf16_f32 v1, v2, v3
	v_cvt_pk_bf16_f32 v2, v4, v5
	v_cvt_pk_bf16_f32 v3, v6, v7
	v_lshl_add_u64 v[16:17], v[16:17], 0, v[152:153]
	v_permlane32_swap_b32_e32 v0, v2
	v_permlane32_swap_b32_e32 v1, v3
	s_and_b64 vcc, exec, s[4:5]
	s_mov_b64 s[0:1], -1
	global_store_dword v[16:17], v12, off offset:128 nt
	global_store_dword v[16:17], v13, off offset:384 nt
	global_store_dword v[16:17], v14, off offset:640 nt
	global_store_dword v[16:17], v15, off offset:896 nt
	s_cbranch_vccnz .LBB0_762
	v_ashrrev_i32_e32 v85, 31, v84
	v_lshlrev_b64 v[4:5], 20, v[84:85]
	v_lshl_add_u64 v[4:5], v[112:113], 0, v[4:5]
	s_mov_b64 s[0:1], 0

.LBB0_764:
	v_lshlrev_b32_e32 v152, 1, v54
	v_lshl_add_u64 v[4:5], v[4:5], 0, v[152:153]
	global_store_dwordx4 v[4:5], v[0:3], off nt
	s_and_b64 vcc, exec, s[4:5]
	s_mov_b64 s[0:1], -1
	v_cvt_pk_bf16_f32 v0, v8, v9
	v_cvt_pk_bf16_f32 v1, v10, v11
	v_cvt_pk_bf16_f32 v2, v12, v13
	v_cvt_pk_bf16_f32 v3, v14, v15
	s_nop 0
	v_permlane32_swap_b32_e32 v0, v2
	v_permlane32_swap_b32_e32 v1, v3
	s_cbranch_vccnz .LBB0_766
	v_ashrrev_i32_e32 v85, 31, v84
	v_lshlrev_b64 v[4:5], 20, v[84:85]
	v_lshl_add_u64 v[4:5], v[112:113], 0, v[4:5]
	s_mov_b64 s[0:1], 0
